# first K-iteration after an epilogue: counted vmcnt leaves the epilogue stores in flight (vmcnt 8+stores) instead of draining them
# speedup vs baseline: 1.0092x; 1.0034x over previous
.LBB0_152:
	s_add_u32 s12, s4, 0x10000000
	s_addc_u32 s13, s5, 0
	s_add_u32 s14, s4, 0x18000000
	s_addc_u32 s15, s5, 0
	s_lshl_b32 s4, s16, 5
	s_mov_b64 s[16:17], 0x80
	s_and_b32 s25, s4, 0x60
	s_add_i32 m0, s6, 0x18000
	v_lshl_add_u64 v[6:7], v[6:7], 0, s[16:17]
	s_lshl_b32 s24, s19, 13
	s_lshl_b32 s26, s25, 7
	s_waitcnt vmcnt(2)
	s_barrier
	global_load_lds_dwordx4 v[6:7], off
	v_lshl_add_u64 v[2:3], v[2:3], 0, s[16:17]
	s_add_i32 m0, s6, 0x1a000
	s_add_i32 s61, s6, 0x8000
	s_add_i32 s62, s6, 0xa000
	global_load_lds_dwordx4 v[2:3], off
	v_lshl_add_u64 v[0:1], v[0:1], 0, s[16:17]
	s_mov_b32 m0, s61
	s_add_u32 s4, s50, 0x40080
	global_load_lds_dwordx4 v[0:1], off
	v_lshl_add_u64 v[0:1], v[4:5], 0, s[16:17]
	s_mov_b32 m0, s62
	s_addc_u32 s5, s51, 0
	global_load_lds_dwordx4 v[0:1], off
	s_add_i32 m0, s6, 0x1c000
	v_lshl_add_u64 v[0:1], s[4:5], 0, v[132:133]
	global_load_lds_dwordx4 v[0:1], off
	v_lshl_add_u64 v[0:1], s[4:5], 0, v[128:129]
	s_add_i32 m0, s6, 0x1e000
	s_cmpk_lt_u32 s18, 0x100
	global_load_lds_dwordx4 v[0:1], off
	v_lshrrev_b32_e32 v1, 1, v8
	v_and_b32_e32 v1, 24, v1
	v_and_b32_e32 v0, 15, v8
	v_lshlrev_b32_e32 v2, 1, v1
	v_lshl_or_b32 v156, s19, 6, v0
	v_lshl_or_b32 v0, v0, 6, v2
	v_lshlrev_b32_e32 v2, 2, v8
	v_and_b32_e32 v2, 32, v2
	v_bitop3_b32 v3, v0, s24, v2 bitop3:0xde
	v_bitop3_b32 v157, v0, s26, v2 bitop3:0xde
	v_lshlrev_b32_e32 v0, 14, v13
	v_and_b32_e32 v0, 0xffff8000, v0
	v_or_b32_e32 v158, s25, v1
	v_lshl_add_u32 v0, v12, 11, v0
	v_and_b32_e32 v1, 1, v13
	v_lshl_or_b32 v0, v1, 6, v0
	v_lshl_add_u32 v138, v14, 1, v0
	v_lshlrev_b32_e32 v0, 14, v9
	v_and_b32_e32 v0, 0xffff8000, v0
	s_waitcnt vmcnt(6)
	v_lshl_add_u32 v0, v10, 11, v0
	v_and_b32_e32 v1, 1, v9
	s_cselect_b64 s[18:19], -1, 0
	v_lshl_or_b32 v0, v1, 6, v0
	s_add_i32 s64, 0, 0x10000
	s_add_i32 s65, 0, 0x14000
	v_or_b32_e32 v159, 0xfffffe00, v158
	v_mov_b32_e32 v139, v137
	v_lshl_add_u32 v140, v11, 1, v0
	v_mov_b32_e32 v141, v137
	v_mov_b64_e32 v[142:143], 0xc00
	v_mov_b64_e32 v[144:145], 0xbff
	s_movk_i32 s63, 0x181
	v_add_u32_e32 v160, s64, v157
	v_add_u32_e32 v161, s65, v157
	v_add_u32_e32 v162, 0, v3
	s_mov_b32 s66, 0x40000
	s_mov_b32 s67, 0x48000
	s_mov_b32 s68, 0x50000
	s_mov_b32 s69, 0x58000
	s_mov_b64 s[24:25], 0x48000
	s_mov_b64 s[26:27], 0x50000
	s_mov_b64 s[28:29], 0x58000
	s_mov_b32 s72, s70
	s_mov_b32 s73, s20
	s_barrier
	s_mov_b32 s99, 0
	s_branch .LBB0_155

.LBB0_154:
	s_mov_b32 s99, 2
	s_andn2_b64 vcc, exec, s[4:5]
	s_mov_b32 s72, s30
	s_mov_b32 s73, s34
	s_mov_b64 s[50:51], s[38:39]
	s_mov_b64 s[48:49], s[36:37]
	s_cbranch_vccz .LBB0_168

.LBB0_158:
	ds_read_b128 v[146:149], v160
	ds_read_b128 v[150:153], v160 offset:1024
	ds_read_b128 v[164:167], v160 offset:2048
	ds_read_b128 v[168:171], v160 offset:3072
	ds_read_b128 v[172:175], v161
	ds_read_b128 v[176:179], v161 offset:1024
	ds_read_b128 v[180:183], v161 offset:2048
	ds_read_b128 v[184:187], v161 offset:3072
	s_add_u32 s50, s48, 0xfffc0080
	s_addc_u32 s51, s49, -1
	s_cmp_eq_u32 s78, 12
	s_cselect_b32 s53, s35, s51
	s_cselect_b32 s52, s74, s50
	s_cselect_b32 s51, s31, s77
	s_cselect_b32 s50, s75, s76
	v_lshl_add_u64 v[154:155], s[48:49], 0, v[138:139]
	s_add_i32 m0, s6, 0xc000
	ds_read_b128 v[188:191], v162
	ds_read_b128 v[192:195], v162 offset:1024
	ds_read_b128 v[196:199], v162 offset:2048
	ds_read_b128 v[200:203], v162 offset:3072
	ds_read_b128 v[204:207], v162 offset:4096
	ds_read_b128 v[208:211], v162 offset:5120
	ds_read_b128 v[212:215], v162 offset:6144
	ds_read_b128 v[218:221], v162 offset:7168
	global_load_lds_dwordx4 v[154:155], off
	v_lshl_add_u64 v[154:155], s[48:49], 0, v[140:141]
	s_add_i32 m0, s6, 0xe000
	s_nop 0
	global_load_lds_dwordx4 v[154:155], off
	s_cmp_lg_u32 s78, -2
	s_cbranch_scc1 .Lzacc0a
	v_mov_b32_e32 v64, 0
	v_mov_b32_e32 v65, 0
	v_mov_b32_e32 v66, 0
	v_mov_b32_e32 v67, 0
	v_mov_b32_e32 v68, 0
	v_mov_b32_e32 v69, 0
	v_mov_b32_e32 v70, 0
	v_mov_b32_e32 v71, 0
	v_mov_b32_e32 v72, 0
	v_mov_b32_e32 v73, 0
	v_mov_b32_e32 v74, 0
	v_mov_b32_e32 v75, 0
	v_mov_b32_e32 v76, 0
	v_mov_b32_e32 v77, 0
	v_mov_b32_e32 v78, 0
	v_mov_b32_e32 v79, 0
	v_mov_b32_e32 v80, 0
	v_mov_b32_e32 v81, 0
	v_mov_b32_e32 v82, 0
	v_mov_b32_e32 v83, 0
	v_mov_b32_e32 v84, 0
	v_mov_b32_e32 v85, 0
	v_mov_b32_e32 v86, 0
	v_mov_b32_e32 v87, 0
	v_mov_b32_e32 v88, 0
	v_mov_b32_e32 v89, 0
	v_mov_b32_e32 v90, 0
	v_mov_b32_e32 v91, 0
	v_mov_b32_e32 v92, 0
	v_mov_b32_e32 v93, 0
	v_mov_b32_e32 v94, 0
	v_mov_b32_e32 v95, 0
	v_mov_b32_e32 v96, 0
	v_mov_b32_e32 v97, 0
	v_mov_b32_e32 v98, 0
	v_mov_b32_e32 v99, 0
	v_mov_b32_e32 v100, 0
	v_mov_b32_e32 v101, 0
	v_mov_b32_e32 v102, 0
	v_mov_b32_e32 v103, 0
	v_mov_b32_e32 v104, 0
	v_mov_b32_e32 v105, 0
	v_mov_b32_e32 v106, 0
	v_mov_b32_e32 v107, 0
	v_mov_b32_e32 v108, 0
	v_mov_b32_e32 v109, 0
	v_mov_b32_e32 v110, 0
	v_mov_b32_e32 v111, 0
	v_mov_b32_e32 v112, 0
	v_mov_b32_e32 v113, 0
	v_mov_b32_e32 v114, 0
	v_mov_b32_e32 v115, 0
	v_mov_b32_e32 v116, 0
	v_mov_b32_e32 v117, 0
	v_mov_b32_e32 v118, 0
	v_mov_b32_e32 v119, 0
	v_mov_b32_e32 v120, 0
	v_mov_b32_e32 v121, 0
	v_mov_b32_e32 v122, 0
	v_mov_b32_e32 v123, 0
	v_mov_b32_e32 v124, 0
	v_mov_b32_e32 v125, 0
	v_mov_b32_e32 v126, 0
	v_mov_b32_e32 v127, 0
	s_cmp_eq_u32 s99, 0
	s_cbranch_scc1 .Lzacc0a
	s_sub_u32 s99, s99, 1
	s_waitcnt vmcnt(16)
	s_branch .Lzacc0a_done

.Lzacc0a_done:
	s_waitcnt lgkmcnt(0)
	s_barrier
	s_setprio 1
	s_waitcnt lgkmcnt(0)
	v_mfma_f32_16x16x32_bf16 v[124:127], v[146:149], v[188:191], v[124:127]
	v_mfma_f32_16x16x32_bf16 v[120:123], v[164:167], v[188:191], v[120:123]
	v_mfma_f32_16x16x32_bf16 v[116:119], v[146:149], v[196:199], v[116:119]
	v_mfma_f32_16x16x32_bf16 v[112:115], v[164:167], v[196:199], v[112:115]
	v_mfma_f32_16x16x32_bf16 v[100:103], v[146:149], v[204:207], v[100:103]
	v_mfma_f32_16x16x32_bf16 v[96:99], v[164:167], v[204:207], v[96:99]
	v_mfma_f32_16x16x32_bf16 v[84:87], v[146:149], v[212:215], v[84:87]
	v_mfma_f32_16x16x32_bf16 v[80:83], v[164:167], v[212:215], v[80:83]
	v_mfma_f32_16x16x32_bf16 v[124:127], v[150:153], v[192:195], v[124:127]
	v_mfma_f32_16x16x32_bf16 v[120:123], v[168:171], v[192:195], v[120:123]
	v_mfma_f32_16x16x32_bf16 v[116:119], v[150:153], v[200:203], v[116:119]
	v_mfma_f32_16x16x32_bf16 v[112:115], v[168:171], v[200:203], v[112:115]
	v_mfma_f32_16x16x32_bf16 v[100:103], v[150:153], v[208:211], v[100:103]
	v_mfma_f32_16x16x32_bf16 v[96:99], v[168:171], v[208:211], v[96:99]
	v_mfma_f32_16x16x32_bf16 v[84:87], v[150:153], v[218:221], v[84:87]
	v_mfma_f32_16x16x32_bf16 v[80:83], v[168:171], v[218:221], v[80:83]
	s_setprio 0
	s_setprio 1
	v_mfma_f32_16x16x32_bf16 v[108:111], v[172:175], v[188:191], v[108:111]
	v_mfma_f32_16x16x32_bf16 v[104:107], v[180:183], v[188:191], v[104:107]
	v_mfma_f32_16x16x32_bf16 v[92:95], v[172:175], v[196:199], v[92:95]
	v_mfma_f32_16x16x32_bf16 v[88:91], v[180:183], v[196:199], v[88:91]
	v_mfma_f32_16x16x32_bf16 v[76:79], v[172:175], v[204:207], v[76:79]
	v_mfma_f32_16x16x32_bf16 v[72:75], v[180:183], v[204:207], v[72:75]
	v_mfma_f32_16x16x32_bf16 v[68:71], v[172:175], v[212:215], v[68:71]
	v_mfma_f32_16x16x32_bf16 v[64:67], v[180:183], v[212:215], v[64:67]
	v_mfma_f32_16x16x32_bf16 v[108:111], v[176:179], v[192:195], v[108:111]
	v_mfma_f32_16x16x32_bf16 v[104:107], v[184:187], v[192:195], v[104:107]
	v_mfma_f32_16x16x32_bf16 v[92:95], v[176:179], v[200:203], v[92:95]
	v_mfma_f32_16x16x32_bf16 v[88:91], v[184:187], v[200:203], v[88:91]
	v_mfma_f32_16x16x32_bf16 v[76:79], v[176:179], v[208:211], v[76:79]
	v_mfma_f32_16x16x32_bf16 v[72:75], v[184:187], v[208:211], v[72:75]
	v_mfma_f32_16x16x32_bf16 v[68:71], v[176:179], v[218:221], v[68:71]
	v_mfma_f32_16x16x32_bf16 v[64:67], v[184:187], v[218:221], v[64:67]
	s_setprio 0
	s_barrier
	s_add_i32 s79, s64, s58
	v_lshl_add_u64 v[154:155], s[50:51], 0, v[132:133]
	s_mov_b32 m0, s79
	ds_read_b128 v[188:191], v162 offset:16384
	ds_read_b128 v[192:195], v162 offset:17408
	ds_read_b128 v[196:199], v162 offset:18432
	ds_read_b128 v[200:203], v162 offset:19456
	ds_read_b128 v[204:207], v162 offset:20480
	ds_read_b128 v[208:211], v162 offset:21504
	ds_read_b128 v[212:215], v162 offset:22528
	ds_read_b128 v[218:221], v162 offset:23552
	global_load_lds_dwordx4 v[154:155], off
	s_add_i32 m0, s79, 0x2000
	s_add_u32 s80, s50, 0x40000
	v_lshl_add_u64 v[222:223], s[50:51], 0, v[128:129]
	s_addc_u32 s81, s51, 0
	s_add_i32 s79, s65, s58
	global_load_lds_dwordx4 v[222:223], off
	v_lshl_add_u64 v[224:225], s[80:81], 0, v[132:133]
	s_mov_b32 m0, s79
	v_lshl_add_u64 v[226:227], s[52:53], 0, v[130:131]
	global_load_lds_dwordx4 v[224:225], off
	v_lshl_add_u64 v[224:225], s[80:81], 0, v[128:129]
	s_add_i32 m0, s79, 0x2000
	s_nop 0
	global_load_lds_dwordx4 v[224:225], off
	v_lshl_add_u64 v[224:225], s[52:53], 0, v[134:135]
	s_mov_b32 m0, s6
	s_nop 0
	global_load_lds_dwordx4 v[224:225], off
	s_mov_b32 m0, s21
	s_nop 0
	global_load_lds_dwordx4 v[226:227], off
	s_cmp_lg_u32 s78, -2
	s_cbranch_scc1 .Lzacc0b
	v_mov_b32_e32 v0, 0
	v_mov_b32_e32 v1, 0
	v_mov_b32_e32 v2, 0
	v_mov_b32_e32 v3, 0
	v_mov_b32_e32 v4, 0
	v_mov_b32_e32 v5, 0
	v_mov_b32_e32 v6, 0
	v_mov_b32_e32 v7, 0
	v_mov_b32_e32 v8, 0
	v_mov_b32_e32 v9, 0
	v_mov_b32_e32 v10, 0
	v_mov_b32_e32 v11, 0
	v_mov_b32_e32 v12, 0
	v_mov_b32_e32 v13, 0
	v_mov_b32_e32 v14, 0
	v_mov_b32_e32 v15, 0
	v_mov_b32_e32 v16, 0
	v_mov_b32_e32 v17, 0
	v_mov_b32_e32 v18, 0
	v_mov_b32_e32 v19, 0
	v_mov_b32_e32 v20, 0
	v_mov_b32_e32 v21, 0
	v_mov_b32_e32 v22, 0
	v_mov_b32_e32 v23, 0
	v_mov_b32_e32 v24, 0
	v_mov_b32_e32 v25, 0
	v_mov_b32_e32 v26, 0
	v_mov_b32_e32 v27, 0
	v_mov_b32_e32 v28, 0
	v_mov_b32_e32 v29, 0
	v_mov_b32_e32 v30, 0
	v_mov_b32_e32 v31, 0
	v_mov_b32_e32 v32, 0
	v_mov_b32_e32 v33, 0
	v_mov_b32_e32 v34, 0
	v_mov_b32_e32 v35, 0
	v_mov_b32_e32 v36, 0
	v_mov_b32_e32 v37, 0
	v_mov_b32_e32 v38, 0
	v_mov_b32_e32 v39, 0
	v_mov_b32_e32 v40, 0
	v_mov_b32_e32 v41, 0
	v_mov_b32_e32 v42, 0
	v_mov_b32_e32 v43, 0
	v_mov_b32_e32 v44, 0
	v_mov_b32_e32 v45, 0
	v_mov_b32_e32 v46, 0
	v_mov_b32_e32 v47, 0
	v_mov_b32_e32 v48, 0
	v_mov_b32_e32 v49, 0
	v_mov_b32_e32 v50, 0
	v_mov_b32_e32 v51, 0
	v_mov_b32_e32 v52, 0
	v_mov_b32_e32 v53, 0
	v_mov_b32_e32 v54, 0
	v_mov_b32_e32 v55, 0
	v_mov_b32_e32 v56, 0
	v_mov_b32_e32 v57, 0
	v_mov_b32_e32 v58, 0
	v_mov_b32_e32 v59, 0
	v_mov_b32_e32 v60, 0
	v_mov_b32_e32 v61, 0
	v_mov_b32_e32 v62, 0
	v_mov_b32_e32 v63, 0
	s_cmp_eq_u32 s99, 0
	s_cbranch_scc1 .Lzacc0b
	s_sub_u32 s99, s99, 1
	s_waitcnt vmcnt(16)
	s_branch .Lzacc0b_done

.Lzacc0b_done:
	s_waitcnt lgkmcnt(0)
	s_barrier
	s_setprio 1
	s_waitcnt lgkmcnt(0)
	v_mfma_f32_16x16x32_bf16 v[60:63], v[146:149], v[188:191], v[60:63]
	v_mfma_f32_16x16x32_bf16 v[56:59], v[164:167], v[188:191], v[56:59]
	v_mfma_f32_16x16x32_bf16 v[52:55], v[146:149], v[196:199], v[52:55]
	v_mfma_f32_16x16x32_bf16 v[48:51], v[164:167], v[196:199], v[48:51]
	v_mfma_f32_16x16x32_bf16 v[36:39], v[146:149], v[204:207], v[36:39]
	v_mfma_f32_16x16x32_bf16 v[32:35], v[164:167], v[204:207], v[32:35]
	v_mfma_f32_16x16x32_bf16 v[20:23], v[146:149], v[212:215], v[20:23]
	v_mfma_f32_16x16x32_bf16 v[16:19], v[164:167], v[212:215], v[16:19]
	v_mfma_f32_16x16x32_bf16 v[60:63], v[150:153], v[192:195], v[60:63]
	v_mfma_f32_16x16x32_bf16 v[56:59], v[168:171], v[192:195], v[56:59]
	v_mfma_f32_16x16x32_bf16 v[52:55], v[150:153], v[200:203], v[52:55]
	v_mfma_f32_16x16x32_bf16 v[48:51], v[168:171], v[200:203], v[48:51]
	v_mfma_f32_16x16x32_bf16 v[36:39], v[150:153], v[208:211], v[36:39]
	v_mfma_f32_16x16x32_bf16 v[32:35], v[168:171], v[208:211], v[32:35]
	v_mfma_f32_16x16x32_bf16 v[20:23], v[150:153], v[218:221], v[20:23]
	v_mfma_f32_16x16x32_bf16 v[16:19], v[168:171], v[218:221], v[16:19]
	s_setprio 0
	s_setprio 1
	v_mfma_f32_16x16x32_bf16 v[44:47], v[172:175], v[188:191], v[44:47]
	v_mfma_f32_16x16x32_bf16 v[40:43], v[180:183], v[188:191], v[40:43]
	v_mfma_f32_16x16x32_bf16 v[28:31], v[172:175], v[196:199], v[28:31]
	v_mfma_f32_16x16x32_bf16 v[24:27], v[180:183], v[196:199], v[24:27]
	v_mfma_f32_16x16x32_bf16 v[12:15], v[172:175], v[204:207], v[12:15]
	v_mfma_f32_16x16x32_bf16 v[8:11], v[180:183], v[204:207], v[8:11]
	v_mfma_f32_16x16x32_bf16 v[4:7], v[172:175], v[212:215], v[4:7]
	v_mfma_f32_16x16x32_bf16 v[0:3], v[180:183], v[212:215], v[0:3]
	v_mfma_f32_16x16x32_bf16 v[44:47], v[176:179], v[192:195], v[44:47]
	v_mfma_f32_16x16x32_bf16 v[40:43], v[184:187], v[192:195], v[40:43]
	v_mfma_f32_16x16x32_bf16 v[28:31], v[176:179], v[200:203], v[28:31]
	v_mfma_f32_16x16x32_bf16 v[24:27], v[184:187], v[200:203], v[24:27]
	v_mfma_f32_16x16x32_bf16 v[12:15], v[176:179], v[208:211], v[12:15]
	v_mfma_f32_16x16x32_bf16 v[8:11], v[184:187], v[208:211], v[8:11]
	v_mfma_f32_16x16x32_bf16 v[4:7], v[176:179], v[218:221], v[4:7]
	v_mfma_f32_16x16x32_bf16 v[0:3], v[184:187], v[218:221], v[0:3]
	s_setprio 0
	s_barrier
	s_add_i32 s79, 0, 0x18000
	v_add_u32_e32 v136, s79, v157
	s_add_i32 s80, 0, 0x1c000
	ds_read_b128 v[146:149], v136
	ds_read_b128 v[150:153], v136 offset:1024
	ds_read_b128 v[164:167], v136 offset:2048
	ds_read_b128 v[168:171], v136 offset:3072
	v_add_u32_e32 v136, s80, v157
	ds_read_b128 v[172:175], v136
	ds_read_b128 v[176:179], v136 offset:1024
	ds_read_b128 v[180:183], v136 offset:2048
	ds_read_b128 v[184:187], v136 offset:3072
	s_add_u32 s52, s52, 0x40000
	s_addc_u32 s53, s53, 0
	s_mov_b32 m0, s59
	v_lshl_add_u64 v[228:229], s[52:53], 0, v[134:135]
	ds_read_b128 v[188:191], v162 offset:32768
	ds_read_b128 v[192:195], v162 offset:33792
	ds_read_b128 v[196:199], v162 offset:34816
	ds_read_b128 v[200:203], v162 offset:35840
	ds_read_b128 v[204:207], v162 offset:36864
	ds_read_b128 v[208:211], v162 offset:37888
	ds_read_b128 v[212:215], v162 offset:38912
	ds_read_b128 v[218:221], v162 offset:39936
	global_load_lds_dwordx4 v[228:229], off
	v_lshl_add_u64 v[228:229], s[52:53], 0, v[130:131]
	s_mov_b32 m0, s60
	s_nop 0
	global_load_lds_dwordx4 v[228:229], off
	s_waitcnt vmcnt(8)
	s_waitcnt lgkmcnt(0)
	s_barrier
	s_setprio 1
	s_waitcnt lgkmcnt(0)
	v_mfma_f32_16x16x32_bf16 v[124:127], v[146:149], v[188:191], v[124:127]
	v_mfma_f32_16x16x32_bf16 v[120:123], v[164:167], v[188:191], v[120:123]
	v_mfma_f32_16x16x32_bf16 v[116:119], v[146:149], v[196:199], v[116:119]
	v_mfma_f32_16x16x32_bf16 v[112:115], v[164:167], v[196:199], v[112:115]
	v_mfma_f32_16x16x32_bf16 v[100:103], v[146:149], v[204:207], v[100:103]
	v_mfma_f32_16x16x32_bf16 v[96:99], v[164:167], v[204:207], v[96:99]
	v_mfma_f32_16x16x32_bf16 v[84:87], v[146:149], v[212:215], v[84:87]
	v_mfma_f32_16x16x32_bf16 v[80:83], v[164:167], v[212:215], v[80:83]
	v_mfma_f32_16x16x32_bf16 v[124:127], v[150:153], v[192:195], v[124:127]
	v_mfma_f32_16x16x32_bf16 v[120:123], v[168:171], v[192:195], v[120:123]
	v_mfma_f32_16x16x32_bf16 v[116:119], v[150:153], v[200:203], v[116:119]
	v_mfma_f32_16x16x32_bf16 v[112:115], v[168:171], v[200:203], v[112:115]
	v_mfma_f32_16x16x32_bf16 v[100:103], v[150:153], v[208:211], v[100:103]
	v_mfma_f32_16x16x32_bf16 v[96:99], v[168:171], v[208:211], v[96:99]
	v_mfma_f32_16x16x32_bf16 v[84:87], v[150:153], v[218:221], v[84:87]
	v_mfma_f32_16x16x32_bf16 v[80:83], v[168:171], v[218:221], v[80:83]
	s_setprio 0
	s_setprio 1
	v_mfma_f32_16x16x32_bf16 v[108:111], v[172:175], v[188:191], v[108:111]
	v_mfma_f32_16x16x32_bf16 v[104:107], v[180:183], v[188:191], v[104:107]
	v_mfma_f32_16x16x32_bf16 v[92:95], v[172:175], v[196:199], v[92:95]
	v_mfma_f32_16x16x32_bf16 v[88:91], v[180:183], v[196:199], v[88:91]
	v_mfma_f32_16x16x32_bf16 v[76:79], v[172:175], v[204:207], v[76:79]
	v_mfma_f32_16x16x32_bf16 v[72:75], v[180:183], v[204:207], v[72:75]
	v_mfma_f32_16x16x32_bf16 v[68:71], v[172:175], v[212:215], v[68:71]
	v_mfma_f32_16x16x32_bf16 v[64:67], v[180:183], v[212:215], v[64:67]
	v_mfma_f32_16x16x32_bf16 v[108:111], v[176:179], v[192:195], v[108:111]
	v_mfma_f32_16x16x32_bf16 v[104:107], v[184:187], v[192:195], v[104:107]
	v_mfma_f32_16x16x32_bf16 v[92:95], v[176:179], v[200:203], v[92:95]
	v_mfma_f32_16x16x32_bf16 v[88:91], v[184:187], v[200:203], v[88:91]
	v_mfma_f32_16x16x32_bf16 v[76:79], v[176:179], v[208:211], v[76:79]
	v_mfma_f32_16x16x32_bf16 v[72:75], v[184:187], v[208:211], v[72:75]
	v_mfma_f32_16x16x32_bf16 v[68:71], v[176:179], v[218:221], v[68:71]
	v_mfma_f32_16x16x32_bf16 v[64:67], v[184:187], v[218:221], v[64:67]
	s_setprio 0
	s_barrier
	s_add_i32 s52, s79, s58
	v_lshl_add_u64 v[154:155], v[154:155], 0, s[16:17]
	s_mov_b32 m0, s52
	ds_read_b128 v[188:191], v162 offset:49152
	ds_read_b128 v[192:195], v162 offset:50176
	ds_read_b128 v[196:199], v162 offset:51200
	ds_read_b128 v[200:203], v162 offset:52224
	ds_read_b128 v[204:207], v162 offset:53248
	ds_read_b128 v[208:211], v162 offset:54272
	ds_read_b128 v[212:215], v162 offset:55296
	ds_read_b128 v[218:221], v162 offset:56320
	global_load_lds_dwordx4 v[154:155], off
	s_add_i32 m0, s52, 0x2000
	s_add_u32 s50, s50, 0x40080
	v_lshl_add_u64 v[154:155], v[222:223], 0, s[16:17]
	s_addc_u32 s51, s51, 0
	s_add_i32 s52, s80, s58
	global_load_lds_dwordx4 v[154:155], off
	v_lshl_add_u64 v[154:155], s[50:51], 0, v[132:133]
	s_mov_b32 m0, s52
	s_nop 0
	global_load_lds_dwordx4 v[154:155], off
	v_lshl_add_u64 v[154:155], s[50:51], 0, v[128:129]
	s_add_i32 m0, s52, 0x2000
	s_nop 0
	global_load_lds_dwordx4 v[154:155], off
	v_lshl_add_u64 v[154:155], v[224:225], 0, s[16:17]
	s_mov_b32 m0, s61
	s_nop 0
	global_load_lds_dwordx4 v[154:155], off
	v_lshl_add_u64 v[154:155], v[226:227], 0, s[16:17]
	s_mov_b32 m0, s62
	s_nop 0
	global_load_lds_dwordx4 v[154:155], off
	s_waitcnt vmcnt(8)
	s_waitcnt lgkmcnt(0)
	s_barrier
	s_setprio 1
	s_waitcnt lgkmcnt(0)
	v_mfma_f32_16x16x32_bf16 v[60:63], v[146:149], v[188:191], v[60:63]
	v_mfma_f32_16x16x32_bf16 v[56:59], v[164:167], v[188:191], v[56:59]
	v_mfma_f32_16x16x32_bf16 v[52:55], v[146:149], v[196:199], v[52:55]
	v_mfma_f32_16x16x32_bf16 v[48:51], v[164:167], v[196:199], v[48:51]
	v_mfma_f32_16x16x32_bf16 v[36:39], v[146:149], v[204:207], v[36:39]
	v_mfma_f32_16x16x32_bf16 v[32:35], v[164:167], v[204:207], v[32:35]
	v_mfma_f32_16x16x32_bf16 v[20:23], v[146:149], v[212:215], v[20:23]
	v_mfma_f32_16x16x32_bf16 v[16:19], v[164:167], v[212:215], v[16:19]
	v_mfma_f32_16x16x32_bf16 v[60:63], v[150:153], v[192:195], v[60:63]
	v_mfma_f32_16x16x32_bf16 v[56:59], v[168:171], v[192:195], v[56:59]
	v_mfma_f32_16x16x32_bf16 v[52:55], v[150:153], v[200:203], v[52:55]
	v_mfma_f32_16x16x32_bf16 v[48:51], v[168:171], v[200:203], v[48:51]
	v_mfma_f32_16x16x32_bf16 v[36:39], v[150:153], v[208:211], v[36:39]
	v_mfma_f32_16x16x32_bf16 v[32:35], v[168:171], v[208:211], v[32:35]
	v_mfma_f32_16x16x32_bf16 v[20:23], v[150:153], v[218:221], v[20:23]
	v_mfma_f32_16x16x32_bf16 v[16:19], v[168:171], v[218:221], v[16:19]
	s_setprio 0
	s_setprio 1
	v_mfma_f32_16x16x32_bf16 v[44:47], v[172:175], v[188:191], v[44:47]
	v_mfma_f32_16x16x32_bf16 v[40:43], v[180:183], v[188:191], v[40:43]
	v_mfma_f32_16x16x32_bf16 v[28:31], v[172:175], v[196:199], v[28:31]
	v_mfma_f32_16x16x32_bf16 v[24:27], v[180:183], v[196:199], v[24:27]
	v_mfma_f32_16x16x32_bf16 v[12:15], v[172:175], v[204:207], v[12:15]
	v_mfma_f32_16x16x32_bf16 v[8:11], v[180:183], v[204:207], v[8:11]
	v_mfma_f32_16x16x32_bf16 v[4:7], v[172:175], v[212:215], v[4:7]
	v_mfma_f32_16x16x32_bf16 v[0:3], v[180:183], v[212:215], v[0:3]
	v_mfma_f32_16x16x32_bf16 v[44:47], v[176:179], v[192:195], v[44:47]
	v_mfma_f32_16x16x32_bf16 v[40:43], v[184:187], v[192:195], v[40:43]
	v_mfma_f32_16x16x32_bf16 v[28:31], v[176:179], v[200:203], v[28:31]
	v_mfma_f32_16x16x32_bf16 v[24:27], v[184:187], v[200:203], v[24:27]
	v_mfma_f32_16x16x32_bf16 v[12:15], v[176:179], v[208:211], v[12:15]
	v_mfma_f32_16x16x32_bf16 v[8:11], v[184:187], v[208:211], v[8:11]
	v_mfma_f32_16x16x32_bf16 v[4:7], v[176:179], v[218:221], v[4:7]
	v_mfma_f32_16x16x32_bf16 v[0:3], v[184:187], v[218:221], v[0:3]
	s_setprio 0
	s_barrier
	s_add_i32 s78, s78, 2
	s_add_u32 s48, s48, 0x100
	s_addc_u32 s49, s49, 0
	s_add_u32 s76, s76, 0x100
	s_addc_u32 s77, s77, 0
	s_cmp_gt_u32 s78, 13
	s_cbranch_scc0 .LBB0_158
	s_and_b64 vcc, exec, s[18:19]
	s_cbranch_vccz .LBB0_161
	s_barrier

.LBB0_284:
	s_add_u32 s24, s12, 0x8000000
	s_mov_b64 s[26:27], 0x80
	s_addc_u32 s25, s13, 0
	s_and_b32 s8, s6, 3
	s_add_i32 m0, s62, 0x18000
	v_lshl_add_u64 v[6:7], v[6:7], 0, s[26:27]
	s_lshl_b32 s66, s7, 6
	s_lshl_b32 s9, s7, 13
	s_lshl_b32 s10, s8, 12
	s_waitcnt vmcnt(2)
	s_barrier
	global_load_lds_dwordx4 v[6:7], off
	v_lshl_add_u64 v[4:5], v[4:5], 0, s[26:27]
	s_add_i32 m0, s62, 0x1a000
	s_add_i32 s67, s62, 0x8000
	s_add_i32 s68, s62, 0xa000
	global_load_lds_dwordx4 v[4:5], off
	v_lshl_add_u64 v[0:1], v[0:1], 0, s[26:27]
	s_mov_b32 m0, s67
	s_add_u32 s6, s54, 0x40080
	global_load_lds_dwordx4 v[0:1], off
	v_lshl_add_u64 v[0:1], v[2:3], 0, s[26:27]
	s_mov_b32 m0, s68
	s_addc_u32 s7, s55, 0
	global_load_lds_dwordx4 v[0:1], off
	s_add_i32 m0, s62, 0x1c000
	v_lshl_add_u64 v[0:1], s[6:7], 0, v[178:179]
	global_load_lds_dwordx4 v[0:1], off
	v_lshl_add_u64 v[0:1], s[6:7], 0, v[182:183]
	s_add_i32 m0, s62, 0x1e000
	s_cmpk_lt_u32 s5, 0x100
	global_load_lds_dwordx4 v[0:1], off
	v_lshrrev_b32_e32 v1, 1, v8
	v_and_b32_e32 v0, 63, v8
	v_and_b32_e32 v1, 24, v1
	v_lshl_or_b32 v207, s8, 5, v1
	s_cselect_b64 s[28:29], -1, 0
	v_cmp_gt_u32_e64 s[6:7], 16, v0
	s_lshl_b32 s69, s8, 10
	s_movk_i32 s8, 0xffc0
	v_mov_b32_e32 v0, s5
	v_bfi_b32 v208, s8, v0, v8
	v_lshlrev_b32_e32 v0, 14, v9
	v_and_b32_e32 v0, 0xffff8000, v0
	v_lshl_add_u32 v0, v10, 11, v0
	v_and_b32_e32 v1, 1, v9
	v_lshl_or_b32 v0, v1, 6, v0
	v_lshl_add_u32 v184, v11, 1, v0
	v_lshlrev_b32_e32 v0, 14, v12
	v_and_b32_e32 v204, 15, v8
	v_and_b32_e32 v2, 48, v8
	v_lshlrev_b32_e32 v3, 2, v8
	v_and_b32_e32 v0, 0xffff8000, v0
	v_lshl_or_b32 v2, v204, 6, v2
	v_and_b32_e32 v3, 32, v3
	s_waitcnt vmcnt(6)
	v_lshl_add_u32 v0, v13, 11, v0
	v_and_b32_e32 v1, 1, v12
	v_bitop3_b32 v4, v2, s9, v3 bitop3:0xde
	v_bitop3_b32 v206, v2, s10, v3 bitop3:0xde
	s_movk_i32 s9, 0x100
	v_lshl_or_b32 v0, v1, 6, v0
	s_add_i32 s72, 0, 0x10000
	s_add_i32 s73, 0, 0x14000
	v_or_b32_e32 v205, s66, v204
	v_cmp_gt_i32_e64 s[8:9], s9, v208
	v_mov_b32_e32 v185, v179
	v_lshl_add_u32 v186, v14, 1, v0
	v_mov_b32_e32 v187, v179
	v_mov_b64_e32 v[188:189], 0x400
	v_mov_b64_e32 v[190:191], 0x3ff
	v_add_u32_e32 v209, s72, v206
	v_add_u32_e32 v210, s73, v206
	v_add_u32_e32 v211, 0, v4
	v_mbcnt_hi_u32_b32 v212, -1, v248
	s_barrier
	s_mov_b32 s99, 0
	s_branch .LBB0_287

.LBB0_286:
	s_mov_b32 s99, 2
	s_andn2_b64 vcc, exec, s[10:11]
	s_mov_b32 s16, s30
	s_mov_b32 s50, s34
	s_mov_b64 s[54:55], s[38:39]
	s_mov_b64 s[52:53], s[36:37]
	s_mov_b32 s4, s74
	s_cbranch_vccz .LBB0_318

.LBB0_294:
	ds_read_b128 v[128:131], v209
	ds_read_b128 v[132:135], v209 offset:1024
	ds_read_b128 v[136:139], v209 offset:2048
	ds_read_b128 v[140:143], v209 offset:3072
	ds_read_b128 v[144:147], v210
	ds_read_b128 v[148:151], v210 offset:1024
	ds_read_b128 v[152:155], v210 offset:2048
	ds_read_b128 v[156:159], v210 offset:3072
	s_add_u32 s54, s52, 0xfffc0080
	s_addc_u32 s55, s53, -1
	s_cmp_eq_u32 s76, 12
	s_cselect_b32 s57, s5, s55
	s_cselect_b32 s56, s17, s54
	s_cselect_b32 s55, s31, s75
	s_cselect_b32 s54, s35, s51
	v_lshl_add_u64 v[214:215], s[52:53], 0, v[184:185]
	s_add_i32 m0, s62, 0xc000
	ds_read_b128 v[160:163], v211
	ds_read_b128 v[164:167], v211 offset:1024
	ds_read_b128 v[168:171], v211 offset:2048
	ds_read_b128 v[172:175], v211 offset:3072
	ds_read_b128 v[192:195], v211 offset:4096
	ds_read_b128 v[196:199], v211 offset:5120
	ds_read_b128 v[200:203], v211 offset:6144
	ds_read_b128 v[218:221], v211 offset:7168
	global_load_lds_dwordx4 v[214:215], off
	v_lshl_add_u64 v[214:215], s[52:53], 0, v[186:187]
	s_add_i32 m0, s62, 0xe000
	s_nop 0
	global_load_lds_dwordx4 v[214:215], off
	s_cmp_lg_u32 s76, -2
	s_cbranch_scc1 .Lzacc1a
	v_mov_b32_e32 v64, 0
	v_mov_b32_e32 v65, 0
	v_mov_b32_e32 v66, 0
	v_mov_b32_e32 v67, 0
	v_mov_b32_e32 v68, 0
	v_mov_b32_e32 v69, 0
	v_mov_b32_e32 v70, 0
	v_mov_b32_e32 v71, 0
	v_mov_b32_e32 v72, 0
	v_mov_b32_e32 v73, 0
	v_mov_b32_e32 v74, 0
	v_mov_b32_e32 v75, 0
	v_mov_b32_e32 v76, 0
	v_mov_b32_e32 v77, 0
	v_mov_b32_e32 v78, 0
	v_mov_b32_e32 v79, 0
	v_mov_b32_e32 v80, 0
	v_mov_b32_e32 v81, 0
	v_mov_b32_e32 v82, 0
	v_mov_b32_e32 v83, 0
	v_mov_b32_e32 v84, 0
	v_mov_b32_e32 v85, 0
	v_mov_b32_e32 v86, 0
	v_mov_b32_e32 v87, 0
	v_mov_b32_e32 v88, 0
	v_mov_b32_e32 v89, 0
	v_mov_b32_e32 v90, 0
	v_mov_b32_e32 v91, 0
	v_mov_b32_e32 v92, 0
	v_mov_b32_e32 v93, 0
	v_mov_b32_e32 v94, 0
	v_mov_b32_e32 v95, 0
	v_mov_b32_e32 v96, 0
	v_mov_b32_e32 v97, 0
	v_mov_b32_e32 v98, 0
	v_mov_b32_e32 v99, 0
	v_mov_b32_e32 v100, 0
	v_mov_b32_e32 v101, 0
	v_mov_b32_e32 v102, 0
	v_mov_b32_e32 v103, 0
	v_mov_b32_e32 v104, 0
	v_mov_b32_e32 v105, 0
	v_mov_b32_e32 v106, 0
	v_mov_b32_e32 v107, 0
	v_mov_b32_e32 v108, 0
	v_mov_b32_e32 v109, 0
	v_mov_b32_e32 v110, 0
	v_mov_b32_e32 v111, 0
	v_mov_b32_e32 v112, 0
	v_mov_b32_e32 v113, 0
	v_mov_b32_e32 v114, 0
	v_mov_b32_e32 v115, 0
	v_mov_b32_e32 v116, 0
	v_mov_b32_e32 v117, 0
	v_mov_b32_e32 v118, 0
	v_mov_b32_e32 v119, 0
	v_mov_b32_e32 v120, 0
	v_mov_b32_e32 v121, 0
	v_mov_b32_e32 v122, 0
	v_mov_b32_e32 v123, 0
	v_mov_b32_e32 v124, 0
	v_mov_b32_e32 v125, 0
	v_mov_b32_e32 v126, 0
	v_mov_b32_e32 v127, 0
	s_cmp_eq_u32 s99, 0
	s_cbranch_scc1 .Lzacc1a
	s_sub_u32 s99, s99, 1
	s_waitcnt vmcnt(24)
	s_branch .Lzacc1a_done

.Lzacc1a_done:
	s_waitcnt lgkmcnt(0)
	s_barrier
	s_setprio 1
	s_waitcnt lgkmcnt(0)
	v_mfma_f32_16x16x32_bf16 v[124:127], v[128:131], v[160:163], v[124:127]
	v_mfma_f32_16x16x32_bf16 v[120:123], v[136:139], v[160:163], v[120:123]
	v_mfma_f32_16x16x32_bf16 v[108:111], v[128:131], v[168:171], v[108:111]
	v_mfma_f32_16x16x32_bf16 v[104:107], v[136:139], v[168:171], v[104:107]
	v_mfma_f32_16x16x32_bf16 v[92:95], v[128:131], v[192:195], v[92:95]
	v_mfma_f32_16x16x32_bf16 v[88:91], v[136:139], v[192:195], v[88:91]
	v_mfma_f32_16x16x32_bf16 v[76:79], v[128:131], v[200:203], v[76:79]
	v_mfma_f32_16x16x32_bf16 v[72:75], v[136:139], v[200:203], v[72:75]
	v_mfma_f32_16x16x32_bf16 v[124:127], v[132:135], v[164:167], v[124:127]
	v_mfma_f32_16x16x32_bf16 v[120:123], v[140:143], v[164:167], v[120:123]
	v_mfma_f32_16x16x32_bf16 v[108:111], v[132:135], v[172:175], v[108:111]
	v_mfma_f32_16x16x32_bf16 v[104:107], v[140:143], v[172:175], v[104:107]
	v_mfma_f32_16x16x32_bf16 v[92:95], v[132:135], v[196:199], v[92:95]
	v_mfma_f32_16x16x32_bf16 v[88:91], v[140:143], v[196:199], v[88:91]
	v_mfma_f32_16x16x32_bf16 v[76:79], v[132:135], v[218:221], v[76:79]
	v_mfma_f32_16x16x32_bf16 v[72:75], v[140:143], v[218:221], v[72:75]
	s_setprio 0
	s_setprio 1
	v_mfma_f32_16x16x32_bf16 v[116:119], v[144:147], v[160:163], v[116:119]
	v_mfma_f32_16x16x32_bf16 v[112:115], v[152:155], v[160:163], v[112:115]
	v_mfma_f32_16x16x32_bf16 v[100:103], v[144:147], v[168:171], v[100:103]
	v_mfma_f32_16x16x32_bf16 v[96:99], v[152:155], v[168:171], v[96:99]
	v_mfma_f32_16x16x32_bf16 v[84:87], v[144:147], v[192:195], v[84:87]
	v_mfma_f32_16x16x32_bf16 v[80:83], v[152:155], v[192:195], v[80:83]
	v_mfma_f32_16x16x32_bf16 v[68:71], v[144:147], v[200:203], v[68:71]
	v_mfma_f32_16x16x32_bf16 v[64:67], v[152:155], v[200:203], v[64:67]
	v_mfma_f32_16x16x32_bf16 v[116:119], v[148:151], v[164:167], v[116:119]
	v_mfma_f32_16x16x32_bf16 v[112:115], v[156:159], v[164:167], v[112:115]
	v_mfma_f32_16x16x32_bf16 v[100:103], v[148:151], v[172:175], v[100:103]
	v_mfma_f32_16x16x32_bf16 v[96:99], v[156:159], v[172:175], v[96:99]
	v_mfma_f32_16x16x32_bf16 v[84:87], v[148:151], v[196:199], v[84:87]
	v_mfma_f32_16x16x32_bf16 v[80:83], v[156:159], v[196:199], v[80:83]
	v_mfma_f32_16x16x32_bf16 v[68:71], v[148:151], v[218:221], v[68:71]
	v_mfma_f32_16x16x32_bf16 v[64:67], v[156:159], v[218:221], v[64:67]
	s_setprio 0
	s_barrier
	s_add_i32 s77, s72, s61
	v_lshl_add_u64 v[214:215], s[54:55], 0, v[178:179]
	s_mov_b32 m0, s77
	ds_read_b128 v[160:163], v211 offset:16384
	ds_read_b128 v[164:167], v211 offset:17408
	ds_read_b128 v[168:171], v211 offset:18432
	ds_read_b128 v[172:175], v211 offset:19456
	ds_read_b128 v[192:195], v211 offset:20480
	ds_read_b128 v[196:199], v211 offset:21504
	ds_read_b128 v[200:203], v211 offset:22528
	ds_read_b128 v[218:221], v211 offset:23552
	global_load_lds_dwordx4 v[214:215], off
	s_add_i32 m0, s77, 0x2000
	s_add_u32 s78, s54, 0x40000
	v_lshl_add_u64 v[222:223], s[54:55], 0, v[182:183]
	s_addc_u32 s79, s55, 0
	s_add_i32 s77, s73, s61
	global_load_lds_dwordx4 v[222:223], off
	v_lshl_add_u64 v[224:225], s[78:79], 0, v[178:179]
	s_mov_b32 m0, s77
	v_lshl_add_u64 v[226:227], s[56:57], 0, v[180:181]
	global_load_lds_dwordx4 v[224:225], off
	v_lshl_add_u64 v[224:225], s[78:79], 0, v[182:183]
	s_add_i32 m0, s77, 0x2000
	s_nop 0
	global_load_lds_dwordx4 v[224:225], off
	v_lshl_add_u64 v[224:225], s[56:57], 0, v[176:177]
	s_mov_b32 m0, s62
	s_nop 0
	global_load_lds_dwordx4 v[224:225], off
	s_mov_b32 m0, s63
	s_nop 0
	global_load_lds_dwordx4 v[226:227], off
	s_cmp_lg_u32 s76, -2
	s_cbranch_scc1 .Lzacc1b
	v_mov_b32_e32 v0, 0
	v_mov_b32_e32 v1, 0
	v_mov_b32_e32 v2, 0
	v_mov_b32_e32 v3, 0
	v_mov_b32_e32 v4, 0
	v_mov_b32_e32 v5, 0
	v_mov_b32_e32 v6, 0
	v_mov_b32_e32 v7, 0
	v_mov_b32_e32 v8, 0
	v_mov_b32_e32 v9, 0
	v_mov_b32_e32 v10, 0
	v_mov_b32_e32 v11, 0
	v_mov_b32_e32 v12, 0
	v_mov_b32_e32 v13, 0
	v_mov_b32_e32 v14, 0
	v_mov_b32_e32 v15, 0
	v_mov_b32_e32 v16, 0
	v_mov_b32_e32 v17, 0
	v_mov_b32_e32 v18, 0
	v_mov_b32_e32 v19, 0
	v_mov_b32_e32 v20, 0
	v_mov_b32_e32 v21, 0
	v_mov_b32_e32 v22, 0
	v_mov_b32_e32 v23, 0
	v_mov_b32_e32 v24, 0
	v_mov_b32_e32 v25, 0
	v_mov_b32_e32 v26, 0
	v_mov_b32_e32 v27, 0
	v_mov_b32_e32 v28, 0
	v_mov_b32_e32 v29, 0
	v_mov_b32_e32 v30, 0
	v_mov_b32_e32 v31, 0
	v_mov_b32_e32 v32, 0
	v_mov_b32_e32 v33, 0
	v_mov_b32_e32 v34, 0
	v_mov_b32_e32 v35, 0
	v_mov_b32_e32 v36, 0
	v_mov_b32_e32 v37, 0
	v_mov_b32_e32 v38, 0
	v_mov_b32_e32 v39, 0
	v_mov_b32_e32 v40, 0
	v_mov_b32_e32 v41, 0
	v_mov_b32_e32 v42, 0
	v_mov_b32_e32 v43, 0
	v_mov_b32_e32 v44, 0
	v_mov_b32_e32 v45, 0
	v_mov_b32_e32 v46, 0
	v_mov_b32_e32 v47, 0
	v_mov_b32_e32 v48, 0
	v_mov_b32_e32 v49, 0
	v_mov_b32_e32 v50, 0
	v_mov_b32_e32 v51, 0
	v_mov_b32_e32 v52, 0
	v_mov_b32_e32 v53, 0
	v_mov_b32_e32 v54, 0
	v_mov_b32_e32 v55, 0
	v_mov_b32_e32 v56, 0
	v_mov_b32_e32 v57, 0
	v_mov_b32_e32 v58, 0
	v_mov_b32_e32 v59, 0
	v_mov_b32_e32 v60, 0
	v_mov_b32_e32 v61, 0
	v_mov_b32_e32 v62, 0
	v_mov_b32_e32 v63, 0
	s_cmp_eq_u32 s99, 0
	s_cbranch_scc1 .Lzacc1b
	s_sub_u32 s99, s99, 1
	s_waitcnt vmcnt(24)
	s_branch .Lzacc1b_done

.Lzacc1b_done:
	s_waitcnt lgkmcnt(0)
	s_barrier
	s_setprio 1
	s_waitcnt lgkmcnt(0)
	v_mfma_f32_16x16x32_bf16 v[60:63], v[128:131], v[160:163], v[60:63]
	v_mfma_f32_16x16x32_bf16 v[56:59], v[136:139], v[160:163], v[56:59]
	v_mfma_f32_16x16x32_bf16 v[44:47], v[128:131], v[168:171], v[44:47]
	v_mfma_f32_16x16x32_bf16 v[40:43], v[136:139], v[168:171], v[40:43]
	v_mfma_f32_16x16x32_bf16 v[28:31], v[128:131], v[192:195], v[28:31]
	v_mfma_f32_16x16x32_bf16 v[24:27], v[136:139], v[192:195], v[24:27]
	v_mfma_f32_16x16x32_bf16 v[12:15], v[128:131], v[200:203], v[12:15]
	v_mfma_f32_16x16x32_bf16 v[8:11], v[136:139], v[200:203], v[8:11]
	v_mfma_f32_16x16x32_bf16 v[60:63], v[132:135], v[164:167], v[60:63]
	v_mfma_f32_16x16x32_bf16 v[56:59], v[140:143], v[164:167], v[56:59]
	v_mfma_f32_16x16x32_bf16 v[44:47], v[132:135], v[172:175], v[44:47]
	v_mfma_f32_16x16x32_bf16 v[40:43], v[140:143], v[172:175], v[40:43]
	v_mfma_f32_16x16x32_bf16 v[28:31], v[132:135], v[196:199], v[28:31]
	v_mfma_f32_16x16x32_bf16 v[24:27], v[140:143], v[196:199], v[24:27]
	v_mfma_f32_16x16x32_bf16 v[12:15], v[132:135], v[218:221], v[12:15]
	v_mfma_f32_16x16x32_bf16 v[8:11], v[140:143], v[218:221], v[8:11]
	s_setprio 0
	s_setprio 1
	v_mfma_f32_16x16x32_bf16 v[52:55], v[144:147], v[160:163], v[52:55]
	v_mfma_f32_16x16x32_bf16 v[48:51], v[152:155], v[160:163], v[48:51]
	v_mfma_f32_16x16x32_bf16 v[36:39], v[144:147], v[168:171], v[36:39]
	v_mfma_f32_16x16x32_bf16 v[32:35], v[152:155], v[168:171], v[32:35]
	v_mfma_f32_16x16x32_bf16 v[20:23], v[144:147], v[192:195], v[20:23]
	v_mfma_f32_16x16x32_bf16 v[16:19], v[152:155], v[192:195], v[16:19]
	v_mfma_f32_16x16x32_bf16 v[4:7], v[144:147], v[200:203], v[4:7]
	v_mfma_f32_16x16x32_bf16 v[0:3], v[152:155], v[200:203], v[0:3]
	v_mfma_f32_16x16x32_bf16 v[52:55], v[148:151], v[164:167], v[52:55]
	v_mfma_f32_16x16x32_bf16 v[48:51], v[156:159], v[164:167], v[48:51]
	v_mfma_f32_16x16x32_bf16 v[36:39], v[148:151], v[172:175], v[36:39]
	v_mfma_f32_16x16x32_bf16 v[32:35], v[156:159], v[172:175], v[32:35]
	v_mfma_f32_16x16x32_bf16 v[20:23], v[148:151], v[196:199], v[20:23]
	v_mfma_f32_16x16x32_bf16 v[16:19], v[156:159], v[196:199], v[16:19]
	v_mfma_f32_16x16x32_bf16 v[4:7], v[148:151], v[218:221], v[4:7]
	v_mfma_f32_16x16x32_bf16 v[0:3], v[156:159], v[218:221], v[0:3]
	s_setprio 0
	s_barrier
	s_add_i32 s77, 0, 0x18000
	s_add_i32 s78, 0, 0x1c000
	v_add_u32_e32 v140, s77, v206
	v_add_u32_e32 v156, s78, v206
	ds_read_b128 v[128:131], v140
	ds_read_b128 v[132:135], v140 offset:1024
	ds_read_b128 v[136:139], v140 offset:2048
	ds_read_b128 v[140:143], v140 offset:3072
	ds_read_b128 v[144:147], v156
	ds_read_b128 v[148:151], v156 offset:1024
	ds_read_b128 v[152:155], v156 offset:2048
	ds_read_b128 v[156:159], v156 offset:3072
	s_add_u32 s56, s56, 0x40000
	s_addc_u32 s57, s57, 0
	s_mov_b32 m0, s64
	v_lshl_add_u64 v[228:229], s[56:57], 0, v[176:177]
	ds_read_b128 v[160:163], v211 offset:32768
	ds_read_b128 v[164:167], v211 offset:33792
	ds_read_b128 v[168:171], v211 offset:34816
	ds_read_b128 v[172:175], v211 offset:35840
	ds_read_b128 v[192:195], v211 offset:36864
	ds_read_b128 v[196:199], v211 offset:37888
	ds_read_b128 v[200:203], v211 offset:38912
	ds_read_b128 v[218:221], v211 offset:39936
	global_load_lds_dwordx4 v[228:229], off
	v_lshl_add_u64 v[228:229], s[56:57], 0, v[180:181]
	s_mov_b32 m0, s65
	s_nop 0
	global_load_lds_dwordx4 v[228:229], off
	s_waitcnt vmcnt(8)
	s_waitcnt lgkmcnt(0)
	s_barrier
	s_setprio 1
	s_waitcnt lgkmcnt(0)
	v_mfma_f32_16x16x32_bf16 v[124:127], v[128:131], v[160:163], v[124:127]
	v_mfma_f32_16x16x32_bf16 v[120:123], v[136:139], v[160:163], v[120:123]
	v_mfma_f32_16x16x32_bf16 v[108:111], v[128:131], v[168:171], v[108:111]
	v_mfma_f32_16x16x32_bf16 v[104:107], v[136:139], v[168:171], v[104:107]
	v_mfma_f32_16x16x32_bf16 v[92:95], v[128:131], v[192:195], v[92:95]
	v_mfma_f32_16x16x32_bf16 v[88:91], v[136:139], v[192:195], v[88:91]
	v_mfma_f32_16x16x32_bf16 v[76:79], v[128:131], v[200:203], v[76:79]
	v_mfma_f32_16x16x32_bf16 v[72:75], v[136:139], v[200:203], v[72:75]
	v_mfma_f32_16x16x32_bf16 v[124:127], v[132:135], v[164:167], v[124:127]
	v_mfma_f32_16x16x32_bf16 v[120:123], v[140:143], v[164:167], v[120:123]
	v_mfma_f32_16x16x32_bf16 v[108:111], v[132:135], v[172:175], v[108:111]
	v_mfma_f32_16x16x32_bf16 v[104:107], v[140:143], v[172:175], v[104:107]
	v_mfma_f32_16x16x32_bf16 v[92:95], v[132:135], v[196:199], v[92:95]
	v_mfma_f32_16x16x32_bf16 v[88:91], v[140:143], v[196:199], v[88:91]
	v_mfma_f32_16x16x32_bf16 v[76:79], v[132:135], v[218:221], v[76:79]
	v_mfma_f32_16x16x32_bf16 v[72:75], v[140:143], v[218:221], v[72:75]
	s_setprio 0
	s_setprio 1
	v_mfma_f32_16x16x32_bf16 v[116:119], v[144:147], v[160:163], v[116:119]
	v_mfma_f32_16x16x32_bf16 v[112:115], v[152:155], v[160:163], v[112:115]
	v_mfma_f32_16x16x32_bf16 v[100:103], v[144:147], v[168:171], v[100:103]
	v_mfma_f32_16x16x32_bf16 v[96:99], v[152:155], v[168:171], v[96:99]
	v_mfma_f32_16x16x32_bf16 v[84:87], v[144:147], v[192:195], v[84:87]
	v_mfma_f32_16x16x32_bf16 v[80:83], v[152:155], v[192:195], v[80:83]
	v_mfma_f32_16x16x32_bf16 v[68:71], v[144:147], v[200:203], v[68:71]
	v_mfma_f32_16x16x32_bf16 v[64:67], v[152:155], v[200:203], v[64:67]
	v_mfma_f32_16x16x32_bf16 v[116:119], v[148:151], v[164:167], v[116:119]
	v_mfma_f32_16x16x32_bf16 v[112:115], v[156:159], v[164:167], v[112:115]
	v_mfma_f32_16x16x32_bf16 v[100:103], v[148:151], v[172:175], v[100:103]
	v_mfma_f32_16x16x32_bf16 v[96:99], v[156:159], v[172:175], v[96:99]
	v_mfma_f32_16x16x32_bf16 v[84:87], v[148:151], v[196:199], v[84:87]
	v_mfma_f32_16x16x32_bf16 v[80:83], v[156:159], v[196:199], v[80:83]
	v_mfma_f32_16x16x32_bf16 v[68:71], v[148:151], v[218:221], v[68:71]
	v_mfma_f32_16x16x32_bf16 v[64:67], v[156:159], v[218:221], v[64:67]
	s_setprio 0
	s_barrier
	s_add_i32 s56, s77, s61
	v_lshl_add_u64 v[214:215], v[214:215], 0, s[26:27]
	s_mov_b32 m0, s56
	ds_read_b128 v[160:163], v211 offset:49152
	ds_read_b128 v[164:167], v211 offset:50176
	ds_read_b128 v[168:171], v211 offset:51200
	ds_read_b128 v[172:175], v211 offset:52224
	ds_read_b128 v[192:195], v211 offset:53248
	ds_read_b128 v[196:199], v211 offset:54272
	ds_read_b128 v[200:203], v211 offset:55296
	ds_read_b128 v[218:221], v211 offset:56320
	global_load_lds_dwordx4 v[214:215], off
	s_add_i32 m0, s56, 0x2000
	s_add_u32 s54, s54, 0x40080
	v_lshl_add_u64 v[214:215], v[222:223], 0, s[26:27]
	s_addc_u32 s55, s55, 0
	s_add_i32 s56, s78, s61
	global_load_lds_dwordx4 v[214:215], off
	v_lshl_add_u64 v[214:215], s[54:55], 0, v[178:179]
	s_mov_b32 m0, s56
	s_nop 0
	global_load_lds_dwordx4 v[214:215], off
	v_lshl_add_u64 v[214:215], s[54:55], 0, v[182:183]
	s_add_i32 m0, s56, 0x2000
	s_nop 0
	global_load_lds_dwordx4 v[214:215], off
	v_lshl_add_u64 v[214:215], v[224:225], 0, s[26:27]
	s_mov_b32 m0, s67
	s_nop 0
	global_load_lds_dwordx4 v[214:215], off
	v_lshl_add_u64 v[214:215], v[226:227], 0, s[26:27]
	s_mov_b32 m0, s68
	s_nop 0
	global_load_lds_dwordx4 v[214:215], off
	s_waitcnt vmcnt(8)
	s_waitcnt lgkmcnt(0)
	s_barrier
	s_setprio 1
	s_waitcnt lgkmcnt(0)
	v_mfma_f32_16x16x32_bf16 v[60:63], v[128:131], v[160:163], v[60:63]
	v_mfma_f32_16x16x32_bf16 v[56:59], v[136:139], v[160:163], v[56:59]
	v_mfma_f32_16x16x32_bf16 v[44:47], v[128:131], v[168:171], v[44:47]
	v_mfma_f32_16x16x32_bf16 v[40:43], v[136:139], v[168:171], v[40:43]
	v_mfma_f32_16x16x32_bf16 v[28:31], v[128:131], v[192:195], v[28:31]
	v_mfma_f32_16x16x32_bf16 v[24:27], v[136:139], v[192:195], v[24:27]
	v_mfma_f32_16x16x32_bf16 v[12:15], v[128:131], v[200:203], v[12:15]
	v_mfma_f32_16x16x32_bf16 v[8:11], v[136:139], v[200:203], v[8:11]
	v_mfma_f32_16x16x32_bf16 v[60:63], v[132:135], v[164:167], v[60:63]
	v_mfma_f32_16x16x32_bf16 v[56:59], v[140:143], v[164:167], v[56:59]
	v_mfma_f32_16x16x32_bf16 v[44:47], v[132:135], v[172:175], v[44:47]
	v_mfma_f32_16x16x32_bf16 v[40:43], v[140:143], v[172:175], v[40:43]
	v_mfma_f32_16x16x32_bf16 v[28:31], v[132:135], v[196:199], v[28:31]
	v_mfma_f32_16x16x32_bf16 v[24:27], v[140:143], v[196:199], v[24:27]
	v_mfma_f32_16x16x32_bf16 v[12:15], v[132:135], v[218:221], v[12:15]
	v_mfma_f32_16x16x32_bf16 v[8:11], v[140:143], v[218:221], v[8:11]
	s_setprio 0
	s_setprio 1
	v_mfma_f32_16x16x32_bf16 v[52:55], v[144:147], v[160:163], v[52:55]
	v_mfma_f32_16x16x32_bf16 v[48:51], v[152:155], v[160:163], v[48:51]
	v_mfma_f32_16x16x32_bf16 v[36:39], v[144:147], v[168:171], v[36:39]
	v_mfma_f32_16x16x32_bf16 v[32:35], v[152:155], v[168:171], v[32:35]
	v_mfma_f32_16x16x32_bf16 v[20:23], v[144:147], v[192:195], v[20:23]
	v_mfma_f32_16x16x32_bf16 v[16:19], v[152:155], v[192:195], v[16:19]
	v_mfma_f32_16x16x32_bf16 v[4:7], v[144:147], v[200:203], v[4:7]
	v_mfma_f32_16x16x32_bf16 v[0:3], v[152:155], v[200:203], v[0:3]
	v_mfma_f32_16x16x32_bf16 v[52:55], v[148:151], v[164:167], v[52:55]
	v_mfma_f32_16x16x32_bf16 v[48:51], v[156:159], v[164:167], v[48:51]
	v_mfma_f32_16x16x32_bf16 v[36:39], v[148:151], v[172:175], v[36:39]
	v_mfma_f32_16x16x32_bf16 v[32:35], v[156:159], v[172:175], v[32:35]
	v_mfma_f32_16x16x32_bf16 v[20:23], v[148:151], v[196:199], v[20:23]
	v_mfma_f32_16x16x32_bf16 v[16:19], v[156:159], v[196:199], v[16:19]
	v_mfma_f32_16x16x32_bf16 v[4:7], v[148:151], v[218:221], v[4:7]
	v_mfma_f32_16x16x32_bf16 v[0:3], v[156:159], v[218:221], v[0:3]
	s_setprio 0
	s_barrier
	s_add_i32 s76, s76, 2
	s_add_u32 s52, s52, 0x100
	s_addc_u32 s53, s53, 0
	s_add_u32 s51, s51, 0x100
	s_addc_u32 s75, s75, 0
	s_cmp_gt_u32 s76, 13
	s_cbranch_scc0 .LBB0_294
	s_and_b64 vcc, exec, s[28:29]
	s_cbranch_vccz .LBB0_297
	s_barrier

.LBB0_375:
	s_add_u32 s73, s24, 0x400000
	s_addc_u32 s74, s25, 0
	s_add_u32 s28, s24, 0x10000000
	s_addc_u32 s29, s25, 0
	s_lshl_b32 s5, s5, 5
	s_mov_b64 s[30:31], 0x80
	s_and_b32 s76, s5, 0x60
	s_add_i32 m0, s53, 0x18000
	v_lshl_add_u64 v[6:7], v[6:7], 0, s[30:31]
	s_lshl_b32 s75, s4, 6
	s_lshl_b32 s8, s4, 13
	s_lshl_b32 s5, s76, 7
	s_waitcnt vmcnt(2)
	s_barrier
	global_load_lds_dwordx4 v[6:7], off
	v_lshl_add_u64 v[4:5], v[4:5], 0, s[30:31]
	s_add_i32 m0, s53, 0x1a000
	s_add_i32 s77, s53, 0x8000
	s_add_i32 s78, s53, 0xa000
	global_load_lds_dwordx4 v[4:5], off
	v_lshl_add_u64 v[0:1], v[0:1], 0, s[30:31]
	s_mov_b32 m0, s77
	s_add_u32 s6, s12, 0x40080
	global_load_lds_dwordx4 v[0:1], off
	v_lshl_add_u64 v[0:1], v[2:3], 0, s[30:31]
	s_mov_b32 m0, s78
	s_addc_u32 s7, s13, 0
	global_load_lds_dwordx4 v[0:1], off
	s_add_i32 m0, s53, 0x1c000
	v_lshl_add_u64 v[0:1], s[6:7], 0, v[172:173]
	global_load_lds_dwordx4 v[0:1], off
	v_lshl_add_u64 v[0:1], s[6:7], 0, v[168:169]
	s_add_i32 m0, s53, 0x1e000
	s_movk_i32 s6, 0x3c0
	global_load_lds_dwordx4 v[0:1], off
	v_and_b32_e32 v0, 48, v8
	v_lshlrev_b32_e32 v1, 6, v8
	v_and_or_b32 v0, v1, s6, v0
	v_lshlrev_b32_e32 v1, 2, v8
	v_and_b32_e32 v1, 32, v1
	v_bitop3_b32 v2, v0, s8, v1 bitop3:0xde
	v_bitop3_b32 v203, s5, v0, v1 bitop3:0xf6
	v_lshlrev_b32_e32 v0, 14, v13
	v_and_b32_e32 v0, 0xffff8000, v0
	s_cmpk_lt_u32 s79, 0x100
	v_lshl_add_u32 v0, v12, 11, v0
	v_and_b32_e32 v1, 1, v13
	s_cselect_b64 s[34:35], -1, 0
	s_cmpk_gt_u32 s79, 0xff
	v_lshl_or_b32 v0, v1, 6, v0
	s_cselect_b64 s[36:37], -1, 0
	s_lshl_b32 s80, s4, 1
	v_lshl_add_u32 v178, v14, 1, v0
	v_lshlrev_b32_e32 v0, 14, v9
	s_andn2_b32 s79, s79, 63
	s_add_i32 s80, s80, 0x3ffff2
	s_lshl_b32 s81, s4, 11
	s_add_i32 s4, s4, 2
	v_and_b32_e32 v0, 0xffff8000, v0
	s_waitcnt vmcnt(6)
	s_cmp_lg_u32 s4, 0
	v_lshl_add_u32 v0, v10, 11, v0
	v_and_b32_e32 v1, 1, v9
	s_cselect_b64 s[38:39], -1, 0
	v_lshl_or_b32 v0, v1, 6, v0
	s_add_i32 s83, 0, 0x10000
	s_add_i32 s94, 0, 0x14000
	v_and_b32_e32 v202, 63, v8
	s_lshl_b32 s82, s4, 11
	v_mov_b32_e32 v179, v177
	v_lshl_add_u32 v180, v11, 1, v0
	v_mov_b32_e32 v181, v177
	v_mov_b64_e32 v[182:183], 0x1600
	v_mov_b64_e32 v[184:185], 0x15ff
	v_add_u32_e32 v204, s83, v203
	v_add_u32_e32 v205, s94, v203
	v_add_u32_e32 v206, 0, v2
	v_mov_b32_e32 v207, 0x358637bd
	s_movk_i32 s95, 0x5800
	s_movk_i32 s96, 0x1600
	v_mov_b32_e32 v208, 0xb000
	v_mov_b32_e32 v209, 2
	s_mov_b32 s8, s50
	s_mov_b32 s4, s52
	s_barrier
	s_mov_b32 s99, 0
	s_branch .LBB0_378

.LBB0_377:
	s_mov_b32 s99, 2
	s_andn2_b64 vcc, exec, s[6:7]
	s_mov_b32 s8, s56
	s_mov_b32 s4, s58
	s_mov_b64 s[12:13], s[62:63]
	s_mov_b64 s[10:11], s[60:61]
	s_mov_b32 s9, s97
	s_cbranch_vccz .LBB0_410

.LBB0_381:
	ds_read_b128 v[128:131], v204
	ds_read_b128 v[132:135], v204 offset:1024
	ds_read_b128 v[136:139], v204 offset:2048
	ds_read_b128 v[140:143], v204 offset:3072
	ds_read_b128 v[144:147], v205
	ds_read_b128 v[148:151], v205 offset:1024
	ds_read_b128 v[152:155], v205 offset:2048
	ds_read_b128 v[156:159], v205 offset:3072
	s_add_u32 s12, s10, 0xfffc0080
	s_addc_u32 s13, s11, -1
	s_cmp_eq_u32 s84, 12
	s_cselect_b32 s15, s5, s13
	s_cselect_b32 s14, s51, s12
	s_cselect_b32 s13, s54, s59
	s_cselect_b32 s12, s55, s57
	v_lshl_add_u64 v[214:215], s[10:11], 0, v[178:179]
	s_add_i32 m0, s53, 0xc000
	ds_read_b128 v[160:163], v206
	ds_read_b128 v[164:167], v206 offset:1024
	ds_read_b128 v[186:189], v206 offset:2048
	ds_read_b128 v[190:193], v206 offset:3072
	ds_read_b128 v[194:197], v206 offset:4096
	ds_read_b128 v[198:201], v206 offset:5120
	ds_read_b128 v[210:213], v206 offset:6144
	ds_read_b128 v[218:221], v206 offset:7168
	global_load_lds_dwordx4 v[214:215], off
	v_lshl_add_u64 v[214:215], s[10:11], 0, v[180:181]
	s_add_i32 m0, s53, 0xe000
	s_nop 0
	global_load_lds_dwordx4 v[214:215], off
	s_cmp_lg_u32 s84, -2
	s_cbranch_scc1 .Lzacc2a
	v_mov_b32_e32 v24, 0
	v_mov_b32_e32 v25, 0
	v_mov_b32_e32 v26, 0
	v_mov_b32_e32 v27, 0
	v_mov_b32_e32 v36, 0
	v_mov_b32_e32 v37, 0
	v_mov_b32_e32 v38, 0
	v_mov_b32_e32 v39, 0
	v_mov_b32_e32 v52, 0
	v_mov_b32_e32 v53, 0
	v_mov_b32_e32 v54, 0
	v_mov_b32_e32 v55, 0
	v_mov_b32_e32 v64, 0
	v_mov_b32_e32 v65, 0
	v_mov_b32_e32 v66, 0
	v_mov_b32_e32 v67, 0
	v_mov_b32_e32 v80, 0
	v_mov_b32_e32 v81, 0
	v_mov_b32_e32 v82, 0
	v_mov_b32_e32 v83, 0
	v_mov_b32_e32 v84, 0
	v_mov_b32_e32 v85, 0
	v_mov_b32_e32 v86, 0
	v_mov_b32_e32 v87, 0
	v_mov_b32_e32 v88, 0
	v_mov_b32_e32 v89, 0
	v_mov_b32_e32 v90, 0
	v_mov_b32_e32 v91, 0
	v_mov_b32_e32 v92, 0
	v_mov_b32_e32 v93, 0
	v_mov_b32_e32 v94, 0
	v_mov_b32_e32 v95, 0
	v_mov_b32_e32 v96, 0
	v_mov_b32_e32 v97, 0
	v_mov_b32_e32 v98, 0
	v_mov_b32_e32 v99, 0
	v_mov_b32_e32 v100, 0
	v_mov_b32_e32 v101, 0
	v_mov_b32_e32 v102, 0
	v_mov_b32_e32 v103, 0
	v_mov_b32_e32 v104, 0
	v_mov_b32_e32 v105, 0
	v_mov_b32_e32 v106, 0
	v_mov_b32_e32 v107, 0
	v_mov_b32_e32 v108, 0
	v_mov_b32_e32 v109, 0
	v_mov_b32_e32 v110, 0
	v_mov_b32_e32 v111, 0
	v_mov_b32_e32 v112, 0
	v_mov_b32_e32 v113, 0
	v_mov_b32_e32 v114, 0
	v_mov_b32_e32 v115, 0
	v_mov_b32_e32 v116, 0
	v_mov_b32_e32 v117, 0
	v_mov_b32_e32 v118, 0
	v_mov_b32_e32 v119, 0
	v_mov_b32_e32 v120, 0
	v_mov_b32_e32 v121, 0
	v_mov_b32_e32 v122, 0
	v_mov_b32_e32 v123, 0
	v_mov_b32_e32 v124, 0
	v_mov_b32_e32 v125, 0
	v_mov_b32_e32 v126, 0
	v_mov_b32_e32 v127, 0
	s_cmp_eq_u32 s99, 0
	s_cbranch_scc1 .Lzacc2a
	s_sub_u32 s99, s99, 1
	s_waitcnt vmcnt(16)
	s_branch .Lzacc2a_done

.Lzacc2a_done:
	s_waitcnt lgkmcnt(0)
	s_barrier
	s_setprio 1
	s_waitcnt lgkmcnt(0)
	v_mfma_f32_16x16x32_bf16 v[124:127], v[128:131], v[160:163], v[124:127]
	v_mfma_f32_16x16x32_bf16 v[120:123], v[136:139], v[160:163], v[120:123]
	v_mfma_f32_16x16x32_bf16 v[116:119], v[128:131], v[186:189], v[116:119]
	v_mfma_f32_16x16x32_bf16 v[112:115], v[136:139], v[186:189], v[112:115]
	v_mfma_f32_16x16x32_bf16 v[108:111], v[128:131], v[194:197], v[108:111]
	v_mfma_f32_16x16x32_bf16 v[104:107], v[136:139], v[194:197], v[104:107]
	v_mfma_f32_16x16x32_bf16 v[92:95], v[128:131], v[210:213], v[92:95]
	v_mfma_f32_16x16x32_bf16 v[84:87], v[136:139], v[210:213], v[84:87]
	v_mfma_f32_16x16x32_bf16 v[124:127], v[132:135], v[164:167], v[124:127]
	v_mfma_f32_16x16x32_bf16 v[120:123], v[140:143], v[164:167], v[120:123]
	v_mfma_f32_16x16x32_bf16 v[116:119], v[132:135], v[190:193], v[116:119]
	v_mfma_f32_16x16x32_bf16 v[112:115], v[140:143], v[190:193], v[112:115]
	v_mfma_f32_16x16x32_bf16 v[108:111], v[132:135], v[198:201], v[108:111]
	v_mfma_f32_16x16x32_bf16 v[104:107], v[140:143], v[198:201], v[104:107]
	v_mfma_f32_16x16x32_bf16 v[92:95], v[132:135], v[218:221], v[92:95]
	v_mfma_f32_16x16x32_bf16 v[84:87], v[140:143], v[218:221], v[84:87]
	s_setprio 0
	s_setprio 1
	v_mfma_f32_16x16x32_bf16 v[88:91], v[144:147], v[160:163], v[88:91]
	v_mfma_f32_16x16x32_bf16 v[24:27], v[152:155], v[160:163], v[24:27]
	v_mfma_f32_16x16x32_bf16 v[100:103], v[144:147], v[186:189], v[100:103]
	v_mfma_f32_16x16x32_bf16 v[36:39], v[152:155], v[186:189], v[36:39]
	v_mfma_f32_16x16x32_bf16 v[96:99], v[144:147], v[194:197], v[96:99]
	v_mfma_f32_16x16x32_bf16 v[52:55], v[152:155], v[194:197], v[52:55]
	v_mfma_f32_16x16x32_bf16 v[80:83], v[144:147], v[210:213], v[80:83]
	v_mfma_f32_16x16x32_bf16 v[64:67], v[152:155], v[210:213], v[64:67]
	v_mfma_f32_16x16x32_bf16 v[88:91], v[148:151], v[164:167], v[88:91]
	v_mfma_f32_16x16x32_bf16 v[24:27], v[156:159], v[164:167], v[24:27]
	v_mfma_f32_16x16x32_bf16 v[100:103], v[148:151], v[190:193], v[100:103]
	v_mfma_f32_16x16x32_bf16 v[36:39], v[156:159], v[190:193], v[36:39]
	v_mfma_f32_16x16x32_bf16 v[96:99], v[148:151], v[198:201], v[96:99]
	v_mfma_f32_16x16x32_bf16 v[52:55], v[156:159], v[198:201], v[52:55]
	v_mfma_f32_16x16x32_bf16 v[80:83], v[148:151], v[218:221], v[80:83]
	v_mfma_f32_16x16x32_bf16 v[64:67], v[156:159], v[218:221], v[64:67]
	s_setprio 0
	s_barrier
	s_add_i32 s85, s83, s67
	v_lshl_add_u64 v[214:215], s[12:13], 0, v[172:173]
	s_mov_b32 m0, s85
	ds_read_b128 v[160:163], v206 offset:16384
	ds_read_b128 v[164:167], v206 offset:17408
	ds_read_b128 v[186:189], v206 offset:18432
	ds_read_b128 v[190:193], v206 offset:19456
	ds_read_b128 v[194:197], v206 offset:20480
	ds_read_b128 v[198:201], v206 offset:21504
	ds_read_b128 v[210:213], v206 offset:22528
	ds_read_b128 v[218:221], v206 offset:23552
	global_load_lds_dwordx4 v[214:215], off
	s_add_i32 m0, s85, 0x2000
	s_add_u32 s92, s12, 0x40000
	v_lshl_add_u64 v[222:223], s[12:13], 0, v[168:169]
	s_addc_u32 s93, s13, 0
	s_add_i32 s85, s94, s67
	global_load_lds_dwordx4 v[222:223], off
	v_lshl_add_u64 v[224:225], s[92:93], 0, v[172:173]
	s_mov_b32 m0, s85
	v_lshl_add_u64 v[226:227], s[14:15], 0, v[170:171]
	global_load_lds_dwordx4 v[224:225], off
	v_lshl_add_u64 v[224:225], s[92:93], 0, v[168:169]
	s_add_i32 m0, s85, 0x2000
	s_nop 0
	global_load_lds_dwordx4 v[224:225], off
	v_lshl_add_u64 v[224:225], s[14:15], 0, v[174:175]
	s_mov_b32 m0, s53
	s_nop 0
	global_load_lds_dwordx4 v[224:225], off
	s_mov_b32 m0, s68
	s_nop 0
	global_load_lds_dwordx4 v[226:227], off
	s_cmp_lg_u32 s84, -2
	s_cbranch_scc1 .Lzacc2b
	v_mov_b32_e32 v0, 0
	v_mov_b32_e32 v1, 0
	v_mov_b32_e32 v2, 0
	v_mov_b32_e32 v3, 0
	v_mov_b32_e32 v4, 0
	v_mov_b32_e32 v5, 0
	v_mov_b32_e32 v6, 0
	v_mov_b32_e32 v7, 0
	v_mov_b32_e32 v8, 0
	v_mov_b32_e32 v9, 0
	v_mov_b32_e32 v10, 0
	v_mov_b32_e32 v11, 0
	v_mov_b32_e32 v12, 0
	v_mov_b32_e32 v13, 0
	v_mov_b32_e32 v14, 0
	v_mov_b32_e32 v15, 0
	v_mov_b32_e32 v16, 0
	v_mov_b32_e32 v17, 0
	v_mov_b32_e32 v18, 0
	v_mov_b32_e32 v19, 0
	v_mov_b32_e32 v20, 0
	v_mov_b32_e32 v21, 0
	v_mov_b32_e32 v22, 0
	v_mov_b32_e32 v23, 0
	v_mov_b32_e32 v28, 0
	v_mov_b32_e32 v29, 0
	v_mov_b32_e32 v30, 0
	v_mov_b32_e32 v31, 0
	v_mov_b32_e32 v32, 0
	v_mov_b32_e32 v33, 0
	v_mov_b32_e32 v34, 0
	v_mov_b32_e32 v35, 0
	v_mov_b32_e32 v40, 0
	v_mov_b32_e32 v41, 0
	v_mov_b32_e32 v42, 0
	v_mov_b32_e32 v43, 0
	v_mov_b32_e32 v44, 0
	v_mov_b32_e32 v45, 0
	v_mov_b32_e32 v46, 0
	v_mov_b32_e32 v47, 0
	v_mov_b32_e32 v48, 0
	v_mov_b32_e32 v49, 0
	v_mov_b32_e32 v50, 0
	v_mov_b32_e32 v51, 0
	v_mov_b32_e32 v56, 0
	v_mov_b32_e32 v57, 0
	v_mov_b32_e32 v58, 0
	v_mov_b32_e32 v59, 0
	v_mov_b32_e32 v60, 0
	v_mov_b32_e32 v61, 0
	v_mov_b32_e32 v62, 0
	v_mov_b32_e32 v63, 0
	v_mov_b32_e32 v68, 0
	v_mov_b32_e32 v69, 0
	v_mov_b32_e32 v70, 0
	v_mov_b32_e32 v71, 0
	v_mov_b32_e32 v72, 0
	v_mov_b32_e32 v73, 0
	v_mov_b32_e32 v74, 0
	v_mov_b32_e32 v75, 0
	v_mov_b32_e32 v76, 0
	v_mov_b32_e32 v77, 0
	v_mov_b32_e32 v78, 0
	v_mov_b32_e32 v79, 0
	s_cmp_eq_u32 s99, 0
	s_cbranch_scc1 .Lzacc2b
	s_sub_u32 s99, s99, 1
	s_waitcnt vmcnt(16)
	s_branch .Lzacc2b_done

.Lzacc2b_done:
	s_waitcnt lgkmcnt(0)
	s_barrier
	s_setprio 1
	s_waitcnt lgkmcnt(0)
	v_mfma_f32_16x16x32_bf16 v[76:79], v[128:131], v[160:163], v[76:79]
	v_mfma_f32_16x16x32_bf16 v[72:75], v[136:139], v[160:163], v[72:75]
	v_mfma_f32_16x16x32_bf16 v[60:63], v[128:131], v[186:189], v[60:63]
	v_mfma_f32_16x16x32_bf16 v[56:59], v[136:139], v[186:189], v[56:59]
	v_mfma_f32_16x16x32_bf16 v[44:47], v[128:131], v[194:197], v[44:47]
	v_mfma_f32_16x16x32_bf16 v[40:43], v[136:139], v[194:197], v[40:43]
	v_mfma_f32_16x16x32_bf16 v[20:23], v[128:131], v[210:213], v[20:23]
	v_mfma_f32_16x16x32_bf16 v[8:11], v[136:139], v[210:213], v[8:11]
	v_mfma_f32_16x16x32_bf16 v[76:79], v[132:135], v[164:167], v[76:79]
	v_mfma_f32_16x16x32_bf16 v[72:75], v[140:143], v[164:167], v[72:75]
	v_mfma_f32_16x16x32_bf16 v[60:63], v[132:135], v[190:193], v[60:63]
	v_mfma_f32_16x16x32_bf16 v[56:59], v[140:143], v[190:193], v[56:59]
	v_mfma_f32_16x16x32_bf16 v[44:47], v[132:135], v[198:201], v[44:47]
	v_mfma_f32_16x16x32_bf16 v[40:43], v[140:143], v[198:201], v[40:43]
	v_mfma_f32_16x16x32_bf16 v[20:23], v[132:135], v[218:221], v[20:23]
	v_mfma_f32_16x16x32_bf16 v[8:11], v[140:143], v[218:221], v[8:11]
	s_setprio 0
	s_setprio 1
	v_mfma_f32_16x16x32_bf16 v[68:71], v[144:147], v[160:163], v[68:71]
	v_mfma_f32_16x16x32_bf16 v[12:15], v[152:155], v[160:163], v[12:15]
	v_mfma_f32_16x16x32_bf16 v[48:51], v[144:147], v[186:189], v[48:51]
	v_mfma_f32_16x16x32_bf16 v[28:31], v[152:155], v[186:189], v[28:31]
	v_mfma_f32_16x16x32_bf16 v[32:35], v[144:147], v[194:197], v[32:35]
	v_mfma_f32_16x16x32_bf16 v[16:19], v[152:155], v[194:197], v[16:19]
	v_mfma_f32_16x16x32_bf16 v[4:7], v[144:147], v[210:213], v[4:7]
	v_mfma_f32_16x16x32_bf16 v[0:3], v[152:155], v[210:213], v[0:3]
	v_mfma_f32_16x16x32_bf16 v[68:71], v[148:151], v[164:167], v[68:71]
	v_mfma_f32_16x16x32_bf16 v[12:15], v[156:159], v[164:167], v[12:15]
	v_mfma_f32_16x16x32_bf16 v[48:51], v[148:151], v[190:193], v[48:51]
	v_mfma_f32_16x16x32_bf16 v[28:31], v[156:159], v[190:193], v[28:31]
	v_mfma_f32_16x16x32_bf16 v[32:35], v[148:151], v[198:201], v[32:35]
	v_mfma_f32_16x16x32_bf16 v[16:19], v[156:159], v[198:201], v[16:19]
	v_mfma_f32_16x16x32_bf16 v[4:7], v[148:151], v[218:221], v[4:7]
	v_mfma_f32_16x16x32_bf16 v[0:3], v[156:159], v[218:221], v[0:3]
	s_setprio 0
	s_barrier
	s_add_i32 s85, 0, 0x18000
	s_add_i32 s89, 0, 0x1c000
	v_add_u32_e32 v140, s85, v203
	v_add_u32_e32 v156, s89, v203
	ds_read_b128 v[128:131], v140
	ds_read_b128 v[132:135], v140 offset:1024
	ds_read_b128 v[136:139], v140 offset:2048
	ds_read_b128 v[140:143], v140 offset:3072
	ds_read_b128 v[144:147], v156
	ds_read_b128 v[148:151], v156 offset:1024
	ds_read_b128 v[152:155], v156 offset:2048
	ds_read_b128 v[156:159], v156 offset:3072
	s_add_u32 s14, s14, 0x40000
	s_addc_u32 s15, s15, 0
	s_mov_b32 m0, s69
	v_lshl_add_u64 v[228:229], s[14:15], 0, v[174:175]
	ds_read_b128 v[160:163], v206 offset:32768
	ds_read_b128 v[164:167], v206 offset:33792
	ds_read_b128 v[186:189], v206 offset:34816
	ds_read_b128 v[190:193], v206 offset:35840
	ds_read_b128 v[194:197], v206 offset:36864
	ds_read_b128 v[198:201], v206 offset:37888
	ds_read_b128 v[210:213], v206 offset:38912
	ds_read_b128 v[218:221], v206 offset:39936
	global_load_lds_dwordx4 v[228:229], off
	v_lshl_add_u64 v[228:229], s[14:15], 0, v[170:171]
	s_mov_b32 m0, s72
	s_nop 0
	global_load_lds_dwordx4 v[228:229], off
	s_waitcnt vmcnt(8)
	s_waitcnt lgkmcnt(0)
	s_barrier
	s_setprio 1
	s_waitcnt lgkmcnt(0)
	v_mfma_f32_16x16x32_bf16 v[124:127], v[128:131], v[160:163], v[124:127]
	v_mfma_f32_16x16x32_bf16 v[120:123], v[136:139], v[160:163], v[120:123]
	v_mfma_f32_16x16x32_bf16 v[116:119], v[128:131], v[186:189], v[116:119]
	v_mfma_f32_16x16x32_bf16 v[112:115], v[136:139], v[186:189], v[112:115]
	v_mfma_f32_16x16x32_bf16 v[108:111], v[128:131], v[194:197], v[108:111]
	v_mfma_f32_16x16x32_bf16 v[104:107], v[136:139], v[194:197], v[104:107]
	v_mfma_f32_16x16x32_bf16 v[92:95], v[128:131], v[210:213], v[92:95]
	v_mfma_f32_16x16x32_bf16 v[84:87], v[136:139], v[210:213], v[84:87]
	v_mfma_f32_16x16x32_bf16 v[124:127], v[132:135], v[164:167], v[124:127]
	v_mfma_f32_16x16x32_bf16 v[120:123], v[140:143], v[164:167], v[120:123]
	v_mfma_f32_16x16x32_bf16 v[116:119], v[132:135], v[190:193], v[116:119]
	v_mfma_f32_16x16x32_bf16 v[112:115], v[140:143], v[190:193], v[112:115]
	v_mfma_f32_16x16x32_bf16 v[108:111], v[132:135], v[198:201], v[108:111]
	v_mfma_f32_16x16x32_bf16 v[104:107], v[140:143], v[198:201], v[104:107]
	v_mfma_f32_16x16x32_bf16 v[92:95], v[132:135], v[218:221], v[92:95]
	v_mfma_f32_16x16x32_bf16 v[84:87], v[140:143], v[218:221], v[84:87]
	s_setprio 0
	s_setprio 1
	v_mfma_f32_16x16x32_bf16 v[88:91], v[144:147], v[160:163], v[88:91]
	v_mfma_f32_16x16x32_bf16 v[24:27], v[152:155], v[160:163], v[24:27]
	v_mfma_f32_16x16x32_bf16 v[100:103], v[144:147], v[186:189], v[100:103]
	v_mfma_f32_16x16x32_bf16 v[36:39], v[152:155], v[186:189], v[36:39]
	v_mfma_f32_16x16x32_bf16 v[96:99], v[144:147], v[194:197], v[96:99]
	v_mfma_f32_16x16x32_bf16 v[52:55], v[152:155], v[194:197], v[52:55]
	v_mfma_f32_16x16x32_bf16 v[80:83], v[144:147], v[210:213], v[80:83]
	v_mfma_f32_16x16x32_bf16 v[64:67], v[152:155], v[210:213], v[64:67]
	v_mfma_f32_16x16x32_bf16 v[88:91], v[148:151], v[164:167], v[88:91]
	v_mfma_f32_16x16x32_bf16 v[24:27], v[156:159], v[164:167], v[24:27]
	v_mfma_f32_16x16x32_bf16 v[100:103], v[148:151], v[190:193], v[100:103]
	v_mfma_f32_16x16x32_bf16 v[36:39], v[156:159], v[190:193], v[36:39]
	v_mfma_f32_16x16x32_bf16 v[96:99], v[148:151], v[198:201], v[96:99]
	v_mfma_f32_16x16x32_bf16 v[52:55], v[156:159], v[198:201], v[52:55]
	v_mfma_f32_16x16x32_bf16 v[80:83], v[148:151], v[218:221], v[80:83]
	v_mfma_f32_16x16x32_bf16 v[64:67], v[156:159], v[218:221], v[64:67]
	s_setprio 0
	s_barrier
	s_add_i32 s14, s85, s67
	v_lshl_add_u64 v[214:215], v[214:215], 0, s[30:31]
	s_mov_b32 m0, s14
	ds_read_b128 v[160:163], v206 offset:49152
	ds_read_b128 v[164:167], v206 offset:50176
	ds_read_b128 v[186:189], v206 offset:51200
	ds_read_b128 v[190:193], v206 offset:52224
	ds_read_b128 v[194:197], v206 offset:53248
	ds_read_b128 v[198:201], v206 offset:54272
	ds_read_b128 v[210:213], v206 offset:55296
	ds_read_b128 v[218:221], v206 offset:56320
	global_load_lds_dwordx4 v[214:215], off
	s_add_i32 m0, s14, 0x2000
	s_add_u32 s12, s12, 0x40080
	v_lshl_add_u64 v[214:215], v[222:223], 0, s[30:31]
	s_addc_u32 s13, s13, 0
	s_add_i32 s14, s89, s67
	global_load_lds_dwordx4 v[214:215], off
	v_lshl_add_u64 v[214:215], s[12:13], 0, v[172:173]
	s_mov_b32 m0, s14
	s_nop 0
	global_load_lds_dwordx4 v[214:215], off
	v_lshl_add_u64 v[214:215], s[12:13], 0, v[168:169]
	s_add_i32 m0, s14, 0x2000
	s_nop 0
	global_load_lds_dwordx4 v[214:215], off
	v_lshl_add_u64 v[214:215], v[224:225], 0, s[30:31]
	s_mov_b32 m0, s77
	s_nop 0
	global_load_lds_dwordx4 v[214:215], off
	v_lshl_add_u64 v[214:215], v[226:227], 0, s[30:31]
	s_mov_b32 m0, s78
	s_nop 0
	global_load_lds_dwordx4 v[214:215], off
	s_waitcnt vmcnt(8)
	s_waitcnt lgkmcnt(0)
	s_barrier
	s_setprio 1
	s_waitcnt lgkmcnt(0)
	v_mfma_f32_16x16x32_bf16 v[76:79], v[128:131], v[160:163], v[76:79]
	v_mfma_f32_16x16x32_bf16 v[72:75], v[136:139], v[160:163], v[72:75]
	v_mfma_f32_16x16x32_bf16 v[60:63], v[128:131], v[186:189], v[60:63]
	v_mfma_f32_16x16x32_bf16 v[56:59], v[136:139], v[186:189], v[56:59]
	v_mfma_f32_16x16x32_bf16 v[44:47], v[128:131], v[194:197], v[44:47]
	v_mfma_f32_16x16x32_bf16 v[40:43], v[136:139], v[194:197], v[40:43]
	v_mfma_f32_16x16x32_bf16 v[20:23], v[128:131], v[210:213], v[20:23]
	v_mfma_f32_16x16x32_bf16 v[8:11], v[136:139], v[210:213], v[8:11]
	v_mfma_f32_16x16x32_bf16 v[76:79], v[132:135], v[164:167], v[76:79]
	v_mfma_f32_16x16x32_bf16 v[72:75], v[140:143], v[164:167], v[72:75]
	v_mfma_f32_16x16x32_bf16 v[60:63], v[132:135], v[190:193], v[60:63]
	v_mfma_f32_16x16x32_bf16 v[56:59], v[140:143], v[190:193], v[56:59]
	v_mfma_f32_16x16x32_bf16 v[44:47], v[132:135], v[198:201], v[44:47]
	v_mfma_f32_16x16x32_bf16 v[40:43], v[140:143], v[198:201], v[40:43]
	v_mfma_f32_16x16x32_bf16 v[20:23], v[132:135], v[218:221], v[20:23]
	v_mfma_f32_16x16x32_bf16 v[8:11], v[140:143], v[218:221], v[8:11]
	s_setprio 0
	s_setprio 1
	v_mfma_f32_16x16x32_bf16 v[68:71], v[144:147], v[160:163], v[68:71]
	v_mfma_f32_16x16x32_bf16 v[12:15], v[152:155], v[160:163], v[12:15]
	v_mfma_f32_16x16x32_bf16 v[48:51], v[144:147], v[186:189], v[48:51]
	v_mfma_f32_16x16x32_bf16 v[28:31], v[152:155], v[186:189], v[28:31]
	v_mfma_f32_16x16x32_bf16 v[32:35], v[144:147], v[194:197], v[32:35]
	v_mfma_f32_16x16x32_bf16 v[16:19], v[152:155], v[194:197], v[16:19]
	v_mfma_f32_16x16x32_bf16 v[4:7], v[144:147], v[210:213], v[4:7]
	v_mfma_f32_16x16x32_bf16 v[0:3], v[152:155], v[210:213], v[0:3]
	v_mfma_f32_16x16x32_bf16 v[68:71], v[148:151], v[164:167], v[68:71]
	v_mfma_f32_16x16x32_bf16 v[12:15], v[156:159], v[164:167], v[12:15]
	v_mfma_f32_16x16x32_bf16 v[48:51], v[148:151], v[190:193], v[48:51]
	v_mfma_f32_16x16x32_bf16 v[28:31], v[156:159], v[190:193], v[28:31]
	v_mfma_f32_16x16x32_bf16 v[32:35], v[148:151], v[198:201], v[32:35]
	v_mfma_f32_16x16x32_bf16 v[16:19], v[156:159], v[198:201], v[16:19]
	v_mfma_f32_16x16x32_bf16 v[4:7], v[148:151], v[218:221], v[4:7]
	v_mfma_f32_16x16x32_bf16 v[0:3], v[156:159], v[218:221], v[0:3]
	s_setprio 0
	s_barrier
	s_add_i32 s84, s84, 2
	s_add_u32 s10, s10, 0x100
	s_addc_u32 s11, s11, 0
	s_add_u32 s57, s57, 0x100
	s_addc_u32 s59, s59, 0
	s_cmp_gt_u32 s84, 13
	s_cbranch_scc0 .LBB0_381
	s_and_b64 vcc, exec, s[34:35]
	s_cbranch_vccz .LBB0_384
	s_barrier

.LBB0_527:
	s_add_u32 s18, s6, 0x100000
	s_addc_u32 s19, s7, 0
	s_add_u32 s24, s6, 0x8000000
	s_mov_b64 s[26:27], 0x80
	s_addc_u32 s25, s7, 0
	s_and_b32 s11, s11, 3
	s_add_i32 m0, s69, 0x18000
	v_lshl_add_u64 v[6:7], v[6:7], 0, s[26:27]
	s_lshl_b32 s75, s9, 6
	s_lshl_b32 s9, s9, 13
	s_lshl_b32 s12, s11, 12
	s_waitcnt vmcnt(2)
	s_barrier
	global_load_lds_dwordx4 v[6:7], off
	v_lshl_add_u64 v[4:5], v[4:5], 0, s[26:27]
	s_add_i32 m0, s69, 0x1a000
	s_add_i32 s51, s69, 0x8000
	s_add_i32 s76, s69, 0xa000
	global_load_lds_dwordx4 v[4:5], off
	v_lshl_add_u64 v[0:1], v[0:1], 0, s[26:27]
	s_mov_b32 m0, s51
	s_add_u32 s6, s60, 0xb0080
	global_load_lds_dwordx4 v[0:1], off
	v_lshl_add_u64 v[0:1], v[2:3], 0, s[26:27]
	s_mov_b32 m0, s76
	s_addc_u32 s7, s61, 0
	global_load_lds_dwordx4 v[0:1], off
	s_add_i32 m0, s69, 0x1c000
	v_lshl_add_u64 v[0:1], s[6:7], 0, v[186:187]
	global_load_lds_dwordx4 v[0:1], off
	v_lshl_add_u64 v[0:1], s[6:7], 0, v[190:191]
	s_add_i32 m0, s69, 0x1e000
	s_cmpk_lt_u32 s8, 0x100
	global_load_lds_dwordx4 v[0:1], off
	v_lshrrev_b32_e32 v1, 1, v8
	v_and_b32_e32 v0, 63, v8
	v_and_b32_e32 v1, 24, v1
	v_lshl_or_b32 v221, s11, 5, v1
	s_cselect_b64 s[28:29], -1, 0
	v_cmp_gt_u32_e64 s[6:7], 16, v0
	s_lshl_b32 s77, s11, 10
	s_movk_i32 s11, 0xffc0
	v_mov_b32_e32 v0, s8
	v_bfi_b32 v222, s11, v0, v8
	v_lshrrev_b32_e32 v1, 1, v9
	v_mul_lo_u32 v0, v11, s10
	s_mov_b32 s11, 0xb000
	v_and_b32_e32 v218, 15, v8
	v_and_b32_e32 v2, 48, v8
	v_lshlrev_b32_e32 v3, 2, v8
	v_mad_u64_u32 v[0:1], s[30:31], v1, s11, v[0:1]
	v_lshl_or_b32 v2, v218, 6, v2
	v_and_b32_e32 v3, 32, v3
	v_or_b32_e32 v0, v0, v10
	v_bitop3_b32 v220, v2, s12, v3 bitop3:0xde
	s_mov_b64 s[12:13], 0xb0080
	v_add_lshl_u32 v0, v0, v12, 1
	v_mov_b32_e32 v1, v187
	v_lshl_add_u64 v[192:193], v[0:1], 0, s[12:13]
	v_lshrrev_b32_e32 v1, 1, v13
	v_mul_lo_u32 v0, v14, s10
	v_mad_u64_u32 v[0:1], s[10:11], v1, s11, v[0:1]
	s_waitcnt vmcnt(6)
	v_or_b32_e32 v0, v0, v15
	v_bitop3_b32 v4, v2, s9, v3 bitop3:0xde
	s_movk_i32 s9, 0x100
	v_add_lshl_u32 v0, v0, v16, 1
	v_mov_b32_e32 v1, v187
	s_add_i32 s78, 0, 0x10000
	s_add_i32 s79, 0, 0x14000
	v_or_b32_e32 v219, s75, v218
	v_cmp_gt_i32_e64 s[8:9], s9, v222
	v_lshl_add_u64 v[194:195], v[0:1], 0, s[12:13]
	v_mov_b64_e32 v[196:197], 0x400
	v_mov_b64_e32 v[198:199], 0x3ff
	v_add_u32_e32 v223, s78, v220
	v_add_u32_e32 v224, s79, v220
	v_add_u32_e32 v225, 0, v4
	s_mov_b64 s[30:31], 0x40000
	s_mov_b64 s[34:35], 0x48000
	s_mov_b64 s[36:37], 0x50000
	s_mov_b64 s[38:39], 0x58000
	v_mbcnt_hi_u32_b32 v226, -1, v248
	s_barrier
	s_mov_b32 s99, 0
	s_branch .LBB0_530

.LBB0_529:
	s_mov_b32 s99, 2
	s_andn2_b64 vcc, exec, s[10:11]
	s_mov_b32 s14, s81
	s_mov_b32 s4, s82
	s_mov_b64 s[60:61], s[56:57]
	s_mov_b64 s[58:59], s[12:13]
	s_mov_b32 s5, s80
	s_cbranch_vccz .LBB0_565

.LBB0_541:
	ds_read_b128 v[112:115], v223
	ds_read_b128 v[124:127], v223 offset:1024
	ds_read_b128 v[136:139], v223 offset:2048
	ds_read_b128 v[140:143], v223 offset:3072
	ds_read_b128 v[144:147], v224
	ds_read_b128 v[148:151], v224 offset:1024
	ds_read_b128 v[152:155], v224 offset:2048
	ds_read_b128 v[156:159], v224 offset:3072
	s_add_u32 s60, s58, 0x100
	s_addc_u32 s61, s59, 0
	s_cmp_eq_u32 s55, 40
	s_cselect_b32 s65, s13, s61
	s_cselect_b32 s64, s12, s60
	s_cselect_b32 s63, s57, s54
	s_cselect_b32 s62, s56, s15
	v_lshl_add_u64 v[208:209], s[58:59], 0, v[192:193]
	s_add_i32 m0, s69, 0xc000
	ds_read_b128 v[160:163], v225
	ds_read_b128 v[164:167], v225 offset:1024
	ds_read_b128 v[168:171], v225 offset:2048
	ds_read_b128 v[172:175], v225 offset:3072
	ds_read_b128 v[176:179], v225 offset:4096
	ds_read_b128 v[180:183], v225 offset:5120
	ds_read_b128 v[200:203], v225 offset:6144
	ds_read_b128 v[204:207], v225 offset:7168
	global_load_lds_dwordx4 v[208:209], off
	v_lshl_add_u64 v[208:209], s[58:59], 0, v[194:195]
	s_add_i32 m0, s69, 0xe000
	s_nop 0
	global_load_lds_dwordx4 v[208:209], off
	s_cmp_lg_u32 s55, -2
	s_cbranch_scc1 .Lzacc3a
	v_mov_b32_e32 v64, 0
	v_mov_b32_e32 v65, 0
	v_mov_b32_e32 v66, 0
	v_mov_b32_e32 v67, 0
	v_mov_b32_e32 v68, 0
	v_mov_b32_e32 v69, 0
	v_mov_b32_e32 v70, 0
	v_mov_b32_e32 v71, 0
	v_mov_b32_e32 v72, 0
	v_mov_b32_e32 v73, 0
	v_mov_b32_e32 v74, 0
	v_mov_b32_e32 v75, 0
	v_mov_b32_e32 v76, 0
	v_mov_b32_e32 v77, 0
	v_mov_b32_e32 v78, 0
	v_mov_b32_e32 v79, 0
	v_mov_b32_e32 v80, 0
	v_mov_b32_e32 v81, 0
	v_mov_b32_e32 v82, 0
	v_mov_b32_e32 v83, 0
	v_mov_b32_e32 v84, 0
	v_mov_b32_e32 v85, 0
	v_mov_b32_e32 v86, 0
	v_mov_b32_e32 v87, 0
	v_mov_b32_e32 v88, 0
	v_mov_b32_e32 v89, 0
	v_mov_b32_e32 v90, 0
	v_mov_b32_e32 v91, 0
	v_mov_b32_e32 v92, 0
	v_mov_b32_e32 v93, 0
	v_mov_b32_e32 v94, 0
	v_mov_b32_e32 v95, 0
	v_mov_b32_e32 v96, 0
	v_mov_b32_e32 v97, 0
	v_mov_b32_e32 v98, 0
	v_mov_b32_e32 v99, 0
	v_mov_b32_e32 v100, 0
	v_mov_b32_e32 v101, 0
	v_mov_b32_e32 v102, 0
	v_mov_b32_e32 v103, 0
	v_mov_b32_e32 v104, 0
	v_mov_b32_e32 v105, 0
	v_mov_b32_e32 v106, 0
	v_mov_b32_e32 v107, 0
	v_mov_b32_e32 v108, 0
	v_mov_b32_e32 v109, 0
	v_mov_b32_e32 v110, 0
	v_mov_b32_e32 v111, 0
	v_mov_b32_e32 v116, 0
	v_mov_b32_e32 v117, 0
	v_mov_b32_e32 v118, 0
	v_mov_b32_e32 v119, 0
	v_mov_b32_e32 v120, 0
	v_mov_b32_e32 v121, 0
	v_mov_b32_e32 v122, 0
	v_mov_b32_e32 v123, 0
	v_mov_b32_e32 v128, 0
	v_mov_b32_e32 v129, 0
	v_mov_b32_e32 v130, 0
	v_mov_b32_e32 v131, 0
	v_mov_b32_e32 v132, 0
	v_mov_b32_e32 v133, 0
	v_mov_b32_e32 v134, 0
	v_mov_b32_e32 v135, 0
	s_cmp_eq_u32 s99, 0
	s_cbranch_scc1 .Lzacc3a
	s_sub_u32 s99, s99, 1
	s_waitcnt vmcnt(24)
	s_branch .Lzacc3a_done

.Lzacc3a_done:
	s_waitcnt lgkmcnt(0)
	s_barrier
	s_setprio 1
	s_waitcnt lgkmcnt(0)
	v_mfma_f32_16x16x32_bf16 v[132:135], v[112:115], v[160:163], v[132:135]
	v_mfma_f32_16x16x32_bf16 v[128:131], v[136:139], v[160:163], v[128:131]
	v_mfma_f32_16x16x32_bf16 v[108:111], v[112:115], v[168:171], v[108:111]
	v_mfma_f32_16x16x32_bf16 v[104:107], v[136:139], v[168:171], v[104:107]
	v_mfma_f32_16x16x32_bf16 v[92:95], v[112:115], v[176:179], v[92:95]
	v_mfma_f32_16x16x32_bf16 v[88:91], v[136:139], v[176:179], v[88:91]
	v_mfma_f32_16x16x32_bf16 v[76:79], v[112:115], v[200:203], v[76:79]
	v_mfma_f32_16x16x32_bf16 v[72:75], v[136:139], v[200:203], v[72:75]
	v_mfma_f32_16x16x32_bf16 v[132:135], v[124:127], v[164:167], v[132:135]
	v_mfma_f32_16x16x32_bf16 v[128:131], v[140:143], v[164:167], v[128:131]
	v_mfma_f32_16x16x32_bf16 v[108:111], v[124:127], v[172:175], v[108:111]
	v_mfma_f32_16x16x32_bf16 v[104:107], v[140:143], v[172:175], v[104:107]
	v_mfma_f32_16x16x32_bf16 v[92:95], v[124:127], v[180:183], v[92:95]
	v_mfma_f32_16x16x32_bf16 v[88:91], v[140:143], v[180:183], v[88:91]
	v_mfma_f32_16x16x32_bf16 v[76:79], v[124:127], v[204:207], v[76:79]
	v_mfma_f32_16x16x32_bf16 v[72:75], v[140:143], v[204:207], v[72:75]
	s_setprio 0
	s_setprio 1
	v_mfma_f32_16x16x32_bf16 v[120:123], v[144:147], v[160:163], v[120:123]
	v_mfma_f32_16x16x32_bf16 v[116:119], v[152:155], v[160:163], v[116:119]
	v_mfma_f32_16x16x32_bf16 v[100:103], v[144:147], v[168:171], v[100:103]
	v_mfma_f32_16x16x32_bf16 v[96:99], v[152:155], v[168:171], v[96:99]
	v_mfma_f32_16x16x32_bf16 v[84:87], v[144:147], v[176:179], v[84:87]
	v_mfma_f32_16x16x32_bf16 v[80:83], v[152:155], v[176:179], v[80:83]
	v_mfma_f32_16x16x32_bf16 v[68:71], v[144:147], v[200:203], v[68:71]
	v_mfma_f32_16x16x32_bf16 v[64:67], v[152:155], v[200:203], v[64:67]
	v_mfma_f32_16x16x32_bf16 v[120:123], v[148:151], v[164:167], v[120:123]
	v_mfma_f32_16x16x32_bf16 v[116:119], v[156:159], v[164:167], v[116:119]
	v_mfma_f32_16x16x32_bf16 v[100:103], v[148:151], v[172:175], v[100:103]
	v_mfma_f32_16x16x32_bf16 v[96:99], v[156:159], v[172:175], v[96:99]
	v_mfma_f32_16x16x32_bf16 v[84:87], v[148:151], v[180:183], v[84:87]
	v_mfma_f32_16x16x32_bf16 v[80:83], v[156:159], v[180:183], v[80:83]
	v_mfma_f32_16x16x32_bf16 v[68:71], v[148:151], v[204:207], v[68:71]
	v_mfma_f32_16x16x32_bf16 v[64:67], v[156:159], v[204:207], v[64:67]
	s_setprio 0
	s_barrier
	s_add_i32 s58, s78, s68
	v_lshl_add_u64 v[208:209], s[62:63], 0, v[186:187]
	s_mov_b32 m0, s58
	ds_read_b128 v[160:163], v225 offset:16384
	ds_read_b128 v[164:167], v225 offset:17408
	ds_read_b128 v[168:171], v225 offset:18432
	ds_read_b128 v[172:175], v225 offset:19456
	ds_read_b128 v[176:179], v225 offset:20480
	ds_read_b128 v[180:183], v225 offset:21504
	ds_read_b128 v[200:203], v225 offset:22528
	ds_read_b128 v[204:207], v225 offset:23552
	global_load_lds_dwordx4 v[208:209], off
	s_add_i32 m0, s58, 0x2000
	s_add_u32 s58, s62, 0xb0000
	v_lshl_add_u64 v[210:211], s[62:63], 0, v[190:191]
	s_addc_u32 s59, s63, 0
	s_add_i32 s83, s79, s68
	global_load_lds_dwordx4 v[210:211], off
	v_lshl_add_u64 v[212:213], s[58:59], 0, v[186:187]
	s_mov_b32 m0, s83
	v_lshl_add_u64 v[214:215], s[64:65], 0, v[188:189]
	global_load_lds_dwordx4 v[212:213], off
	v_lshl_add_u64 v[212:213], s[58:59], 0, v[190:191]
	s_add_i32 m0, s83, 0x2000
	s_nop 0
	global_load_lds_dwordx4 v[212:213], off
	v_lshl_add_u64 v[212:213], s[64:65], 0, v[184:185]
	s_mov_b32 m0, s69
	s_nop 0
	global_load_lds_dwordx4 v[212:213], off
	s_mov_b32 m0, s72
	s_nop 0
	global_load_lds_dwordx4 v[214:215], off
	s_cmp_lg_u32 s55, -2
	s_cbranch_scc1 .Lzacc3b
	v_mov_b32_e32 v0, 0
	v_mov_b32_e32 v1, 0
	v_mov_b32_e32 v2, 0
	v_mov_b32_e32 v3, 0
	v_mov_b32_e32 v4, 0
	v_mov_b32_e32 v5, 0
	v_mov_b32_e32 v6, 0
	v_mov_b32_e32 v7, 0
	v_mov_b32_e32 v8, 0
	v_mov_b32_e32 v9, 0
	v_mov_b32_e32 v10, 0
	v_mov_b32_e32 v11, 0
	v_mov_b32_e32 v12, 0
	v_mov_b32_e32 v13, 0
	v_mov_b32_e32 v14, 0
	v_mov_b32_e32 v15, 0
	v_mov_b32_e32 v16, 0
	v_mov_b32_e32 v17, 0
	v_mov_b32_e32 v18, 0
	v_mov_b32_e32 v19, 0
	v_mov_b32_e32 v20, 0
	v_mov_b32_e32 v21, 0
	v_mov_b32_e32 v22, 0
	v_mov_b32_e32 v23, 0
	v_mov_b32_e32 v24, 0
	v_mov_b32_e32 v25, 0
	v_mov_b32_e32 v26, 0
	v_mov_b32_e32 v27, 0
	v_mov_b32_e32 v28, 0
	v_mov_b32_e32 v29, 0
	v_mov_b32_e32 v30, 0
	v_mov_b32_e32 v31, 0
	v_mov_b32_e32 v32, 0
	v_mov_b32_e32 v33, 0
	v_mov_b32_e32 v34, 0
	v_mov_b32_e32 v35, 0
	v_mov_b32_e32 v36, 0
	v_mov_b32_e32 v37, 0
	v_mov_b32_e32 v38, 0
	v_mov_b32_e32 v39, 0
	v_mov_b32_e32 v40, 0
	v_mov_b32_e32 v41, 0
	v_mov_b32_e32 v42, 0
	v_mov_b32_e32 v43, 0
	v_mov_b32_e32 v44, 0
	v_mov_b32_e32 v45, 0
	v_mov_b32_e32 v46, 0
	v_mov_b32_e32 v47, 0
	v_mov_b32_e32 v48, 0
	v_mov_b32_e32 v49, 0
	v_mov_b32_e32 v50, 0
	v_mov_b32_e32 v51, 0
	v_mov_b32_e32 v52, 0
	v_mov_b32_e32 v53, 0
	v_mov_b32_e32 v54, 0
	v_mov_b32_e32 v55, 0
	v_mov_b32_e32 v56, 0
	v_mov_b32_e32 v57, 0
	v_mov_b32_e32 v58, 0
	v_mov_b32_e32 v59, 0
	v_mov_b32_e32 v60, 0
	v_mov_b32_e32 v61, 0
	v_mov_b32_e32 v62, 0
	v_mov_b32_e32 v63, 0
	s_cmp_eq_u32 s99, 0
	s_cbranch_scc1 .Lzacc3b
	s_sub_u32 s99, s99, 1
	s_waitcnt vmcnt(24)
	s_branch .Lzacc3b_done

.Lzacc3b_done:
	s_waitcnt lgkmcnt(0)
	s_barrier
	s_setprio 1
	s_waitcnt lgkmcnt(0)
	v_mfma_f32_16x16x32_bf16 v[60:63], v[112:115], v[160:163], v[60:63]
	v_mfma_f32_16x16x32_bf16 v[56:59], v[136:139], v[160:163], v[56:59]
	v_mfma_f32_16x16x32_bf16 v[44:47], v[112:115], v[168:171], v[44:47]
	v_mfma_f32_16x16x32_bf16 v[40:43], v[136:139], v[168:171], v[40:43]
	v_mfma_f32_16x16x32_bf16 v[28:31], v[112:115], v[176:179], v[28:31]
	v_mfma_f32_16x16x32_bf16 v[24:27], v[136:139], v[176:179], v[24:27]
	v_mfma_f32_16x16x32_bf16 v[12:15], v[112:115], v[200:203], v[12:15]
	v_mfma_f32_16x16x32_bf16 v[8:11], v[136:139], v[200:203], v[8:11]
	v_mfma_f32_16x16x32_bf16 v[60:63], v[124:127], v[164:167], v[60:63]
	v_mfma_f32_16x16x32_bf16 v[56:59], v[140:143], v[164:167], v[56:59]
	v_mfma_f32_16x16x32_bf16 v[44:47], v[124:127], v[172:175], v[44:47]
	v_mfma_f32_16x16x32_bf16 v[40:43], v[140:143], v[172:175], v[40:43]
	v_mfma_f32_16x16x32_bf16 v[28:31], v[124:127], v[180:183], v[28:31]
	v_mfma_f32_16x16x32_bf16 v[24:27], v[140:143], v[180:183], v[24:27]
	v_mfma_f32_16x16x32_bf16 v[12:15], v[124:127], v[204:207], v[12:15]
	v_mfma_f32_16x16x32_bf16 v[8:11], v[140:143], v[204:207], v[8:11]
	s_setprio 0
	s_setprio 1
	v_mfma_f32_16x16x32_bf16 v[52:55], v[144:147], v[160:163], v[52:55]
	v_mfma_f32_16x16x32_bf16 v[48:51], v[152:155], v[160:163], v[48:51]
	v_mfma_f32_16x16x32_bf16 v[36:39], v[144:147], v[168:171], v[36:39]
	v_mfma_f32_16x16x32_bf16 v[32:35], v[152:155], v[168:171], v[32:35]
	v_mfma_f32_16x16x32_bf16 v[20:23], v[144:147], v[176:179], v[20:23]
	v_mfma_f32_16x16x32_bf16 v[16:19], v[152:155], v[176:179], v[16:19]
	v_mfma_f32_16x16x32_bf16 v[4:7], v[144:147], v[200:203], v[4:7]
	v_mfma_f32_16x16x32_bf16 v[0:3], v[152:155], v[200:203], v[0:3]
	v_mfma_f32_16x16x32_bf16 v[52:55], v[148:151], v[164:167], v[52:55]
	v_mfma_f32_16x16x32_bf16 v[48:51], v[156:159], v[164:167], v[48:51]
	v_mfma_f32_16x16x32_bf16 v[36:39], v[148:151], v[172:175], v[36:39]
	v_mfma_f32_16x16x32_bf16 v[32:35], v[156:159], v[172:175], v[32:35]
	v_mfma_f32_16x16x32_bf16 v[20:23], v[148:151], v[180:183], v[20:23]
	v_mfma_f32_16x16x32_bf16 v[16:19], v[156:159], v[180:183], v[16:19]
	v_mfma_f32_16x16x32_bf16 v[4:7], v[148:151], v[204:207], v[4:7]
	v_mfma_f32_16x16x32_bf16 v[0:3], v[156:159], v[204:207], v[0:3]
	s_setprio 0
	s_barrier
	s_add_i32 s83, 0, 0x18000
	s_add_i32 s84, 0, 0x1c000
	v_add_u32_e32 v140, s83, v220
	v_add_u32_e32 v156, s84, v220
	ds_read_b128 v[112:115], v140
	ds_read_b128 v[124:127], v140 offset:1024
	ds_read_b128 v[136:139], v140 offset:2048
	ds_read_b128 v[140:143], v140 offset:3072
	ds_read_b128 v[144:147], v156
	ds_read_b128 v[148:151], v156 offset:1024
	ds_read_b128 v[152:155], v156 offset:2048
	ds_read_b128 v[156:159], v156 offset:3072
	s_add_u32 s58, s64, 0xb0000
	s_addc_u32 s59, s65, 0
	s_mov_b32 m0, s73
	v_lshl_add_u64 v[228:229], s[58:59], 0, v[184:185]
	ds_read_b128 v[160:163], v225 offset:32768
	ds_read_b128 v[164:167], v225 offset:33792
	ds_read_b128 v[168:171], v225 offset:34816
	ds_read_b128 v[172:175], v225 offset:35840
	ds_read_b128 v[176:179], v225 offset:36864
	ds_read_b128 v[180:183], v225 offset:37888
	ds_read_b128 v[200:203], v225 offset:38912
	ds_read_b128 v[204:207], v225 offset:39936
	global_load_lds_dwordx4 v[228:229], off
	v_lshl_add_u64 v[228:229], s[58:59], 0, v[188:189]
	s_mov_b32 m0, s74
	s_nop 0
	global_load_lds_dwordx4 v[228:229], off
	s_waitcnt vmcnt(8)
	s_waitcnt lgkmcnt(0)
	s_barrier
	s_setprio 1
	s_waitcnt lgkmcnt(0)
	v_mfma_f32_16x16x32_bf16 v[132:135], v[112:115], v[160:163], v[132:135]
	v_mfma_f32_16x16x32_bf16 v[128:131], v[136:139], v[160:163], v[128:131]
	v_mfma_f32_16x16x32_bf16 v[108:111], v[112:115], v[168:171], v[108:111]
	v_mfma_f32_16x16x32_bf16 v[104:107], v[136:139], v[168:171], v[104:107]
	v_mfma_f32_16x16x32_bf16 v[92:95], v[112:115], v[176:179], v[92:95]
	v_mfma_f32_16x16x32_bf16 v[88:91], v[136:139], v[176:179], v[88:91]
	v_mfma_f32_16x16x32_bf16 v[76:79], v[112:115], v[200:203], v[76:79]
	v_mfma_f32_16x16x32_bf16 v[72:75], v[136:139], v[200:203], v[72:75]
	v_mfma_f32_16x16x32_bf16 v[132:135], v[124:127], v[164:167], v[132:135]
	v_mfma_f32_16x16x32_bf16 v[128:131], v[140:143], v[164:167], v[128:131]
	v_mfma_f32_16x16x32_bf16 v[108:111], v[124:127], v[172:175], v[108:111]
	v_mfma_f32_16x16x32_bf16 v[104:107], v[140:143], v[172:175], v[104:107]
	v_mfma_f32_16x16x32_bf16 v[92:95], v[124:127], v[180:183], v[92:95]
	v_mfma_f32_16x16x32_bf16 v[88:91], v[140:143], v[180:183], v[88:91]
	v_mfma_f32_16x16x32_bf16 v[76:79], v[124:127], v[204:207], v[76:79]
	v_mfma_f32_16x16x32_bf16 v[72:75], v[140:143], v[204:207], v[72:75]
	s_setprio 0
	s_setprio 1
	v_mfma_f32_16x16x32_bf16 v[120:123], v[144:147], v[160:163], v[120:123]
	v_mfma_f32_16x16x32_bf16 v[116:119], v[152:155], v[160:163], v[116:119]
	v_mfma_f32_16x16x32_bf16 v[100:103], v[144:147], v[168:171], v[100:103]
	v_mfma_f32_16x16x32_bf16 v[96:99], v[152:155], v[168:171], v[96:99]
	v_mfma_f32_16x16x32_bf16 v[84:87], v[144:147], v[176:179], v[84:87]
	v_mfma_f32_16x16x32_bf16 v[80:83], v[152:155], v[176:179], v[80:83]
	v_mfma_f32_16x16x32_bf16 v[68:71], v[144:147], v[200:203], v[68:71]
	v_mfma_f32_16x16x32_bf16 v[64:67], v[152:155], v[200:203], v[64:67]
	v_mfma_f32_16x16x32_bf16 v[120:123], v[148:151], v[164:167], v[120:123]
	v_mfma_f32_16x16x32_bf16 v[116:119], v[156:159], v[164:167], v[116:119]
	v_mfma_f32_16x16x32_bf16 v[100:103], v[148:151], v[172:175], v[100:103]
	v_mfma_f32_16x16x32_bf16 v[96:99], v[156:159], v[172:175], v[96:99]
	v_mfma_f32_16x16x32_bf16 v[84:87], v[148:151], v[180:183], v[84:87]
	v_mfma_f32_16x16x32_bf16 v[80:83], v[156:159], v[180:183], v[80:83]
	v_mfma_f32_16x16x32_bf16 v[68:71], v[148:151], v[204:207], v[68:71]
	v_mfma_f32_16x16x32_bf16 v[64:67], v[156:159], v[204:207], v[64:67]
	s_setprio 0
	s_barrier
	s_add_i32 s58, s83, s68
	v_lshl_add_u64 v[208:209], v[208:209], 0, s[26:27]
	s_mov_b32 m0, s58
	ds_read_b128 v[160:163], v225 offset:49152
	ds_read_b128 v[164:167], v225 offset:50176
	ds_read_b128 v[168:171], v225 offset:51200
	ds_read_b128 v[172:175], v225 offset:52224
	ds_read_b128 v[176:179], v225 offset:53248
	ds_read_b128 v[180:183], v225 offset:54272
	ds_read_b128 v[200:203], v225 offset:55296
	ds_read_b128 v[204:207], v225 offset:56320
	global_load_lds_dwordx4 v[208:209], off
	s_add_i32 m0, s58, 0x2000
	s_add_u32 s58, s62, 0xb0080
	v_lshl_add_u64 v[208:209], v[210:211], 0, s[26:27]
	s_addc_u32 s59, s63, 0
	s_add_i32 s62, s84, s68
	global_load_lds_dwordx4 v[208:209], off
	v_lshl_add_u64 v[208:209], s[58:59], 0, v[186:187]
	s_mov_b32 m0, s62
	s_nop 0
	global_load_lds_dwordx4 v[208:209], off
	v_lshl_add_u64 v[208:209], s[58:59], 0, v[190:191]
	s_add_i32 m0, s62, 0x2000
	s_nop 0
	global_load_lds_dwordx4 v[208:209], off
	v_lshl_add_u64 v[208:209], v[212:213], 0, s[26:27]
	s_mov_b32 m0, s51
	s_nop 0
	global_load_lds_dwordx4 v[208:209], off
	v_lshl_add_u64 v[208:209], v[214:215], 0, s[26:27]
	s_mov_b32 m0, s76
	s_nop 0
	global_load_lds_dwordx4 v[208:209], off
	s_waitcnt vmcnt(8)
	s_waitcnt lgkmcnt(0)
	s_barrier
	s_setprio 1
	s_waitcnt lgkmcnt(0)
	v_mfma_f32_16x16x32_bf16 v[60:63], v[112:115], v[160:163], v[60:63]
	v_mfma_f32_16x16x32_bf16 v[56:59], v[136:139], v[160:163], v[56:59]
	v_mfma_f32_16x16x32_bf16 v[44:47], v[112:115], v[168:171], v[44:47]
	v_mfma_f32_16x16x32_bf16 v[40:43], v[136:139], v[168:171], v[40:43]
	v_mfma_f32_16x16x32_bf16 v[28:31], v[112:115], v[176:179], v[28:31]
	v_mfma_f32_16x16x32_bf16 v[24:27], v[136:139], v[176:179], v[24:27]
	v_mfma_f32_16x16x32_bf16 v[12:15], v[112:115], v[200:203], v[12:15]
	v_mfma_f32_16x16x32_bf16 v[8:11], v[136:139], v[200:203], v[8:11]
	v_mfma_f32_16x16x32_bf16 v[60:63], v[124:127], v[164:167], v[60:63]
	v_mfma_f32_16x16x32_bf16 v[56:59], v[140:143], v[164:167], v[56:59]
	v_mfma_f32_16x16x32_bf16 v[44:47], v[124:127], v[172:175], v[44:47]
	v_mfma_f32_16x16x32_bf16 v[40:43], v[140:143], v[172:175], v[40:43]
	v_mfma_f32_16x16x32_bf16 v[28:31], v[124:127], v[180:183], v[28:31]
	v_mfma_f32_16x16x32_bf16 v[24:27], v[140:143], v[180:183], v[24:27]
	v_mfma_f32_16x16x32_bf16 v[12:15], v[124:127], v[204:207], v[12:15]
	v_mfma_f32_16x16x32_bf16 v[8:11], v[140:143], v[204:207], v[8:11]
	s_setprio 0
	s_setprio 1
	v_mfma_f32_16x16x32_bf16 v[52:55], v[144:147], v[160:163], v[52:55]
	v_mfma_f32_16x16x32_bf16 v[48:51], v[152:155], v[160:163], v[48:51]
	v_mfma_f32_16x16x32_bf16 v[36:39], v[144:147], v[168:171], v[36:39]
	v_mfma_f32_16x16x32_bf16 v[32:35], v[152:155], v[168:171], v[32:35]
	v_mfma_f32_16x16x32_bf16 v[20:23], v[144:147], v[176:179], v[20:23]
	v_mfma_f32_16x16x32_bf16 v[16:19], v[152:155], v[176:179], v[16:19]
	v_mfma_f32_16x16x32_bf16 v[4:7], v[144:147], v[200:203], v[4:7]
	v_mfma_f32_16x16x32_bf16 v[0:3], v[152:155], v[200:203], v[0:3]
	v_mfma_f32_16x16x32_bf16 v[52:55], v[148:151], v[164:167], v[52:55]
	v_mfma_f32_16x16x32_bf16 v[48:51], v[156:159], v[164:167], v[48:51]
	v_mfma_f32_16x16x32_bf16 v[36:39], v[148:151], v[172:175], v[36:39]
	v_mfma_f32_16x16x32_bf16 v[32:35], v[156:159], v[172:175], v[32:35]
	v_mfma_f32_16x16x32_bf16 v[20:23], v[148:151], v[180:183], v[20:23]
	v_mfma_f32_16x16x32_bf16 v[16:19], v[156:159], v[180:183], v[16:19]
	v_mfma_f32_16x16x32_bf16 v[4:7], v[148:151], v[204:207], v[4:7]
	v_mfma_f32_16x16x32_bf16 v[0:3], v[156:159], v[204:207], v[0:3]
	s_setprio 0
	s_barrier
	s_add_i32 s55, s55, 2
	s_add_u32 s15, s15, 0x100
	s_addc_u32 s54, s54, 0
	s_cmp_gt_u32 s55, 41
	s_mov_b64 s[58:59], s[60:61]
	s_cbranch_scc0 .LBB0_541
	s_and_b64 vcc, exec, s[28:29]
	s_cbranch_vccz .LBB0_544
	s_barrier

.LBB0_622:
	s_add_u32 s12, s6, 0x100000
	s_addc_u32 s13, s7, 0
	s_and_b32 s15, s18, 3
	s_lshl_b32 s58, s14, 6
	s_lshl_b32 s17, s14, 13
	s_lshl_b32 s21, s15, 12
	s_mov_b64 s[14:15], 0x80
	s_add_i32 m0, s8, 0x18000
	v_lshl_add_u64 v[6:7], v[6:7], 0, s[14:15]
	s_lshl_b32 s19, s18, 5
	s_waitcnt vmcnt(2)
	s_barrier
	global_load_lds_dwordx4 v[6:7], off
	v_lshl_add_u64 v[4:5], v[4:5], 0, s[14:15]
	s_add_i32 m0, s8, 0x1a000
	s_add_i32 s59, s8, 0x8000
	s_add_i32 s60, s8, 0xa000
	global_load_lds_dwordx4 v[4:5], off
	v_lshl_add_u64 v[0:1], v[0:1], 0, s[14:15]
	s_mov_b32 m0, s59
	s_add_u32 s22, s36, 0x40080
	global_load_lds_dwordx4 v[0:1], off
	v_lshl_add_u64 v[0:1], v[2:3], 0, s[14:15]
	s_mov_b32 m0, s60
	s_addc_u32 s23, s37, 0
	global_load_lds_dwordx4 v[0:1], off
	s_add_i32 m0, s8, 0x1c000
	v_lshl_add_u64 v[0:1], s[22:23], 0, v[132:133]
	global_load_lds_dwordx4 v[0:1], off
	v_lshl_add_u64 v[0:1], s[22:23], 0, v[128:129]
	s_add_i32 m0, s8, 0x1e000
	v_and_b32_e32 v149, 15, v8
	global_load_lds_dwordx4 v[0:1], off
	v_lshrrev_b32_e32 v0, 1, v8
	v_and_b32_e32 v0, 24, v0
	v_lshlrev_b32_e32 v1, 1, v0
	v_lshlrev_b32_e32 v2, 2, v8
	v_and_or_b32 v0, s19, 32, v0
	v_lshl_or_b32 v1, v149, 6, v1
	v_and_b32_e32 v2, 32, v2
	v_lshlrev_b32_e32 v136, 1, v0
	v_bitop3_b32 v3, v1, s17, v2 bitop3:0xde
	v_bitop3_b32 v151, v1, s21, v2 bitop3:0xde
	v_lshl_add_u64 v[0:1], s[6:7], 0, v[136:137]
	s_mov_b64 s[6:7], 0x10000000
	v_lshl_add_u64 v[138:139], v[0:1], 0, s[6:7]
	v_lshlrev_b32_e32 v0, 14, v13
	v_and_b32_e32 v0, 0xffff8000, v0
	v_lshl_add_u32 v0, v12, 11, v0
	v_and_b32_e32 v1, 1, v13
	v_lshl_or_b32 v0, v1, 6, v0
	v_lshl_add_u32 v140, v14, 1, v0
	v_lshlrev_b32_e32 v0, 14, v9
	v_and_b32_e32 v0, 0xffff8000, v0
	s_waitcnt vmcnt(6)
	s_cmpk_lt_u32 s16, 0x100
	v_lshl_add_u32 v0, v10, 11, v0
	v_and_b32_e32 v1, 1, v9
	s_cselect_b64 s[16:17], -1, 0
	v_lshl_or_b32 v0, v1, 6, v0
	s_add_i32 s63, 0, 0x10000
	s_add_i32 s64, 0, 0x14000
	s_bfe_u32 s61, s18, 0x10001
	v_mov_b32_e32 v141, v137
	v_lshl_add_u32 v142, v11, 1, v0
	v_mov_b32_e32 v143, v137
	v_mov_b64_e32 v[144:145], 0xc00
	v_mov_b64_e32 v[146:147], 0xbff
	s_movk_i32 s62, 0x181
	v_add_u32_e32 v154, s63, v151
	v_add_u32_e32 v155, s64, v151
	v_add_u32_e32 v156, 0, v3
	v_mov_b32_e32 v157, 0x358637bd
	s_mov_b64 s[18:19], 0x1000
	s_mov_b64 s[22:23], 0x1800
	v_mov_b32_e32 v158, 0x3e38aa3b
	s_barrier
	s_mov_b32 s99, 0
	s_branch .LBB0_625

.LBB0_624:
	s_mov_b32 s99, 2
	s_andn2_b64 vcc, exec, s[6:7]
	s_mov_b32 s70, s24
	s_mov_b32 s20, s26
	s_mov_b64 s[36:37], s[30:31]
	s_mov_b64 s[34:35], s[28:29]
	s_cbranch_vccz .LBB0_634

.LBB0_628:
	ds_read_b128 v[160:163], v154
	ds_read_b128 v[164:167], v154 offset:1024
	ds_read_b128 v[168:171], v154 offset:2048
	ds_read_b128 v[172:175], v154 offset:3072
	ds_read_b128 v[176:179], v155
	ds_read_b128 v[180:183], v155 offset:1024
	ds_read_b128 v[184:187], v155 offset:2048
	ds_read_b128 v[188:191], v155 offset:3072
	s_add_u32 s36, s34, 0xfffc0080
	s_addc_u32 s37, s35, -1
	s_cmp_eq_u32 s68, 12
	s_cselect_b32 s39, s21, s37
	s_cselect_b32 s38, s27, s36
	s_cselect_b32 s37, s25, s67
	s_cselect_b32 s36, s65, s66
	v_lshl_add_u64 v[152:153], s[34:35], 0, v[140:141]
	s_add_i32 m0, s8, 0xc000
	ds_read_b128 v[192:195], v156
	ds_read_b128 v[196:199], v156 offset:1024
	ds_read_b128 v[200:203], v156 offset:2048
	ds_read_b128 v[204:207], v156 offset:3072
	ds_read_b128 v[208:211], v156 offset:4096
	ds_read_b128 v[212:215], v156 offset:5120
	ds_read_b128 v[218:221], v156 offset:6144
	ds_read_b128 v[222:225], v156 offset:7168
	global_load_lds_dwordx4 v[152:153], off
	v_lshl_add_u64 v[152:153], s[34:35], 0, v[142:143]
	s_add_i32 m0, s8, 0xe000
	s_nop 0
	global_load_lds_dwordx4 v[152:153], off
	s_cmp_lg_u32 s68, -2
	s_cbranch_scc1 .Lzacc4a
	v_mov_b32_e32 v64, 0
	v_mov_b32_e32 v65, 0
	v_mov_b32_e32 v66, 0
	v_mov_b32_e32 v67, 0
	v_mov_b32_e32 v68, 0
	v_mov_b32_e32 v69, 0
	v_mov_b32_e32 v70, 0
	v_mov_b32_e32 v71, 0
	v_mov_b32_e32 v72, 0
	v_mov_b32_e32 v73, 0
	v_mov_b32_e32 v74, 0
	v_mov_b32_e32 v75, 0
	v_mov_b32_e32 v76, 0
	v_mov_b32_e32 v77, 0
	v_mov_b32_e32 v78, 0
	v_mov_b32_e32 v79, 0
	v_mov_b32_e32 v80, 0
	v_mov_b32_e32 v81, 0
	v_mov_b32_e32 v82, 0
	v_mov_b32_e32 v83, 0
	v_mov_b32_e32 v84, 0
	v_mov_b32_e32 v85, 0
	v_mov_b32_e32 v86, 0
	v_mov_b32_e32 v87, 0
	v_mov_b32_e32 v88, 0
	v_mov_b32_e32 v89, 0
	v_mov_b32_e32 v90, 0
	v_mov_b32_e32 v91, 0
	v_mov_b32_e32 v92, 0
	v_mov_b32_e32 v93, 0
	v_mov_b32_e32 v94, 0
	v_mov_b32_e32 v95, 0
	v_mov_b32_e32 v96, 0
	v_mov_b32_e32 v97, 0
	v_mov_b32_e32 v98, 0
	v_mov_b32_e32 v99, 0
	v_mov_b32_e32 v100, 0
	v_mov_b32_e32 v101, 0
	v_mov_b32_e32 v102, 0
	v_mov_b32_e32 v103, 0
	v_mov_b32_e32 v104, 0
	v_mov_b32_e32 v105, 0
	v_mov_b32_e32 v106, 0
	v_mov_b32_e32 v107, 0
	v_mov_b32_e32 v108, 0
	v_mov_b32_e32 v109, 0
	v_mov_b32_e32 v110, 0
	v_mov_b32_e32 v111, 0
	v_mov_b32_e32 v112, 0
	v_mov_b32_e32 v113, 0
	v_mov_b32_e32 v114, 0
	v_mov_b32_e32 v115, 0
	v_mov_b32_e32 v116, 0
	v_mov_b32_e32 v117, 0
	v_mov_b32_e32 v118, 0
	v_mov_b32_e32 v119, 0
	v_mov_b32_e32 v120, 0
	v_mov_b32_e32 v121, 0
	v_mov_b32_e32 v122, 0
	v_mov_b32_e32 v123, 0
	v_mov_b32_e32 v124, 0
	v_mov_b32_e32 v125, 0
	v_mov_b32_e32 v126, 0
	v_mov_b32_e32 v127, 0
	s_cmp_eq_u32 s99, 0
	s_cbranch_scc1 .Lzacc4a
	s_sub_u32 s99, s99, 1
	s_waitcnt vmcnt(24)
	s_branch .Lzacc4a_done

.Lzacc4a_done:
	s_waitcnt lgkmcnt(0)
	s_barrier
	s_setprio 1
	s_waitcnt lgkmcnt(0)
	v_mfma_f32_16x16x32_bf16 v[124:127], v[160:163], v[192:195], v[124:127]
	v_mfma_f32_16x16x32_bf16 v[120:123], v[168:171], v[192:195], v[120:123]
	v_mfma_f32_16x16x32_bf16 v[116:119], v[160:163], v[200:203], v[116:119]
	v_mfma_f32_16x16x32_bf16 v[108:111], v[168:171], v[200:203], v[108:111]
	v_mfma_f32_16x16x32_bf16 v[100:103], v[160:163], v[208:211], v[100:103]
	v_mfma_f32_16x16x32_bf16 v[92:95], v[168:171], v[208:211], v[92:95]
	v_mfma_f32_16x16x32_bf16 v[84:87], v[160:163], v[218:221], v[84:87]
	v_mfma_f32_16x16x32_bf16 v[76:79], v[168:171], v[218:221], v[76:79]
	v_mfma_f32_16x16x32_bf16 v[124:127], v[164:167], v[196:199], v[124:127]
	v_mfma_f32_16x16x32_bf16 v[120:123], v[172:175], v[196:199], v[120:123]
	v_mfma_f32_16x16x32_bf16 v[116:119], v[164:167], v[204:207], v[116:119]
	v_mfma_f32_16x16x32_bf16 v[108:111], v[172:175], v[204:207], v[108:111]
	v_mfma_f32_16x16x32_bf16 v[100:103], v[164:167], v[212:215], v[100:103]
	v_mfma_f32_16x16x32_bf16 v[92:95], v[172:175], v[212:215], v[92:95]
	v_mfma_f32_16x16x32_bf16 v[84:87], v[164:167], v[222:225], v[84:87]
	v_mfma_f32_16x16x32_bf16 v[76:79], v[172:175], v[222:225], v[76:79]
	s_setprio 0
	s_setprio 1
	v_mfma_f32_16x16x32_bf16 v[112:115], v[176:179], v[192:195], v[112:115]
	v_mfma_f32_16x16x32_bf16 v[104:107], v[184:187], v[192:195], v[104:107]
	v_mfma_f32_16x16x32_bf16 v[96:99], v[176:179], v[200:203], v[96:99]
	v_mfma_f32_16x16x32_bf16 v[88:91], v[184:187], v[200:203], v[88:91]
	v_mfma_f32_16x16x32_bf16 v[80:83], v[176:179], v[208:211], v[80:83]
	v_mfma_f32_16x16x32_bf16 v[72:75], v[184:187], v[208:211], v[72:75]
	v_mfma_f32_16x16x32_bf16 v[68:71], v[176:179], v[218:221], v[68:71]
	v_mfma_f32_16x16x32_bf16 v[64:67], v[184:187], v[218:221], v[64:67]
	v_mfma_f32_16x16x32_bf16 v[112:115], v[180:183], v[196:199], v[112:115]
	v_mfma_f32_16x16x32_bf16 v[104:107], v[188:191], v[196:199], v[104:107]
	v_mfma_f32_16x16x32_bf16 v[96:99], v[180:183], v[204:207], v[96:99]
	v_mfma_f32_16x16x32_bf16 v[88:91], v[188:191], v[204:207], v[88:91]
	v_mfma_f32_16x16x32_bf16 v[80:83], v[180:183], v[212:215], v[80:83]
	v_mfma_f32_16x16x32_bf16 v[72:75], v[188:191], v[212:215], v[72:75]
	v_mfma_f32_16x16x32_bf16 v[68:71], v[180:183], v[222:225], v[68:71]
	v_mfma_f32_16x16x32_bf16 v[64:67], v[188:191], v[222:225], v[64:67]
	s_setprio 0
	s_barrier
	s_add_i32 s69, s63, s54
	v_lshl_add_u64 v[152:153], s[36:37], 0, v[132:133]
	s_mov_b32 m0, s69
	ds_read_b128 v[192:195], v156 offset:16384
	ds_read_b128 v[196:199], v156 offset:17408
	ds_read_b128 v[200:203], v156 offset:18432
	ds_read_b128 v[204:207], v156 offset:19456
	ds_read_b128 v[208:211], v156 offset:20480
	ds_read_b128 v[212:215], v156 offset:21504
	ds_read_b128 v[218:221], v156 offset:22528
	ds_read_b128 v[222:225], v156 offset:23552
	global_load_lds_dwordx4 v[152:153], off
	s_add_i32 m0, s69, 0x2000
	s_add_u32 s72, s36, 0x40000
	v_lshl_add_u64 v[226:227], s[36:37], 0, v[128:129]
	s_addc_u32 s73, s37, 0
	s_add_i32 s69, s64, s54
	global_load_lds_dwordx4 v[226:227], off
	v_lshl_add_u64 v[228:229], s[72:73], 0, v[132:133]
	s_mov_b32 m0, s69
	v_lshl_add_u64 v[230:231], s[38:39], 0, v[130:131]
	global_load_lds_dwordx4 v[228:229], off
	v_lshl_add_u64 v[228:229], s[72:73], 0, v[128:129]
	s_add_i32 m0, s69, 0x2000
	s_nop 0
	global_load_lds_dwordx4 v[228:229], off
	v_lshl_add_u64 v[228:229], s[38:39], 0, v[134:135]
	s_mov_b32 m0, s8
	s_nop 0
	global_load_lds_dwordx4 v[228:229], off
	s_mov_b32 m0, s55
	s_nop 0
	global_load_lds_dwordx4 v[230:231], off
	s_cmp_lg_u32 s68, -2
	s_cbranch_scc1 .Lzacc4b
	v_mov_b32_e32 v0, 0
	v_mov_b32_e32 v1, 0
	v_mov_b32_e32 v2, 0
	v_mov_b32_e32 v3, 0
	v_mov_b32_e32 v4, 0
	v_mov_b32_e32 v5, 0
	v_mov_b32_e32 v6, 0
	v_mov_b32_e32 v7, 0
	v_mov_b32_e32 v8, 0
	v_mov_b32_e32 v9, 0
	v_mov_b32_e32 v10, 0
	v_mov_b32_e32 v11, 0
	v_mov_b32_e32 v12, 0
	v_mov_b32_e32 v13, 0
	v_mov_b32_e32 v14, 0
	v_mov_b32_e32 v15, 0
	v_mov_b32_e32 v16, 0
	v_mov_b32_e32 v17, 0
	v_mov_b32_e32 v18, 0
	v_mov_b32_e32 v19, 0
	v_mov_b32_e32 v20, 0
	v_mov_b32_e32 v21, 0
	v_mov_b32_e32 v22, 0
	v_mov_b32_e32 v23, 0
	v_mov_b32_e32 v24, 0
	v_mov_b32_e32 v25, 0
	v_mov_b32_e32 v26, 0
	v_mov_b32_e32 v27, 0
	v_mov_b32_e32 v28, 0
	v_mov_b32_e32 v29, 0
	v_mov_b32_e32 v30, 0
	v_mov_b32_e32 v31, 0
	v_mov_b32_e32 v32, 0
	v_mov_b32_e32 v33, 0
	v_mov_b32_e32 v34, 0
	v_mov_b32_e32 v35, 0
	v_mov_b32_e32 v36, 0
	v_mov_b32_e32 v37, 0
	v_mov_b32_e32 v38, 0
	v_mov_b32_e32 v39, 0
	v_mov_b32_e32 v40, 0
	v_mov_b32_e32 v41, 0
	v_mov_b32_e32 v42, 0
	v_mov_b32_e32 v43, 0
	v_mov_b32_e32 v44, 0
	v_mov_b32_e32 v45, 0
	v_mov_b32_e32 v46, 0
	v_mov_b32_e32 v47, 0
	v_mov_b32_e32 v48, 0
	v_mov_b32_e32 v49, 0
	v_mov_b32_e32 v50, 0
	v_mov_b32_e32 v51, 0
	v_mov_b32_e32 v52, 0
	v_mov_b32_e32 v53, 0
	v_mov_b32_e32 v54, 0
	v_mov_b32_e32 v55, 0
	v_mov_b32_e32 v56, 0
	v_mov_b32_e32 v57, 0
	v_mov_b32_e32 v58, 0
	v_mov_b32_e32 v59, 0
	v_mov_b32_e32 v60, 0
	v_mov_b32_e32 v61, 0
	v_mov_b32_e32 v62, 0
	v_mov_b32_e32 v63, 0
	s_cmp_eq_u32 s99, 0
	s_cbranch_scc1 .Lzacc4b
	s_sub_u32 s99, s99, 1
	s_waitcnt vmcnt(24)
	s_branch .Lzacc4b_done

.Lzacc4b_done:
	s_waitcnt lgkmcnt(0)
	s_barrier
	s_setprio 1
	s_waitcnt lgkmcnt(0)
	v_mfma_f32_16x16x32_bf16 v[60:63], v[160:163], v[192:195], v[60:63]
	v_mfma_f32_16x16x32_bf16 v[56:59], v[168:171], v[192:195], v[56:59]
	v_mfma_f32_16x16x32_bf16 v[52:55], v[160:163], v[200:203], v[52:55]
	v_mfma_f32_16x16x32_bf16 v[44:47], v[168:171], v[200:203], v[44:47]
	v_mfma_f32_16x16x32_bf16 v[36:39], v[160:163], v[208:211], v[36:39]
	v_mfma_f32_16x16x32_bf16 v[28:31], v[168:171], v[208:211], v[28:31]
	v_mfma_f32_16x16x32_bf16 v[20:23], v[160:163], v[218:221], v[20:23]
	v_mfma_f32_16x16x32_bf16 v[12:15], v[168:171], v[218:221], v[12:15]
	v_mfma_f32_16x16x32_bf16 v[60:63], v[164:167], v[196:199], v[60:63]
	v_mfma_f32_16x16x32_bf16 v[56:59], v[172:175], v[196:199], v[56:59]
	v_mfma_f32_16x16x32_bf16 v[52:55], v[164:167], v[204:207], v[52:55]
	v_mfma_f32_16x16x32_bf16 v[44:47], v[172:175], v[204:207], v[44:47]
	v_mfma_f32_16x16x32_bf16 v[36:39], v[164:167], v[212:215], v[36:39]
	v_mfma_f32_16x16x32_bf16 v[28:31], v[172:175], v[212:215], v[28:31]
	v_mfma_f32_16x16x32_bf16 v[20:23], v[164:167], v[222:225], v[20:23]
	v_mfma_f32_16x16x32_bf16 v[12:15], v[172:175], v[222:225], v[12:15]
	s_setprio 0
	s_setprio 1
	v_mfma_f32_16x16x32_bf16 v[48:51], v[176:179], v[192:195], v[48:51]
	v_mfma_f32_16x16x32_bf16 v[40:43], v[184:187], v[192:195], v[40:43]
	v_mfma_f32_16x16x32_bf16 v[32:35], v[176:179], v[200:203], v[32:35]
	v_mfma_f32_16x16x32_bf16 v[24:27], v[184:187], v[200:203], v[24:27]
	v_mfma_f32_16x16x32_bf16 v[16:19], v[176:179], v[208:211], v[16:19]
	v_mfma_f32_16x16x32_bf16 v[8:11], v[184:187], v[208:211], v[8:11]
	v_mfma_f32_16x16x32_bf16 v[4:7], v[176:179], v[218:221], v[4:7]
	v_mfma_f32_16x16x32_bf16 v[0:3], v[184:187], v[218:221], v[0:3]
	v_mfma_f32_16x16x32_bf16 v[48:51], v[180:183], v[196:199], v[48:51]
	v_mfma_f32_16x16x32_bf16 v[40:43], v[188:191], v[196:199], v[40:43]
	v_mfma_f32_16x16x32_bf16 v[32:35], v[180:183], v[204:207], v[32:35]
	v_mfma_f32_16x16x32_bf16 v[24:27], v[188:191], v[204:207], v[24:27]
	v_mfma_f32_16x16x32_bf16 v[16:19], v[180:183], v[212:215], v[16:19]
	v_mfma_f32_16x16x32_bf16 v[8:11], v[188:191], v[212:215], v[8:11]
	v_mfma_f32_16x16x32_bf16 v[4:7], v[180:183], v[222:225], v[4:7]
	v_mfma_f32_16x16x32_bf16 v[0:3], v[188:191], v[222:225], v[0:3]
	s_setprio 0
	s_barrier
	s_add_i32 s69, 0, 0x18000
	v_add_u32_e32 v136, s69, v151
	s_add_i32 s71, 0, 0x1c000
	ds_read_b128 v[160:163], v136
	ds_read_b128 v[164:167], v136 offset:1024
	ds_read_b128 v[168:171], v136 offset:2048
	ds_read_b128 v[172:175], v136 offset:3072
	v_add_u32_e32 v136, s71, v151
	ds_read_b128 v[176:179], v136
	ds_read_b128 v[180:183], v136 offset:1024
	ds_read_b128 v[184:187], v136 offset:2048
	ds_read_b128 v[188:191], v136 offset:3072
	s_add_u32 s38, s38, 0x40000
	s_addc_u32 s39, s39, 0
	s_mov_b32 m0, s56
	v_lshl_add_u64 v[232:233], s[38:39], 0, v[134:135]
	ds_read_b128 v[192:195], v156 offset:32768
	ds_read_b128 v[196:199], v156 offset:33792
	ds_read_b128 v[200:203], v156 offset:34816
	ds_read_b128 v[204:207], v156 offset:35840
	ds_read_b128 v[208:211], v156 offset:36864
	ds_read_b128 v[212:215], v156 offset:37888
	ds_read_b128 v[218:221], v156 offset:38912
	ds_read_b128 v[222:225], v156 offset:39936
	global_load_lds_dwordx4 v[232:233], off
	v_lshl_add_u64 v[232:233], s[38:39], 0, v[130:131]
	s_mov_b32 m0, s57
	s_nop 0
	global_load_lds_dwordx4 v[232:233], off
	s_waitcnt vmcnt(8)
	s_waitcnt lgkmcnt(0)
	s_barrier
	s_setprio 1
	s_waitcnt lgkmcnt(0)
	v_mfma_f32_16x16x32_bf16 v[124:127], v[160:163], v[192:195], v[124:127]
	v_mfma_f32_16x16x32_bf16 v[120:123], v[168:171], v[192:195], v[120:123]
	v_mfma_f32_16x16x32_bf16 v[116:119], v[160:163], v[200:203], v[116:119]
	v_mfma_f32_16x16x32_bf16 v[108:111], v[168:171], v[200:203], v[108:111]
	v_mfma_f32_16x16x32_bf16 v[100:103], v[160:163], v[208:211], v[100:103]
	v_mfma_f32_16x16x32_bf16 v[92:95], v[168:171], v[208:211], v[92:95]
	v_mfma_f32_16x16x32_bf16 v[84:87], v[160:163], v[218:221], v[84:87]
	v_mfma_f32_16x16x32_bf16 v[76:79], v[168:171], v[218:221], v[76:79]
	v_mfma_f32_16x16x32_bf16 v[124:127], v[164:167], v[196:199], v[124:127]
	v_mfma_f32_16x16x32_bf16 v[120:123], v[172:175], v[196:199], v[120:123]
	v_mfma_f32_16x16x32_bf16 v[116:119], v[164:167], v[204:207], v[116:119]
	v_mfma_f32_16x16x32_bf16 v[108:111], v[172:175], v[204:207], v[108:111]
	v_mfma_f32_16x16x32_bf16 v[100:103], v[164:167], v[212:215], v[100:103]
	v_mfma_f32_16x16x32_bf16 v[92:95], v[172:175], v[212:215], v[92:95]
	v_mfma_f32_16x16x32_bf16 v[84:87], v[164:167], v[222:225], v[84:87]
	v_mfma_f32_16x16x32_bf16 v[76:79], v[172:175], v[222:225], v[76:79]
	s_setprio 0
	s_setprio 1
	v_mfma_f32_16x16x32_bf16 v[112:115], v[176:179], v[192:195], v[112:115]
	v_mfma_f32_16x16x32_bf16 v[104:107], v[184:187], v[192:195], v[104:107]
	v_mfma_f32_16x16x32_bf16 v[96:99], v[176:179], v[200:203], v[96:99]
	v_mfma_f32_16x16x32_bf16 v[88:91], v[184:187], v[200:203], v[88:91]
	v_mfma_f32_16x16x32_bf16 v[80:83], v[176:179], v[208:211], v[80:83]
	v_mfma_f32_16x16x32_bf16 v[72:75], v[184:187], v[208:211], v[72:75]
	v_mfma_f32_16x16x32_bf16 v[68:71], v[176:179], v[218:221], v[68:71]
	v_mfma_f32_16x16x32_bf16 v[64:67], v[184:187], v[218:221], v[64:67]
	v_mfma_f32_16x16x32_bf16 v[112:115], v[180:183], v[196:199], v[112:115]
	v_mfma_f32_16x16x32_bf16 v[104:107], v[188:191], v[196:199], v[104:107]
	v_mfma_f32_16x16x32_bf16 v[96:99], v[180:183], v[204:207], v[96:99]
	v_mfma_f32_16x16x32_bf16 v[88:91], v[188:191], v[204:207], v[88:91]
	v_mfma_f32_16x16x32_bf16 v[80:83], v[180:183], v[212:215], v[80:83]
	v_mfma_f32_16x16x32_bf16 v[72:75], v[188:191], v[212:215], v[72:75]
	v_mfma_f32_16x16x32_bf16 v[68:71], v[180:183], v[222:225], v[68:71]
	v_mfma_f32_16x16x32_bf16 v[64:67], v[188:191], v[222:225], v[64:67]
	s_setprio 0
	s_barrier
	s_add_i32 s38, s69, s54
	v_lshl_add_u64 v[152:153], v[152:153], 0, s[14:15]
	s_mov_b32 m0, s38
	ds_read_b128 v[192:195], v156 offset:49152
	ds_read_b128 v[196:199], v156 offset:50176
	ds_read_b128 v[200:203], v156 offset:51200
	ds_read_b128 v[204:207], v156 offset:52224
	ds_read_b128 v[208:211], v156 offset:53248
	ds_read_b128 v[212:215], v156 offset:54272
	ds_read_b128 v[218:221], v156 offset:55296
	ds_read_b128 v[222:225], v156 offset:56320
	global_load_lds_dwordx4 v[152:153], off
	s_add_i32 m0, s38, 0x2000
	s_add_u32 s36, s36, 0x40080
	v_lshl_add_u64 v[152:153], v[226:227], 0, s[14:15]
	s_addc_u32 s37, s37, 0
	s_add_i32 s38, s71, s54
	global_load_lds_dwordx4 v[152:153], off
	v_lshl_add_u64 v[152:153], s[36:37], 0, v[132:133]
	s_mov_b32 m0, s38
	s_nop 0
	global_load_lds_dwordx4 v[152:153], off
	v_lshl_add_u64 v[152:153], s[36:37], 0, v[128:129]
	s_add_i32 m0, s38, 0x2000
	s_nop 0
	global_load_lds_dwordx4 v[152:153], off
	v_lshl_add_u64 v[152:153], v[228:229], 0, s[14:15]
	s_mov_b32 m0, s59
	s_nop 0
	global_load_lds_dwordx4 v[152:153], off
	v_lshl_add_u64 v[152:153], v[230:231], 0, s[14:15]
	s_mov_b32 m0, s60
	s_nop 0
	global_load_lds_dwordx4 v[152:153], off
	s_waitcnt vmcnt(8)
	s_waitcnt lgkmcnt(0)
	s_barrier
	s_setprio 1
	s_waitcnt lgkmcnt(0)
	v_mfma_f32_16x16x32_bf16 v[60:63], v[160:163], v[192:195], v[60:63]
	v_mfma_f32_16x16x32_bf16 v[56:59], v[168:171], v[192:195], v[56:59]
	v_mfma_f32_16x16x32_bf16 v[52:55], v[160:163], v[200:203], v[52:55]
	v_mfma_f32_16x16x32_bf16 v[44:47], v[168:171], v[200:203], v[44:47]
	v_mfma_f32_16x16x32_bf16 v[36:39], v[160:163], v[208:211], v[36:39]
	v_mfma_f32_16x16x32_bf16 v[28:31], v[168:171], v[208:211], v[28:31]
	v_mfma_f32_16x16x32_bf16 v[20:23], v[160:163], v[218:221], v[20:23]
	v_mfma_f32_16x16x32_bf16 v[12:15], v[168:171], v[218:221], v[12:15]
	v_mfma_f32_16x16x32_bf16 v[60:63], v[164:167], v[196:199], v[60:63]
	v_mfma_f32_16x16x32_bf16 v[56:59], v[172:175], v[196:199], v[56:59]
	v_mfma_f32_16x16x32_bf16 v[52:55], v[164:167], v[204:207], v[52:55]
	v_mfma_f32_16x16x32_bf16 v[44:47], v[172:175], v[204:207], v[44:47]
	v_mfma_f32_16x16x32_bf16 v[36:39], v[164:167], v[212:215], v[36:39]
	v_mfma_f32_16x16x32_bf16 v[28:31], v[172:175], v[212:215], v[28:31]
	v_mfma_f32_16x16x32_bf16 v[20:23], v[164:167], v[222:225], v[20:23]
	v_mfma_f32_16x16x32_bf16 v[12:15], v[172:175], v[222:225], v[12:15]
	s_setprio 0
	s_setprio 1
	v_mfma_f32_16x16x32_bf16 v[48:51], v[176:179], v[192:195], v[48:51]
	v_mfma_f32_16x16x32_bf16 v[40:43], v[184:187], v[192:195], v[40:43]
	v_mfma_f32_16x16x32_bf16 v[32:35], v[176:179], v[200:203], v[32:35]
	v_mfma_f32_16x16x32_bf16 v[24:27], v[184:187], v[200:203], v[24:27]
	v_mfma_f32_16x16x32_bf16 v[16:19], v[176:179], v[208:211], v[16:19]
	v_mfma_f32_16x16x32_bf16 v[8:11], v[184:187], v[208:211], v[8:11]
	v_mfma_f32_16x16x32_bf16 v[4:7], v[176:179], v[218:221], v[4:7]
	v_mfma_f32_16x16x32_bf16 v[0:3], v[184:187], v[218:221], v[0:3]
	v_mfma_f32_16x16x32_bf16 v[48:51], v[180:183], v[196:199], v[48:51]
	v_mfma_f32_16x16x32_bf16 v[40:43], v[188:191], v[196:199], v[40:43]
	v_mfma_f32_16x16x32_bf16 v[32:35], v[180:183], v[204:207], v[32:35]
	v_mfma_f32_16x16x32_bf16 v[24:27], v[188:191], v[204:207], v[24:27]
	v_mfma_f32_16x16x32_bf16 v[16:19], v[180:183], v[212:215], v[16:19]
	v_mfma_f32_16x16x32_bf16 v[8:11], v[188:191], v[212:215], v[8:11]
	v_mfma_f32_16x16x32_bf16 v[4:7], v[180:183], v[222:225], v[4:7]
	v_mfma_f32_16x16x32_bf16 v[0:3], v[188:191], v[222:225], v[0:3]
	s_setprio 0
	s_barrier
	s_add_i32 s68, s68, 2
	s_add_u32 s34, s34, 0x100
	s_addc_u32 s35, s35, 0
	s_add_u32 s66, s66, 0x100
	s_addc_u32 s67, s67, 0
	s_cmp_gt_u32 s68, 13
	s_cbranch_scc0 .LBB0_628
	s_and_b64 vcc, exec, s[16:17]
	s_cbranch_vccz .LBB0_631
	s_barrier

.LBB0_894:
	s_add_u32 s18, s6, 0x200000
	s_addc_u32 s19, s7, 0
	s_add_u32 s20, s6, 0x8000000
	s_mov_b64 s[22:23], 0x80
	s_addc_u32 s21, s7, 0
	s_and_b32 s9, s9, 3
	s_add_i32 m0, s70, 0x18000
	v_lshl_add_u64 v[6:7], v[6:7], 0, s[22:23]
	s_lshl_b32 s74, s8, 6
	s_lshl_b32 s8, s8, 13
	s_lshl_b32 s10, s9, 12
	s_waitcnt vmcnt(2)
	s_barrier
	global_load_lds_dwordx4 v[6:7], off
	v_lshl_add_u64 v[2:3], v[2:3], 0, s[22:23]
	s_add_i32 m0, s70, 0x1a000
	s_add_i32 s51, s70, 0x8000
	s_add_i32 s75, s70, 0xa000
	global_load_lds_dwordx4 v[2:3], off
	v_lshl_add_u64 v[0:1], v[0:1], 0, s[22:23]
	s_mov_b32 m0, s51
	s_add_u32 s6, s62, 0x40080
	global_load_lds_dwordx4 v[0:1], off
	v_lshl_add_u64 v[0:1], v[4:5], 0, s[22:23]
	s_mov_b32 m0, s75
	s_addc_u32 s7, s63, 0
	global_load_lds_dwordx4 v[0:1], off
	s_add_i32 m0, s70, 0x1c000
	v_lshl_add_u64 v[0:1], s[6:7], 0, v[186:187]
	global_load_lds_dwordx4 v[0:1], off
	v_lshl_add_u64 v[0:1], s[6:7], 0, v[190:191]
	s_add_i32 m0, s70, 0x1e000
	s_cmpk_lt_u32 s5, 0x100
	global_load_lds_dwordx4 v[0:1], off
	v_lshrrev_b32_e32 v1, 1, v8
	v_and_b32_e32 v0, 63, v8
	v_and_b32_e32 v1, 24, v1
	v_lshl_or_b32 v221, s9, 5, v1
	s_cselect_b64 s[24:25], -1, 0
	v_cmp_gt_u32_e64 s[6:7], 16, v0
	s_lshl_b32 s76, s9, 10
	s_movk_i32 s9, 0xffc0
	v_mov_b32_e32 v0, s5
	v_bfi_b32 v222, s9, v0, v8
	v_lshlrev_b32_e32 v0, 14, v9
	v_and_b32_e32 v0, 0xffff8000, v0
	v_lshl_add_u32 v0, v10, 11, v0
	v_and_b32_e32 v1, 1, v9
	v_lshl_or_b32 v0, v1, 6, v0
	v_lshl_add_u32 v192, v11, 1, v0
	v_lshlrev_b32_e32 v0, 14, v12
	v_and_b32_e32 v218, 15, v8
	v_and_b32_e32 v2, 48, v8
	v_lshlrev_b32_e32 v3, 2, v8
	v_and_b32_e32 v0, 0xffff8000, v0
	v_lshl_or_b32 v2, v218, 6, v2
	v_and_b32_e32 v3, 32, v3
	s_waitcnt vmcnt(6)
	v_lshl_add_u32 v0, v13, 11, v0
	v_and_b32_e32 v1, 1, v12
	v_bitop3_b32 v4, v2, s8, v3 bitop3:0xde
	v_bitop3_b32 v220, v2, s10, v3 bitop3:0xde
	s_movk_i32 s8, 0x100
	v_lshl_or_b32 v0, v1, 6, v0
	s_add_i32 s77, 0, 0x10000
	s_add_i32 s78, 0, 0x14000
	v_or_b32_e32 v219, s74, v218
	v_cmp_gt_i32_e64 s[8:9], s8, v222
	v_mov_b32_e32 v193, v187
	v_lshl_add_u32 v194, v14, 1, v0
	v_mov_b32_e32 v195, v187
	v_mov_b64_e32 v[196:197], 0x400
	v_mov_b64_e32 v[198:199], 0x3ff
	v_add_u32_e32 v223, s77, v220
	v_add_u32_e32 v224, s78, v220
	v_add_u32_e32 v225, 0, v4
	s_mov_b64 s[26:27], 0x48000
	s_mov_b64 s[28:29], 0x50000
	s_mov_b64 s[30:31], 0x58000
	v_mbcnt_hi_u32_b32 v226, -1, v248
	s_barrier
	s_mov_b32 s99, 0
	s_branch .LBB0_897

.LBB0_896:
	s_mov_b32 s99, 2
	s_andn2_b64 vcc, exec, s[10:11]
	s_mov_b32 s12, s34
	s_mov_b32 s58, s36
	s_mov_b64 s[62:63], s[56:57]
	s_mov_b64 s[60:61], s[38:39]
	s_mov_b32 s4, s79
	s_cbranch_vccz .LBB0_928

.LBB0_904:
	ds_read_b128 v[112:115], v223
	ds_read_b128 v[124:127], v223 offset:1024
	ds_read_b128 v[136:139], v223 offset:2048
	ds_read_b128 v[140:143], v223 offset:3072
	ds_read_b128 v[144:147], v224
	ds_read_b128 v[148:151], v224 offset:1024
	ds_read_b128 v[152:155], v224 offset:2048
	ds_read_b128 v[156:159], v224 offset:3072
	s_add_u32 s46, s60, 0xfffc0080
	s_addc_u32 s47, s61, -1
	s_cmp_eq_u32 s59, 12
	s_cselect_b32 s65, s5, s47
	s_cselect_b32 s64, s13, s46
	s_cselect_b32 s63, s35, s55
	s_cselect_b32 s62, s37, s54
	v_lshl_add_u64 v[208:209], s[60:61], 0, v[192:193]
	s_add_i32 m0, s70, 0xc000
	ds_read_b128 v[160:163], v225
	ds_read_b128 v[164:167], v225 offset:1024
	ds_read_b128 v[168:171], v225 offset:2048
	ds_read_b128 v[172:175], v225 offset:3072
	ds_read_b128 v[176:179], v225 offset:4096
	ds_read_b128 v[180:183], v225 offset:5120
	ds_read_b128 v[200:203], v225 offset:6144
	ds_read_b128 v[204:207], v225 offset:7168
	global_load_lds_dwordx4 v[208:209], off
	v_lshl_add_u64 v[208:209], s[60:61], 0, v[194:195]
	s_add_i32 m0, s70, 0xe000
	s_nop 0
	global_load_lds_dwordx4 v[208:209], off
	s_cmp_lg_u32 s59, -2
	s_cbranch_scc1 .Lzacc5a
	v_mov_b32_e32 v64, 0
	v_mov_b32_e32 v65, 0
	v_mov_b32_e32 v66, 0
	v_mov_b32_e32 v67, 0
	v_mov_b32_e32 v68, 0
	v_mov_b32_e32 v69, 0
	v_mov_b32_e32 v70, 0
	v_mov_b32_e32 v71, 0
	v_mov_b32_e32 v72, 0
	v_mov_b32_e32 v73, 0
	v_mov_b32_e32 v74, 0
	v_mov_b32_e32 v75, 0
	v_mov_b32_e32 v76, 0
	v_mov_b32_e32 v77, 0
	v_mov_b32_e32 v78, 0
	v_mov_b32_e32 v79, 0
	v_mov_b32_e32 v80, 0
	v_mov_b32_e32 v81, 0
	v_mov_b32_e32 v82, 0
	v_mov_b32_e32 v83, 0
	v_mov_b32_e32 v84, 0
	v_mov_b32_e32 v85, 0
	v_mov_b32_e32 v86, 0
	v_mov_b32_e32 v87, 0
	v_mov_b32_e32 v88, 0
	v_mov_b32_e32 v89, 0
	v_mov_b32_e32 v90, 0
	v_mov_b32_e32 v91, 0
	v_mov_b32_e32 v92, 0
	v_mov_b32_e32 v93, 0
	v_mov_b32_e32 v94, 0
	v_mov_b32_e32 v95, 0
	v_mov_b32_e32 v96, 0
	v_mov_b32_e32 v97, 0
	v_mov_b32_e32 v98, 0
	v_mov_b32_e32 v99, 0
	v_mov_b32_e32 v100, 0
	v_mov_b32_e32 v101, 0
	v_mov_b32_e32 v102, 0
	v_mov_b32_e32 v103, 0
	v_mov_b32_e32 v104, 0
	v_mov_b32_e32 v105, 0
	v_mov_b32_e32 v106, 0
	v_mov_b32_e32 v107, 0
	v_mov_b32_e32 v108, 0
	v_mov_b32_e32 v109, 0
	v_mov_b32_e32 v110, 0
	v_mov_b32_e32 v111, 0
	v_mov_b32_e32 v116, 0
	v_mov_b32_e32 v117, 0
	v_mov_b32_e32 v118, 0
	v_mov_b32_e32 v119, 0
	v_mov_b32_e32 v120, 0
	v_mov_b32_e32 v121, 0
	v_mov_b32_e32 v122, 0
	v_mov_b32_e32 v123, 0
	v_mov_b32_e32 v128, 0
	v_mov_b32_e32 v129, 0
	v_mov_b32_e32 v130, 0
	v_mov_b32_e32 v131, 0
	v_mov_b32_e32 v132, 0
	v_mov_b32_e32 v133, 0
	v_mov_b32_e32 v134, 0
	v_mov_b32_e32 v135, 0
	s_cmp_eq_u32 s99, 0
	s_cbranch_scc1 .Lzacc5a
	s_sub_u32 s99, s99, 1
	s_waitcnt vmcnt(24)
	s_branch .Lzacc5a_done

.Lzacc5a_done:
	s_waitcnt lgkmcnt(0)
	s_barrier
	s_setprio 1
	s_waitcnt lgkmcnt(0)
	v_mfma_f32_16x16x32_bf16 v[132:135], v[112:115], v[160:163], v[132:135]
	v_mfma_f32_16x16x32_bf16 v[128:131], v[136:139], v[160:163], v[128:131]
	v_mfma_f32_16x16x32_bf16 v[108:111], v[112:115], v[168:171], v[108:111]
	v_mfma_f32_16x16x32_bf16 v[104:107], v[136:139], v[168:171], v[104:107]
	v_mfma_f32_16x16x32_bf16 v[92:95], v[112:115], v[176:179], v[92:95]
	v_mfma_f32_16x16x32_bf16 v[88:91], v[136:139], v[176:179], v[88:91]
	v_mfma_f32_16x16x32_bf16 v[76:79], v[112:115], v[200:203], v[76:79]
	v_mfma_f32_16x16x32_bf16 v[72:75], v[136:139], v[200:203], v[72:75]
	v_mfma_f32_16x16x32_bf16 v[132:135], v[124:127], v[164:167], v[132:135]
	v_mfma_f32_16x16x32_bf16 v[128:131], v[140:143], v[164:167], v[128:131]
	v_mfma_f32_16x16x32_bf16 v[108:111], v[124:127], v[172:175], v[108:111]
	v_mfma_f32_16x16x32_bf16 v[104:107], v[140:143], v[172:175], v[104:107]
	v_mfma_f32_16x16x32_bf16 v[92:95], v[124:127], v[180:183], v[92:95]
	v_mfma_f32_16x16x32_bf16 v[88:91], v[140:143], v[180:183], v[88:91]
	v_mfma_f32_16x16x32_bf16 v[76:79], v[124:127], v[204:207], v[76:79]
	v_mfma_f32_16x16x32_bf16 v[72:75], v[140:143], v[204:207], v[72:75]
	s_setprio 0
	s_setprio 1
	v_mfma_f32_16x16x32_bf16 v[120:123], v[144:147], v[160:163], v[120:123]
	v_mfma_f32_16x16x32_bf16 v[116:119], v[152:155], v[160:163], v[116:119]
	v_mfma_f32_16x16x32_bf16 v[100:103], v[144:147], v[168:171], v[100:103]
	v_mfma_f32_16x16x32_bf16 v[96:99], v[152:155], v[168:171], v[96:99]
	v_mfma_f32_16x16x32_bf16 v[84:87], v[144:147], v[176:179], v[84:87]
	v_mfma_f32_16x16x32_bf16 v[80:83], v[152:155], v[176:179], v[80:83]
	v_mfma_f32_16x16x32_bf16 v[68:71], v[144:147], v[200:203], v[68:71]
	v_mfma_f32_16x16x32_bf16 v[64:67], v[152:155], v[200:203], v[64:67]
	v_mfma_f32_16x16x32_bf16 v[120:123], v[148:151], v[164:167], v[120:123]
	v_mfma_f32_16x16x32_bf16 v[116:119], v[156:159], v[164:167], v[116:119]
	v_mfma_f32_16x16x32_bf16 v[100:103], v[148:151], v[172:175], v[100:103]
	v_mfma_f32_16x16x32_bf16 v[96:99], v[156:159], v[172:175], v[96:99]
	v_mfma_f32_16x16x32_bf16 v[84:87], v[148:151], v[180:183], v[84:87]
	v_mfma_f32_16x16x32_bf16 v[80:83], v[156:159], v[180:183], v[80:83]
	v_mfma_f32_16x16x32_bf16 v[68:71], v[148:151], v[204:207], v[68:71]
	v_mfma_f32_16x16x32_bf16 v[64:67], v[156:159], v[204:207], v[64:67]
	s_setprio 0
	s_barrier
	s_add_i32 s46, s77, s69
	v_lshl_add_u64 v[208:209], s[62:63], 0, v[186:187]
	s_mov_b32 m0, s46
	ds_read_b128 v[160:163], v225 offset:16384
	ds_read_b128 v[164:167], v225 offset:17408
	ds_read_b128 v[168:171], v225 offset:18432
	ds_read_b128 v[172:175], v225 offset:19456
	ds_read_b128 v[176:179], v225 offset:20480
	ds_read_b128 v[180:183], v225 offset:21504
	ds_read_b128 v[200:203], v225 offset:22528
	ds_read_b128 v[204:207], v225 offset:23552
	global_load_lds_dwordx4 v[208:209], off
	s_add_i32 m0, s46, 0x2000
	s_add_u32 s80, s62, 0x40000
	v_lshl_add_u64 v[210:211], s[62:63], 0, v[190:191]
	s_addc_u32 s81, s63, 0
	s_add_i32 s46, s78, s69
	global_load_lds_dwordx4 v[210:211], off
	v_lshl_add_u64 v[212:213], s[80:81], 0, v[186:187]
	s_mov_b32 m0, s46
	v_lshl_add_u64 v[214:215], s[64:65], 0, v[188:189]
	global_load_lds_dwordx4 v[212:213], off
	v_lshl_add_u64 v[212:213], s[80:81], 0, v[190:191]
	s_add_i32 m0, s46, 0x2000
	s_nop 0
	global_load_lds_dwordx4 v[212:213], off
	v_lshl_add_u64 v[212:213], s[64:65], 0, v[184:185]
	s_mov_b32 m0, s70
	s_nop 0
	global_load_lds_dwordx4 v[212:213], off
	s_mov_b32 m0, s71
	s_nop 0
	global_load_lds_dwordx4 v[214:215], off
	s_cmp_lg_u32 s59, -2
	s_cbranch_scc1 .Lzacc5b
	v_mov_b32_e32 v0, 0
	v_mov_b32_e32 v1, 0
	v_mov_b32_e32 v2, 0
	v_mov_b32_e32 v3, 0
	v_mov_b32_e32 v4, 0
	v_mov_b32_e32 v5, 0
	v_mov_b32_e32 v6, 0
	v_mov_b32_e32 v7, 0
	v_mov_b32_e32 v8, 0
	v_mov_b32_e32 v9, 0
	v_mov_b32_e32 v10, 0
	v_mov_b32_e32 v11, 0
	v_mov_b32_e32 v12, 0
	v_mov_b32_e32 v13, 0
	v_mov_b32_e32 v14, 0
	v_mov_b32_e32 v15, 0
	v_mov_b32_e32 v16, 0
	v_mov_b32_e32 v17, 0
	v_mov_b32_e32 v18, 0
	v_mov_b32_e32 v19, 0
	v_mov_b32_e32 v20, 0
	v_mov_b32_e32 v21, 0
	v_mov_b32_e32 v22, 0
	v_mov_b32_e32 v23, 0
	v_mov_b32_e32 v24, 0
	v_mov_b32_e32 v25, 0
	v_mov_b32_e32 v26, 0
	v_mov_b32_e32 v27, 0
	v_mov_b32_e32 v28, 0
	v_mov_b32_e32 v29, 0
	v_mov_b32_e32 v30, 0
	v_mov_b32_e32 v31, 0
	v_mov_b32_e32 v32, 0
	v_mov_b32_e32 v33, 0
	v_mov_b32_e32 v34, 0
	v_mov_b32_e32 v35, 0
	v_mov_b32_e32 v36, 0
	v_mov_b32_e32 v37, 0
	v_mov_b32_e32 v38, 0
	v_mov_b32_e32 v39, 0
	v_mov_b32_e32 v40, 0
	v_mov_b32_e32 v41, 0
	v_mov_b32_e32 v42, 0
	v_mov_b32_e32 v43, 0
	v_mov_b32_e32 v44, 0
	v_mov_b32_e32 v45, 0
	v_mov_b32_e32 v46, 0
	v_mov_b32_e32 v47, 0
	v_mov_b32_e32 v48, 0
	v_mov_b32_e32 v49, 0
	v_mov_b32_e32 v50, 0
	v_mov_b32_e32 v51, 0
	v_mov_b32_e32 v52, 0
	v_mov_b32_e32 v53, 0
	v_mov_b32_e32 v54, 0
	v_mov_b32_e32 v55, 0
	v_mov_b32_e32 v56, 0
	v_mov_b32_e32 v57, 0
	v_mov_b32_e32 v58, 0
	v_mov_b32_e32 v59, 0
	v_mov_b32_e32 v60, 0
	v_mov_b32_e32 v61, 0
	v_mov_b32_e32 v62, 0
	v_mov_b32_e32 v63, 0
	s_cmp_eq_u32 s99, 0
	s_cbranch_scc1 .Lzacc5b
	s_sub_u32 s99, s99, 1
	s_waitcnt vmcnt(24)
	s_branch .Lzacc5b_done

.Lzacc5b_done:
	s_waitcnt lgkmcnt(0)
	s_barrier
	s_setprio 1
	s_waitcnt lgkmcnt(0)
	v_mfma_f32_16x16x32_bf16 v[60:63], v[112:115], v[160:163], v[60:63]
	v_mfma_f32_16x16x32_bf16 v[56:59], v[136:139], v[160:163], v[56:59]
	v_mfma_f32_16x16x32_bf16 v[44:47], v[112:115], v[168:171], v[44:47]
	v_mfma_f32_16x16x32_bf16 v[40:43], v[136:139], v[168:171], v[40:43]
	v_mfma_f32_16x16x32_bf16 v[28:31], v[112:115], v[176:179], v[28:31]
	v_mfma_f32_16x16x32_bf16 v[24:27], v[136:139], v[176:179], v[24:27]
	v_mfma_f32_16x16x32_bf16 v[12:15], v[112:115], v[200:203], v[12:15]
	v_mfma_f32_16x16x32_bf16 v[8:11], v[136:139], v[200:203], v[8:11]
	v_mfma_f32_16x16x32_bf16 v[60:63], v[124:127], v[164:167], v[60:63]
	v_mfma_f32_16x16x32_bf16 v[56:59], v[140:143], v[164:167], v[56:59]
	v_mfma_f32_16x16x32_bf16 v[44:47], v[124:127], v[172:175], v[44:47]
	v_mfma_f32_16x16x32_bf16 v[40:43], v[140:143], v[172:175], v[40:43]
	v_mfma_f32_16x16x32_bf16 v[28:31], v[124:127], v[180:183], v[28:31]
	v_mfma_f32_16x16x32_bf16 v[24:27], v[140:143], v[180:183], v[24:27]
	v_mfma_f32_16x16x32_bf16 v[12:15], v[124:127], v[204:207], v[12:15]
	v_mfma_f32_16x16x32_bf16 v[8:11], v[140:143], v[204:207], v[8:11]
	s_setprio 0
	s_setprio 1
	v_mfma_f32_16x16x32_bf16 v[52:55], v[144:147], v[160:163], v[52:55]
	v_mfma_f32_16x16x32_bf16 v[48:51], v[152:155], v[160:163], v[48:51]
	v_mfma_f32_16x16x32_bf16 v[36:39], v[144:147], v[168:171], v[36:39]
	v_mfma_f32_16x16x32_bf16 v[32:35], v[152:155], v[168:171], v[32:35]
	v_mfma_f32_16x16x32_bf16 v[20:23], v[144:147], v[176:179], v[20:23]
	v_mfma_f32_16x16x32_bf16 v[16:19], v[152:155], v[176:179], v[16:19]
	v_mfma_f32_16x16x32_bf16 v[4:7], v[144:147], v[200:203], v[4:7]
	v_mfma_f32_16x16x32_bf16 v[0:3], v[152:155], v[200:203], v[0:3]
	v_mfma_f32_16x16x32_bf16 v[52:55], v[148:151], v[164:167], v[52:55]
	v_mfma_f32_16x16x32_bf16 v[48:51], v[156:159], v[164:167], v[48:51]
	v_mfma_f32_16x16x32_bf16 v[36:39], v[148:151], v[172:175], v[36:39]
	v_mfma_f32_16x16x32_bf16 v[32:35], v[156:159], v[172:175], v[32:35]
	v_mfma_f32_16x16x32_bf16 v[20:23], v[148:151], v[180:183], v[20:23]
	v_mfma_f32_16x16x32_bf16 v[16:19], v[156:159], v[180:183], v[16:19]
	v_mfma_f32_16x16x32_bf16 v[4:7], v[148:151], v[204:207], v[4:7]
	v_mfma_f32_16x16x32_bf16 v[0:3], v[156:159], v[204:207], v[0:3]
	s_setprio 0
	s_barrier
	s_add_i32 s46, 0, 0x18000
	s_add_i32 s47, 0, 0x1c000
	v_add_u32_e32 v140, s46, v220
	v_add_u32_e32 v156, s47, v220
	ds_read_b128 v[112:115], v140
	ds_read_b128 v[124:127], v140 offset:1024
	ds_read_b128 v[136:139], v140 offset:2048
	ds_read_b128 v[140:143], v140 offset:3072
	ds_read_b128 v[144:147], v156
	ds_read_b128 v[148:151], v156 offset:1024
	ds_read_b128 v[152:155], v156 offset:2048
	ds_read_b128 v[156:159], v156 offset:3072
	s_add_u32 s64, s64, 0x40000
	s_addc_u32 s65, s65, 0
	s_mov_b32 m0, s72
	v_lshl_add_u64 v[228:229], s[64:65], 0, v[184:185]
	ds_read_b128 v[160:163], v225 offset:32768
	ds_read_b128 v[164:167], v225 offset:33792
	ds_read_b128 v[168:171], v225 offset:34816
	ds_read_b128 v[172:175], v225 offset:35840
	ds_read_b128 v[176:179], v225 offset:36864
	ds_read_b128 v[180:183], v225 offset:37888
	ds_read_b128 v[200:203], v225 offset:38912
	ds_read_b128 v[204:207], v225 offset:39936
	global_load_lds_dwordx4 v[228:229], off
	v_lshl_add_u64 v[228:229], s[64:65], 0, v[188:189]
	s_mov_b32 m0, s73
	s_nop 0
	global_load_lds_dwordx4 v[228:229], off
	s_waitcnt vmcnt(8)
	s_waitcnt lgkmcnt(0)
	s_barrier
	s_setprio 1
	s_waitcnt lgkmcnt(0)
	v_mfma_f32_16x16x32_bf16 v[132:135], v[112:115], v[160:163], v[132:135]
	v_mfma_f32_16x16x32_bf16 v[128:131], v[136:139], v[160:163], v[128:131]
	v_mfma_f32_16x16x32_bf16 v[108:111], v[112:115], v[168:171], v[108:111]
	v_mfma_f32_16x16x32_bf16 v[104:107], v[136:139], v[168:171], v[104:107]
	v_mfma_f32_16x16x32_bf16 v[92:95], v[112:115], v[176:179], v[92:95]
	v_mfma_f32_16x16x32_bf16 v[88:91], v[136:139], v[176:179], v[88:91]
	v_mfma_f32_16x16x32_bf16 v[76:79], v[112:115], v[200:203], v[76:79]
	v_mfma_f32_16x16x32_bf16 v[72:75], v[136:139], v[200:203], v[72:75]
	v_mfma_f32_16x16x32_bf16 v[132:135], v[124:127], v[164:167], v[132:135]
	v_mfma_f32_16x16x32_bf16 v[128:131], v[140:143], v[164:167], v[128:131]
	v_mfma_f32_16x16x32_bf16 v[108:111], v[124:127], v[172:175], v[108:111]
	v_mfma_f32_16x16x32_bf16 v[104:107], v[140:143], v[172:175], v[104:107]
	v_mfma_f32_16x16x32_bf16 v[92:95], v[124:127], v[180:183], v[92:95]
	v_mfma_f32_16x16x32_bf16 v[88:91], v[140:143], v[180:183], v[88:91]
	v_mfma_f32_16x16x32_bf16 v[76:79], v[124:127], v[204:207], v[76:79]
	v_mfma_f32_16x16x32_bf16 v[72:75], v[140:143], v[204:207], v[72:75]
	s_setprio 0
	s_setprio 1
	v_mfma_f32_16x16x32_bf16 v[120:123], v[144:147], v[160:163], v[120:123]
	v_mfma_f32_16x16x32_bf16 v[116:119], v[152:155], v[160:163], v[116:119]
	v_mfma_f32_16x16x32_bf16 v[100:103], v[144:147], v[168:171], v[100:103]
	v_mfma_f32_16x16x32_bf16 v[96:99], v[152:155], v[168:171], v[96:99]
	v_mfma_f32_16x16x32_bf16 v[84:87], v[144:147], v[176:179], v[84:87]
	v_mfma_f32_16x16x32_bf16 v[80:83], v[152:155], v[176:179], v[80:83]
	v_mfma_f32_16x16x32_bf16 v[68:71], v[144:147], v[200:203], v[68:71]
	v_mfma_f32_16x16x32_bf16 v[64:67], v[152:155], v[200:203], v[64:67]
	v_mfma_f32_16x16x32_bf16 v[120:123], v[148:151], v[164:167], v[120:123]
	v_mfma_f32_16x16x32_bf16 v[116:119], v[156:159], v[164:167], v[116:119]
	v_mfma_f32_16x16x32_bf16 v[100:103], v[148:151], v[172:175], v[100:103]
	v_mfma_f32_16x16x32_bf16 v[96:99], v[156:159], v[172:175], v[96:99]
	v_mfma_f32_16x16x32_bf16 v[84:87], v[148:151], v[180:183], v[84:87]
	v_mfma_f32_16x16x32_bf16 v[80:83], v[156:159], v[180:183], v[80:83]
	v_mfma_f32_16x16x32_bf16 v[68:71], v[148:151], v[204:207], v[68:71]
	v_mfma_f32_16x16x32_bf16 v[64:67], v[156:159], v[204:207], v[64:67]
	s_setprio 0
	s_barrier
	s_add_i32 s46, s46, s69
	v_lshl_add_u64 v[208:209], v[208:209], 0, s[22:23]
	s_mov_b32 m0, s46
	ds_read_b128 v[160:163], v225 offset:49152
	ds_read_b128 v[164:167], v225 offset:50176
	ds_read_b128 v[168:171], v225 offset:51200
	ds_read_b128 v[172:175], v225 offset:52224
	ds_read_b128 v[176:179], v225 offset:53248
	ds_read_b128 v[180:183], v225 offset:54272
	ds_read_b128 v[200:203], v225 offset:55296
	ds_read_b128 v[204:207], v225 offset:56320
	global_load_lds_dwordx4 v[208:209], off
	s_add_i32 m0, s46, 0x2000
	s_add_u32 s62, s62, 0x40080
	v_lshl_add_u64 v[208:209], v[210:211], 0, s[22:23]
	s_addc_u32 s63, s63, 0
	s_add_i32 s46, s47, s69
	global_load_lds_dwordx4 v[208:209], off
	v_lshl_add_u64 v[208:209], s[62:63], 0, v[186:187]
	s_mov_b32 m0, s46
	s_nop 0
	global_load_lds_dwordx4 v[208:209], off
	v_lshl_add_u64 v[208:209], s[62:63], 0, v[190:191]
	s_add_i32 m0, s46, 0x2000
	s_nop 0
	global_load_lds_dwordx4 v[208:209], off
	v_lshl_add_u64 v[208:209], v[212:213], 0, s[22:23]
	s_mov_b32 m0, s51
	s_nop 0
	global_load_lds_dwordx4 v[208:209], off
	v_lshl_add_u64 v[208:209], v[214:215], 0, s[22:23]
	s_mov_b32 m0, s75
	s_nop 0
	global_load_lds_dwordx4 v[208:209], off
	s_waitcnt vmcnt(8)
	s_waitcnt lgkmcnt(0)
	s_barrier
	s_setprio 1
	s_waitcnt lgkmcnt(0)
	v_mfma_f32_16x16x32_bf16 v[60:63], v[112:115], v[160:163], v[60:63]
	v_mfma_f32_16x16x32_bf16 v[56:59], v[136:139], v[160:163], v[56:59]
	v_mfma_f32_16x16x32_bf16 v[44:47], v[112:115], v[168:171], v[44:47]
	v_mfma_f32_16x16x32_bf16 v[40:43], v[136:139], v[168:171], v[40:43]
	v_mfma_f32_16x16x32_bf16 v[28:31], v[112:115], v[176:179], v[28:31]
	v_mfma_f32_16x16x32_bf16 v[24:27], v[136:139], v[176:179], v[24:27]
	v_mfma_f32_16x16x32_bf16 v[12:15], v[112:115], v[200:203], v[12:15]
	v_mfma_f32_16x16x32_bf16 v[8:11], v[136:139], v[200:203], v[8:11]
	v_mfma_f32_16x16x32_bf16 v[60:63], v[124:127], v[164:167], v[60:63]
	v_mfma_f32_16x16x32_bf16 v[56:59], v[140:143], v[164:167], v[56:59]
	v_mfma_f32_16x16x32_bf16 v[44:47], v[124:127], v[172:175], v[44:47]
	v_mfma_f32_16x16x32_bf16 v[40:43], v[140:143], v[172:175], v[40:43]
	v_mfma_f32_16x16x32_bf16 v[28:31], v[124:127], v[180:183], v[28:31]
	v_mfma_f32_16x16x32_bf16 v[24:27], v[140:143], v[180:183], v[24:27]
	v_mfma_f32_16x16x32_bf16 v[12:15], v[124:127], v[204:207], v[12:15]
	v_mfma_f32_16x16x32_bf16 v[8:11], v[140:143], v[204:207], v[8:11]
	s_setprio 0
	s_setprio 1
	v_mfma_f32_16x16x32_bf16 v[52:55], v[144:147], v[160:163], v[52:55]
	v_mfma_f32_16x16x32_bf16 v[48:51], v[152:155], v[160:163], v[48:51]
	v_mfma_f32_16x16x32_bf16 v[36:39], v[144:147], v[168:171], v[36:39]
	v_mfma_f32_16x16x32_bf16 v[32:35], v[152:155], v[168:171], v[32:35]
	v_mfma_f32_16x16x32_bf16 v[20:23], v[144:147], v[176:179], v[20:23]
	v_mfma_f32_16x16x32_bf16 v[16:19], v[152:155], v[176:179], v[16:19]
	v_mfma_f32_16x16x32_bf16 v[4:7], v[144:147], v[200:203], v[4:7]
	v_mfma_f32_16x16x32_bf16 v[0:3], v[152:155], v[200:203], v[0:3]
	v_mfma_f32_16x16x32_bf16 v[52:55], v[148:151], v[164:167], v[52:55]
	v_mfma_f32_16x16x32_bf16 v[48:51], v[156:159], v[164:167], v[48:51]
	v_mfma_f32_16x16x32_bf16 v[36:39], v[148:151], v[172:175], v[36:39]
	v_mfma_f32_16x16x32_bf16 v[32:35], v[156:159], v[172:175], v[32:35]
	v_mfma_f32_16x16x32_bf16 v[20:23], v[148:151], v[180:183], v[20:23]
	v_mfma_f32_16x16x32_bf16 v[16:19], v[156:159], v[180:183], v[16:19]
	v_mfma_f32_16x16x32_bf16 v[4:7], v[148:151], v[204:207], v[4:7]
	v_mfma_f32_16x16x32_bf16 v[0:3], v[156:159], v[204:207], v[0:3]
	s_setprio 0
	s_barrier
	s_add_i32 s59, s59, 2
	s_add_u32 s60, s60, 0x100
	s_addc_u32 s61, s61, 0
	s_add_u32 s54, s54, 0x100
	s_addc_u32 s55, s55, 0
	s_cmp_gt_u32 s59, 13
	s_cbranch_scc0 .LBB0_904
	s_and_b64 vcc, exec, s[24:25]
	s_cbranch_vccz .LBB0_907
	s_barrier

.LBB0_985:
	s_add_u32 s18, s6, 0x200000
	s_addc_u32 s19, s7, 0
	s_add_u32 s71, s6, 0x400000
	s_addc_u32 s72, s7, 0
	s_add_u32 s20, s6, 0x10000000
	s_addc_u32 s21, s7, 0
	s_waitcnt lgkmcnt(0)
	s_add_u32 s22, s8, 0x10800
	s_addc_u32 s23, s9, 0
	s_add_u32 s24, s10, 0x5800
	s_addc_u32 s25, s11, 0
	s_lshl_b32 s5, s5, 5
	s_mov_b64 s[26:27], 0x80
	s_and_b32 s74, s5, 0x60
	s_add_i32 m0, s53, 0x18000
	v_lshl_add_u64 v[6:7], v[6:7], 0, s[26:27]
	s_lshl_b32 s73, s4, 6
	s_lshl_b32 s8, s4, 13
	s_lshl_b32 s5, s74, 7
	s_waitcnt vmcnt(2)
	s_barrier
	global_load_lds_dwordx4 v[6:7], off
	v_lshl_add_u64 v[4:5], v[4:5], 0, s[26:27]
	s_add_i32 m0, s53, 0x1a000
	s_add_i32 s75, s53, 0x8000
	s_add_i32 s76, s53, 0xa000
	global_load_lds_dwordx4 v[4:5], off
	v_lshl_add_u64 v[0:1], v[0:1], 0, s[26:27]
	s_mov_b32 m0, s75
	s_add_u32 s6, s14, 0x40080
	global_load_lds_dwordx4 v[0:1], off
	v_lshl_add_u64 v[0:1], v[2:3], 0, s[26:27]
	s_mov_b32 m0, s76
	s_addc_u32 s7, s15, 0
	global_load_lds_dwordx4 v[0:1], off
	s_add_i32 m0, s53, 0x1c000
	v_lshl_add_u64 v[0:1], s[6:7], 0, v[172:173]
	global_load_lds_dwordx4 v[0:1], off
	v_lshl_add_u64 v[0:1], s[6:7], 0, v[168:169]
	s_add_i32 m0, s53, 0x1e000
	s_movk_i32 s6, 0x3c0
	global_load_lds_dwordx4 v[0:1], off
	v_and_b32_e32 v0, 48, v8
	v_lshlrev_b32_e32 v1, 6, v8
	v_and_or_b32 v0, v1, s6, v0
	v_lshlrev_b32_e32 v1, 2, v8
	v_and_b32_e32 v1, 32, v1
	v_bitop3_b32 v2, v0, s8, v1 bitop3:0xde
	v_bitop3_b32 v203, s5, v0, v1 bitop3:0xf6
	v_lshlrev_b32_e32 v0, 14, v13
	v_and_b32_e32 v0, 0xffff8000, v0
	s_cmpk_lt_u32 s77, 0x100
	v_lshl_add_u32 v0, v12, 11, v0
	v_and_b32_e32 v1, 1, v13
	s_cselect_b64 s[30:31], -1, 0
	s_cmpk_gt_u32 s77, 0xff
	v_lshl_or_b32 v0, v1, 6, v0
	s_cselect_b64 s[34:35], -1, 0
	s_lshl_b32 s78, s4, 1
	v_lshl_add_u32 v178, v14, 1, v0
	v_lshlrev_b32_e32 v0, 14, v9
	s_andn2_b32 s77, s77, 63
	s_add_i32 s78, s78, 0x3ffff2
	s_lshl_b32 s79, s4, 11
	s_add_i32 s4, s4, 2
	v_and_b32_e32 v0, 0xffff8000, v0
	s_waitcnt vmcnt(6)
	s_cmp_lg_u32 s4, 0
	v_lshl_add_u32 v0, v10, 11, v0
	v_and_b32_e32 v1, 1, v9
	s_cselect_b64 s[36:37], -1, 0
	v_lshl_or_b32 v0, v1, 6, v0
	s_add_i32 s82, 0, 0x10000
	s_add_i32 s83, 0, 0x14000
	s_mov_b64 s[28:29], 0x5800
	v_and_b32_e32 v202, 63, v8
	s_lshl_b32 s80, s4, 11
	v_mov_b32_e32 v179, v177
	v_lshl_add_u32 v180, v11, 1, v0
	v_mov_b32_e32 v181, v177
	v_mov_b64_e32 v[182:183], 0x1600
	v_mov_b64_e32 v[184:185], 0x15ff
	s_movk_i32 s81, 0x2c1
	v_add_u32_e32 v204, s82, v203
	v_add_u32_e32 v205, s83, v203
	v_add_u32_e32 v206, 0, v2
	s_movk_i32 s94, 0xb00
	s_movk_i32 s95, 0x7f
	v_mov_b32_e32 v207, 0x358637bd
	s_movk_i32 s96, 0x5800
	s_movk_i32 s97, 0x1600
	v_mov_b32_e32 v208, 0xb000
	v_mov_b32_e32 v209, 2
	s_barrier
	s_mov_b32 s99, 0
	s_branch .LBB0_988

.LBB0_987:
	s_mov_b32 s99, 2
	s_andn2_b64 vcc, exec, s[6:7]
	s_mov_b32 s50, s38
	s_mov_b32 s52, s54
	s_mov_b64 s[14:15], s[58:59]
	s_mov_b64 s[60:61], s[56:57]
	s_mov_b32 s13, s85
	s_cbranch_vccz .LBB0_1020

.LBB0_991:
	ds_read_b128 v[128:131], v204
	ds_read_b128 v[132:135], v204 offset:1024
	ds_read_b128 v[136:139], v204 offset:2048
	ds_read_b128 v[140:143], v204 offset:3072
	ds_read_b128 v[144:147], v205
	ds_read_b128 v[148:151], v205 offset:1024
	ds_read_b128 v[152:155], v205 offset:2048
	ds_read_b128 v[156:159], v205 offset:3072
	s_add_u32 s10, s8, 0xfffc0080
	s_addc_u32 s11, s9, -1
	s_cmp_eq_u32 s60, 12
	s_cselect_b32 s15, s4, s11
	s_cselect_b32 s14, s5, s10
	s_cselect_b32 s11, s12, s55
	s_cselect_b32 s10, s39, s51
	v_lshl_add_u64 v[214:215], s[8:9], 0, v[178:179]
	s_add_i32 m0, s53, 0xc000
	ds_read_b128 v[160:163], v206
	ds_read_b128 v[164:167], v206 offset:1024
	ds_read_b128 v[186:189], v206 offset:2048
	ds_read_b128 v[190:193], v206 offset:3072
	ds_read_b128 v[194:197], v206 offset:4096
	ds_read_b128 v[198:201], v206 offset:5120
	ds_read_b128 v[210:213], v206 offset:6144
	ds_read_b128 v[218:221], v206 offset:7168
	global_load_lds_dwordx4 v[214:215], off
	v_lshl_add_u64 v[214:215], s[8:9], 0, v[180:181]
	s_add_i32 m0, s53, 0xe000
	s_nop 0
	global_load_lds_dwordx4 v[214:215], off
	s_cmp_lg_u32 s60, -2
	s_cbranch_scc1 .Lzacc6a
	v_mov_b32_e32 v24, 0
	v_mov_b32_e32 v25, 0
	v_mov_b32_e32 v26, 0
	v_mov_b32_e32 v27, 0
	v_mov_b32_e32 v36, 0
	v_mov_b32_e32 v37, 0
	v_mov_b32_e32 v38, 0
	v_mov_b32_e32 v39, 0
	v_mov_b32_e32 v52, 0
	v_mov_b32_e32 v53, 0
	v_mov_b32_e32 v54, 0
	v_mov_b32_e32 v55, 0
	v_mov_b32_e32 v64, 0
	v_mov_b32_e32 v65, 0
	v_mov_b32_e32 v66, 0
	v_mov_b32_e32 v67, 0
	v_mov_b32_e32 v80, 0
	v_mov_b32_e32 v81, 0
	v_mov_b32_e32 v82, 0
	v_mov_b32_e32 v83, 0
	v_mov_b32_e32 v84, 0
	v_mov_b32_e32 v85, 0
	v_mov_b32_e32 v86, 0
	v_mov_b32_e32 v87, 0
	v_mov_b32_e32 v88, 0
	v_mov_b32_e32 v89, 0
	v_mov_b32_e32 v90, 0
	v_mov_b32_e32 v91, 0
	v_mov_b32_e32 v92, 0
	v_mov_b32_e32 v93, 0
	v_mov_b32_e32 v94, 0
	v_mov_b32_e32 v95, 0
	v_mov_b32_e32 v96, 0
	v_mov_b32_e32 v97, 0
	v_mov_b32_e32 v98, 0
	v_mov_b32_e32 v99, 0
	v_mov_b32_e32 v100, 0
	v_mov_b32_e32 v101, 0
	v_mov_b32_e32 v102, 0
	v_mov_b32_e32 v103, 0
	v_mov_b32_e32 v104, 0
	v_mov_b32_e32 v105, 0
	v_mov_b32_e32 v106, 0
	v_mov_b32_e32 v107, 0
	v_mov_b32_e32 v108, 0
	v_mov_b32_e32 v109, 0
	v_mov_b32_e32 v110, 0
	v_mov_b32_e32 v111, 0
	v_mov_b32_e32 v112, 0
	v_mov_b32_e32 v113, 0
	v_mov_b32_e32 v114, 0
	v_mov_b32_e32 v115, 0
	v_mov_b32_e32 v116, 0
	v_mov_b32_e32 v117, 0
	v_mov_b32_e32 v118, 0
	v_mov_b32_e32 v119, 0
	v_mov_b32_e32 v120, 0
	v_mov_b32_e32 v121, 0
	v_mov_b32_e32 v122, 0
	v_mov_b32_e32 v123, 0
	v_mov_b32_e32 v124, 0
	v_mov_b32_e32 v125, 0
	v_mov_b32_e32 v126, 0
	v_mov_b32_e32 v127, 0
	s_cmp_eq_u32 s99, 0
	s_cbranch_scc1 .Lzacc6a
	s_sub_u32 s99, s99, 1
	s_waitcnt vmcnt(16)
	s_branch .Lzacc6a_done

.Lzacc6a_done:
	s_waitcnt lgkmcnt(0)
	s_barrier
	s_setprio 1
	s_waitcnt lgkmcnt(0)
	v_mfma_f32_16x16x32_bf16 v[124:127], v[128:131], v[160:163], v[124:127]
	v_mfma_f32_16x16x32_bf16 v[120:123], v[136:139], v[160:163], v[120:123]
	v_mfma_f32_16x16x32_bf16 v[116:119], v[128:131], v[186:189], v[116:119]
	v_mfma_f32_16x16x32_bf16 v[112:115], v[136:139], v[186:189], v[112:115]
	v_mfma_f32_16x16x32_bf16 v[108:111], v[128:131], v[194:197], v[108:111]
	v_mfma_f32_16x16x32_bf16 v[104:107], v[136:139], v[194:197], v[104:107]
	v_mfma_f32_16x16x32_bf16 v[92:95], v[128:131], v[210:213], v[92:95]
	v_mfma_f32_16x16x32_bf16 v[84:87], v[136:139], v[210:213], v[84:87]
	v_mfma_f32_16x16x32_bf16 v[124:127], v[132:135], v[164:167], v[124:127]
	v_mfma_f32_16x16x32_bf16 v[120:123], v[140:143], v[164:167], v[120:123]
	v_mfma_f32_16x16x32_bf16 v[116:119], v[132:135], v[190:193], v[116:119]
	v_mfma_f32_16x16x32_bf16 v[112:115], v[140:143], v[190:193], v[112:115]
	v_mfma_f32_16x16x32_bf16 v[108:111], v[132:135], v[198:201], v[108:111]
	v_mfma_f32_16x16x32_bf16 v[104:107], v[140:143], v[198:201], v[104:107]
	v_mfma_f32_16x16x32_bf16 v[92:95], v[132:135], v[218:221], v[92:95]
	v_mfma_f32_16x16x32_bf16 v[84:87], v[140:143], v[218:221], v[84:87]
	s_setprio 0
	s_setprio 1
	v_mfma_f32_16x16x32_bf16 v[88:91], v[144:147], v[160:163], v[88:91]
	v_mfma_f32_16x16x32_bf16 v[24:27], v[152:155], v[160:163], v[24:27]
	v_mfma_f32_16x16x32_bf16 v[100:103], v[144:147], v[186:189], v[100:103]
	v_mfma_f32_16x16x32_bf16 v[36:39], v[152:155], v[186:189], v[36:39]
	v_mfma_f32_16x16x32_bf16 v[96:99], v[144:147], v[194:197], v[96:99]
	v_mfma_f32_16x16x32_bf16 v[52:55], v[152:155], v[194:197], v[52:55]
	v_mfma_f32_16x16x32_bf16 v[80:83], v[144:147], v[210:213], v[80:83]
	v_mfma_f32_16x16x32_bf16 v[64:67], v[152:155], v[210:213], v[64:67]
	v_mfma_f32_16x16x32_bf16 v[88:91], v[148:151], v[164:167], v[88:91]
	v_mfma_f32_16x16x32_bf16 v[24:27], v[156:159], v[164:167], v[24:27]
	v_mfma_f32_16x16x32_bf16 v[100:103], v[148:151], v[190:193], v[100:103]
	v_mfma_f32_16x16x32_bf16 v[36:39], v[156:159], v[190:193], v[36:39]
	v_mfma_f32_16x16x32_bf16 v[96:99], v[148:151], v[198:201], v[96:99]
	v_mfma_f32_16x16x32_bf16 v[52:55], v[156:159], v[198:201], v[52:55]
	v_mfma_f32_16x16x32_bf16 v[80:83], v[148:151], v[218:221], v[80:83]
	v_mfma_f32_16x16x32_bf16 v[64:67], v[156:159], v[218:221], v[64:67]
	s_setprio 0
	s_barrier
	s_add_i32 s46, s82, s66
	v_lshl_add_u64 v[214:215], s[10:11], 0, v[172:173]
	s_mov_b32 m0, s46
	ds_read_b128 v[160:163], v206 offset:16384
	ds_read_b128 v[164:167], v206 offset:17408
	ds_read_b128 v[186:189], v206 offset:18432
	ds_read_b128 v[190:193], v206 offset:19456
	ds_read_b128 v[194:197], v206 offset:20480
	ds_read_b128 v[198:201], v206 offset:21504
	ds_read_b128 v[210:213], v206 offset:22528
	ds_read_b128 v[218:221], v206 offset:23552
	global_load_lds_dwordx4 v[214:215], off
	s_add_i32 m0, s46, 0x2000
	s_add_u32 s92, s10, 0x40000
	v_lshl_add_u64 v[222:223], s[10:11], 0, v[168:169]
	s_addc_u32 s93, s11, 0
	s_add_i32 s46, s83, s66
	global_load_lds_dwordx4 v[222:223], off
	v_lshl_add_u64 v[224:225], s[92:93], 0, v[172:173]
	s_mov_b32 m0, s46
	v_lshl_add_u64 v[226:227], s[14:15], 0, v[170:171]
	global_load_lds_dwordx4 v[224:225], off
	v_lshl_add_u64 v[224:225], s[92:93], 0, v[168:169]
	s_add_i32 m0, s46, 0x2000
	s_nop 0
	global_load_lds_dwordx4 v[224:225], off
	v_lshl_add_u64 v[224:225], s[14:15], 0, v[174:175]
	s_mov_b32 m0, s53
	s_nop 0
	global_load_lds_dwordx4 v[224:225], off
	s_mov_b32 m0, s67
	s_nop 0
	global_load_lds_dwordx4 v[226:227], off
	s_cmp_lg_u32 s60, -2
	s_cbranch_scc1 .Lzacc6b
	v_mov_b32_e32 v0, 0
	v_mov_b32_e32 v1, 0
	v_mov_b32_e32 v2, 0
	v_mov_b32_e32 v3, 0
	v_mov_b32_e32 v4, 0
	v_mov_b32_e32 v5, 0
	v_mov_b32_e32 v6, 0
	v_mov_b32_e32 v7, 0
	v_mov_b32_e32 v8, 0
	v_mov_b32_e32 v9, 0
	v_mov_b32_e32 v10, 0
	v_mov_b32_e32 v11, 0
	v_mov_b32_e32 v12, 0
	v_mov_b32_e32 v13, 0
	v_mov_b32_e32 v14, 0
	v_mov_b32_e32 v15, 0
	v_mov_b32_e32 v16, 0
	v_mov_b32_e32 v17, 0
	v_mov_b32_e32 v18, 0
	v_mov_b32_e32 v19, 0
	v_mov_b32_e32 v20, 0
	v_mov_b32_e32 v21, 0
	v_mov_b32_e32 v22, 0
	v_mov_b32_e32 v23, 0
	v_mov_b32_e32 v28, 0
	v_mov_b32_e32 v29, 0
	v_mov_b32_e32 v30, 0
	v_mov_b32_e32 v31, 0
	v_mov_b32_e32 v32, 0
	v_mov_b32_e32 v33, 0
	v_mov_b32_e32 v34, 0
	v_mov_b32_e32 v35, 0
	v_mov_b32_e32 v40, 0
	v_mov_b32_e32 v41, 0
	v_mov_b32_e32 v42, 0
	v_mov_b32_e32 v43, 0
	v_mov_b32_e32 v44, 0
	v_mov_b32_e32 v45, 0
	v_mov_b32_e32 v46, 0
	v_mov_b32_e32 v47, 0
	v_mov_b32_e32 v48, 0
	v_mov_b32_e32 v49, 0
	v_mov_b32_e32 v50, 0
	v_mov_b32_e32 v51, 0
	v_mov_b32_e32 v56, 0
	v_mov_b32_e32 v57, 0
	v_mov_b32_e32 v58, 0
	v_mov_b32_e32 v59, 0
	v_mov_b32_e32 v60, 0
	v_mov_b32_e32 v61, 0
	v_mov_b32_e32 v62, 0
	v_mov_b32_e32 v63, 0
	v_mov_b32_e32 v68, 0
	v_mov_b32_e32 v69, 0
	v_mov_b32_e32 v70, 0
	v_mov_b32_e32 v71, 0
	v_mov_b32_e32 v72, 0
	v_mov_b32_e32 v73, 0
	v_mov_b32_e32 v74, 0
	v_mov_b32_e32 v75, 0
	v_mov_b32_e32 v76, 0
	v_mov_b32_e32 v77, 0
	v_mov_b32_e32 v78, 0
	v_mov_b32_e32 v79, 0
	s_cmp_eq_u32 s99, 0
	s_cbranch_scc1 .Lzacc6b
	s_sub_u32 s99, s99, 1
	s_waitcnt vmcnt(16)
	s_branch .Lzacc6b_done

.Lzacc6b_done:
	s_waitcnt lgkmcnt(0)
	s_barrier
	s_setprio 1
	s_waitcnt lgkmcnt(0)
	v_mfma_f32_16x16x32_bf16 v[76:79], v[128:131], v[160:163], v[76:79]
	v_mfma_f32_16x16x32_bf16 v[72:75], v[136:139], v[160:163], v[72:75]
	v_mfma_f32_16x16x32_bf16 v[60:63], v[128:131], v[186:189], v[60:63]
	v_mfma_f32_16x16x32_bf16 v[56:59], v[136:139], v[186:189], v[56:59]
	v_mfma_f32_16x16x32_bf16 v[44:47], v[128:131], v[194:197], v[44:47]
	v_mfma_f32_16x16x32_bf16 v[40:43], v[136:139], v[194:197], v[40:43]
	v_mfma_f32_16x16x32_bf16 v[20:23], v[128:131], v[210:213], v[20:23]
	v_mfma_f32_16x16x32_bf16 v[8:11], v[136:139], v[210:213], v[8:11]
	v_mfma_f32_16x16x32_bf16 v[76:79], v[132:135], v[164:167], v[76:79]
	v_mfma_f32_16x16x32_bf16 v[72:75], v[140:143], v[164:167], v[72:75]
	v_mfma_f32_16x16x32_bf16 v[60:63], v[132:135], v[190:193], v[60:63]
	v_mfma_f32_16x16x32_bf16 v[56:59], v[140:143], v[190:193], v[56:59]
	v_mfma_f32_16x16x32_bf16 v[44:47], v[132:135], v[198:201], v[44:47]
	v_mfma_f32_16x16x32_bf16 v[40:43], v[140:143], v[198:201], v[40:43]
	v_mfma_f32_16x16x32_bf16 v[20:23], v[132:135], v[218:221], v[20:23]
	v_mfma_f32_16x16x32_bf16 v[8:11], v[140:143], v[218:221], v[8:11]
	s_setprio 0
	s_setprio 1
	v_mfma_f32_16x16x32_bf16 v[68:71], v[144:147], v[160:163], v[68:71]
	v_mfma_f32_16x16x32_bf16 v[12:15], v[152:155], v[160:163], v[12:15]
	v_mfma_f32_16x16x32_bf16 v[48:51], v[144:147], v[186:189], v[48:51]
	v_mfma_f32_16x16x32_bf16 v[28:31], v[152:155], v[186:189], v[28:31]
	v_mfma_f32_16x16x32_bf16 v[32:35], v[144:147], v[194:197], v[32:35]
	v_mfma_f32_16x16x32_bf16 v[16:19], v[152:155], v[194:197], v[16:19]
	v_mfma_f32_16x16x32_bf16 v[4:7], v[144:147], v[210:213], v[4:7]
	v_mfma_f32_16x16x32_bf16 v[0:3], v[152:155], v[210:213], v[0:3]
	v_mfma_f32_16x16x32_bf16 v[68:71], v[148:151], v[164:167], v[68:71]
	v_mfma_f32_16x16x32_bf16 v[12:15], v[156:159], v[164:167], v[12:15]
	v_mfma_f32_16x16x32_bf16 v[48:51], v[148:151], v[190:193], v[48:51]
	v_mfma_f32_16x16x32_bf16 v[28:31], v[156:159], v[190:193], v[28:31]
	v_mfma_f32_16x16x32_bf16 v[32:35], v[148:151], v[198:201], v[32:35]
	v_mfma_f32_16x16x32_bf16 v[16:19], v[156:159], v[198:201], v[16:19]
	v_mfma_f32_16x16x32_bf16 v[4:7], v[148:151], v[218:221], v[4:7]
	v_mfma_f32_16x16x32_bf16 v[0:3], v[156:159], v[218:221], v[0:3]
	s_setprio 0
	s_barrier
	s_add_i32 s46, 0, 0x18000
	s_add_i32 s47, 0, 0x1c000
	v_add_u32_e32 v140, s46, v203
	v_add_u32_e32 v156, s47, v203
	ds_read_b128 v[128:131], v140
	ds_read_b128 v[132:135], v140 offset:1024
	ds_read_b128 v[136:139], v140 offset:2048
	ds_read_b128 v[140:143], v140 offset:3072
	ds_read_b128 v[144:147], v156
	ds_read_b128 v[148:151], v156 offset:1024
	ds_read_b128 v[152:155], v156 offset:2048
	ds_read_b128 v[156:159], v156 offset:3072
	s_add_u32 s14, s14, 0x40000
	s_addc_u32 s15, s15, 0
	s_mov_b32 m0, s68
	v_lshl_add_u64 v[228:229], s[14:15], 0, v[174:175]
	ds_read_b128 v[160:163], v206 offset:32768
	ds_read_b128 v[164:167], v206 offset:33792
	ds_read_b128 v[186:189], v206 offset:34816
	ds_read_b128 v[190:193], v206 offset:35840
	ds_read_b128 v[194:197], v206 offset:36864
	ds_read_b128 v[198:201], v206 offset:37888
	ds_read_b128 v[210:213], v206 offset:38912
	ds_read_b128 v[218:221], v206 offset:39936
	global_load_lds_dwordx4 v[228:229], off
	v_lshl_add_u64 v[228:229], s[14:15], 0, v[170:171]
	s_mov_b32 m0, s69
	s_nop 0
	global_load_lds_dwordx4 v[228:229], off
	s_waitcnt vmcnt(8)
	s_waitcnt lgkmcnt(0)
	s_barrier
	s_setprio 1
	s_waitcnt lgkmcnt(0)
	v_mfma_f32_16x16x32_bf16 v[124:127], v[128:131], v[160:163], v[124:127]
	v_mfma_f32_16x16x32_bf16 v[120:123], v[136:139], v[160:163], v[120:123]
	v_mfma_f32_16x16x32_bf16 v[116:119], v[128:131], v[186:189], v[116:119]
	v_mfma_f32_16x16x32_bf16 v[112:115], v[136:139], v[186:189], v[112:115]
	v_mfma_f32_16x16x32_bf16 v[108:111], v[128:131], v[194:197], v[108:111]
	v_mfma_f32_16x16x32_bf16 v[104:107], v[136:139], v[194:197], v[104:107]
	v_mfma_f32_16x16x32_bf16 v[92:95], v[128:131], v[210:213], v[92:95]
	v_mfma_f32_16x16x32_bf16 v[84:87], v[136:139], v[210:213], v[84:87]
	v_mfma_f32_16x16x32_bf16 v[124:127], v[132:135], v[164:167], v[124:127]
	v_mfma_f32_16x16x32_bf16 v[120:123], v[140:143], v[164:167], v[120:123]
	v_mfma_f32_16x16x32_bf16 v[116:119], v[132:135], v[190:193], v[116:119]
	v_mfma_f32_16x16x32_bf16 v[112:115], v[140:143], v[190:193], v[112:115]
	v_mfma_f32_16x16x32_bf16 v[108:111], v[132:135], v[198:201], v[108:111]
	v_mfma_f32_16x16x32_bf16 v[104:107], v[140:143], v[198:201], v[104:107]
	v_mfma_f32_16x16x32_bf16 v[92:95], v[132:135], v[218:221], v[92:95]
	v_mfma_f32_16x16x32_bf16 v[84:87], v[140:143], v[218:221], v[84:87]
	s_setprio 0
	s_setprio 1
	v_mfma_f32_16x16x32_bf16 v[88:91], v[144:147], v[160:163], v[88:91]
	v_mfma_f32_16x16x32_bf16 v[24:27], v[152:155], v[160:163], v[24:27]
	v_mfma_f32_16x16x32_bf16 v[100:103], v[144:147], v[186:189], v[100:103]
	v_mfma_f32_16x16x32_bf16 v[36:39], v[152:155], v[186:189], v[36:39]
	v_mfma_f32_16x16x32_bf16 v[96:99], v[144:147], v[194:197], v[96:99]
	v_mfma_f32_16x16x32_bf16 v[52:55], v[152:155], v[194:197], v[52:55]
	v_mfma_f32_16x16x32_bf16 v[80:83], v[144:147], v[210:213], v[80:83]
	v_mfma_f32_16x16x32_bf16 v[64:67], v[152:155], v[210:213], v[64:67]
	v_mfma_f32_16x16x32_bf16 v[88:91], v[148:151], v[164:167], v[88:91]
	v_mfma_f32_16x16x32_bf16 v[24:27], v[156:159], v[164:167], v[24:27]
	v_mfma_f32_16x16x32_bf16 v[100:103], v[148:151], v[190:193], v[100:103]
	v_mfma_f32_16x16x32_bf16 v[36:39], v[156:159], v[190:193], v[36:39]
	v_mfma_f32_16x16x32_bf16 v[96:99], v[148:151], v[198:201], v[96:99]
	v_mfma_f32_16x16x32_bf16 v[52:55], v[156:159], v[198:201], v[52:55]
	v_mfma_f32_16x16x32_bf16 v[80:83], v[148:151], v[218:221], v[80:83]
	v_mfma_f32_16x16x32_bf16 v[64:67], v[156:159], v[218:221], v[64:67]
	s_setprio 0
	s_barrier
	s_add_i32 s14, s46, s66
	v_lshl_add_u64 v[214:215], v[214:215], 0, s[26:27]
	s_mov_b32 m0, s14
	ds_read_b128 v[160:163], v206 offset:49152
	ds_read_b128 v[164:167], v206 offset:50176
	ds_read_b128 v[186:189], v206 offset:51200
	ds_read_b128 v[190:193], v206 offset:52224
	ds_read_b128 v[194:197], v206 offset:53248
	ds_read_b128 v[198:201], v206 offset:54272
	ds_read_b128 v[210:213], v206 offset:55296
	ds_read_b128 v[218:221], v206 offset:56320
	global_load_lds_dwordx4 v[214:215], off
	s_add_i32 m0, s14, 0x2000
	s_add_u32 s10, s10, 0x40080
	v_lshl_add_u64 v[214:215], v[222:223], 0, s[26:27]
	s_addc_u32 s11, s11, 0
	s_add_i32 s14, s47, s66
	global_load_lds_dwordx4 v[214:215], off
	v_lshl_add_u64 v[214:215], s[10:11], 0, v[172:173]
	s_mov_b32 m0, s14
	s_nop 0
	global_load_lds_dwordx4 v[214:215], off
	v_lshl_add_u64 v[214:215], s[10:11], 0, v[168:169]
	s_add_i32 m0, s14, 0x2000
	s_nop 0
	global_load_lds_dwordx4 v[214:215], off
	v_lshl_add_u64 v[214:215], v[224:225], 0, s[26:27]
	s_mov_b32 m0, s75
	s_nop 0
	global_load_lds_dwordx4 v[214:215], off
	v_lshl_add_u64 v[214:215], v[226:227], 0, s[26:27]
	s_mov_b32 m0, s76
	s_nop 0
	global_load_lds_dwordx4 v[214:215], off
	s_waitcnt vmcnt(8)
	s_waitcnt lgkmcnt(0)
	s_barrier
	s_setprio 1
	s_waitcnt lgkmcnt(0)
	v_mfma_f32_16x16x32_bf16 v[76:79], v[128:131], v[160:163], v[76:79]
	v_mfma_f32_16x16x32_bf16 v[72:75], v[136:139], v[160:163], v[72:75]
	v_mfma_f32_16x16x32_bf16 v[60:63], v[128:131], v[186:189], v[60:63]
	v_mfma_f32_16x16x32_bf16 v[56:59], v[136:139], v[186:189], v[56:59]
	v_mfma_f32_16x16x32_bf16 v[44:47], v[128:131], v[194:197], v[44:47]
	v_mfma_f32_16x16x32_bf16 v[40:43], v[136:139], v[194:197], v[40:43]
	v_mfma_f32_16x16x32_bf16 v[20:23], v[128:131], v[210:213], v[20:23]
	v_mfma_f32_16x16x32_bf16 v[8:11], v[136:139], v[210:213], v[8:11]
	v_mfma_f32_16x16x32_bf16 v[76:79], v[132:135], v[164:167], v[76:79]
	v_mfma_f32_16x16x32_bf16 v[72:75], v[140:143], v[164:167], v[72:75]
	v_mfma_f32_16x16x32_bf16 v[60:63], v[132:135], v[190:193], v[60:63]
	v_mfma_f32_16x16x32_bf16 v[56:59], v[140:143], v[190:193], v[56:59]
	v_mfma_f32_16x16x32_bf16 v[44:47], v[132:135], v[198:201], v[44:47]
	v_mfma_f32_16x16x32_bf16 v[40:43], v[140:143], v[198:201], v[40:43]
	v_mfma_f32_16x16x32_bf16 v[20:23], v[132:135], v[218:221], v[20:23]
	v_mfma_f32_16x16x32_bf16 v[8:11], v[140:143], v[218:221], v[8:11]
	s_setprio 0
	s_setprio 1
	v_mfma_f32_16x16x32_bf16 v[68:71], v[144:147], v[160:163], v[68:71]
	v_mfma_f32_16x16x32_bf16 v[12:15], v[152:155], v[160:163], v[12:15]
	v_mfma_f32_16x16x32_bf16 v[48:51], v[144:147], v[186:189], v[48:51]
	v_mfma_f32_16x16x32_bf16 v[28:31], v[152:155], v[186:189], v[28:31]
	v_mfma_f32_16x16x32_bf16 v[32:35], v[144:147], v[194:197], v[32:35]
	v_mfma_f32_16x16x32_bf16 v[16:19], v[152:155], v[194:197], v[16:19]
	v_mfma_f32_16x16x32_bf16 v[4:7], v[144:147], v[210:213], v[4:7]
	v_mfma_f32_16x16x32_bf16 v[0:3], v[152:155], v[210:213], v[0:3]
	v_mfma_f32_16x16x32_bf16 v[68:71], v[148:151], v[164:167], v[68:71]
	v_mfma_f32_16x16x32_bf16 v[12:15], v[156:159], v[164:167], v[12:15]
	v_mfma_f32_16x16x32_bf16 v[48:51], v[148:151], v[190:193], v[48:51]
	v_mfma_f32_16x16x32_bf16 v[28:31], v[156:159], v[190:193], v[28:31]
	v_mfma_f32_16x16x32_bf16 v[32:35], v[148:151], v[198:201], v[32:35]
	v_mfma_f32_16x16x32_bf16 v[16:19], v[156:159], v[198:201], v[16:19]
	v_mfma_f32_16x16x32_bf16 v[4:7], v[148:151], v[218:221], v[4:7]
	v_mfma_f32_16x16x32_bf16 v[0:3], v[156:159], v[218:221], v[0:3]
	s_setprio 0
	s_barrier
	s_add_i32 s60, s60, 2
	s_add_u32 s8, s8, 0x100
	s_addc_u32 s9, s9, 0
	s_add_u32 s51, s51, 0x100
	s_addc_u32 s55, s55, 0
	s_cmp_gt_u32 s60, 13
	s_cbranch_scc0 .LBB0_991
	s_and_b64 vcc, exec, s[30:31]
	s_cbranch_vccz .LBB0_994
	s_barrier

.LBB0_1137:
	s_add_u32 s16, s4, 0x300000
	s_addc_u32 s17, s5, 0
	s_add_u32 s18, s4, 0x8000000
	s_mov_b64 s[20:21], 0x80
	s_addc_u32 s19, s5, 0
	s_and_b32 s7, s7, 3
	s_add_i32 m0, s55, 0x18000
	v_lshl_add_u64 v[6:7], v[6:7], 0, s[20:21]
	s_lshl_b32 s59, s6, 6
	s_lshl_b32 s6, s6, 13
	s_lshl_b32 s10, s7, 12
	s_waitcnt vmcnt(2)
	s_barrier
	global_load_lds_dwordx4 v[6:7], off
	v_lshl_add_u64 v[4:5], v[4:5], 0, s[20:21]
	s_add_i32 m0, s55, 0x1a000
	s_add_i32 s60, s55, 0x8000
	s_add_i32 s61, s55, 0xa000
	global_load_lds_dwordx4 v[4:5], off
	v_lshl_add_u64 v[0:1], v[0:1], 0, s[20:21]
	s_mov_b32 m0, s60
	s_add_u32 s4, s38, 0xb0080
	global_load_lds_dwordx4 v[0:1], off
	v_lshl_add_u64 v[0:1], v[2:3], 0, s[20:21]
	s_mov_b32 m0, s61
	s_addc_u32 s5, s39, 0
	global_load_lds_dwordx4 v[0:1], off
	s_add_i32 m0, s55, 0x1c000
	v_lshl_add_u64 v[0:1], s[4:5], 0, v[186:187]
	global_load_lds_dwordx4 v[0:1], off
	v_lshl_add_u64 v[0:1], s[4:5], 0, v[190:191]
	s_add_i32 m0, s55, 0x1e000
	s_cmpk_lt_u32 s8, 0x100
	global_load_lds_dwordx4 v[0:1], off
	v_lshrrev_b32_e32 v1, 1, v8
	v_and_b32_e32 v0, 63, v8
	v_and_b32_e32 v1, 24, v1
	v_lshl_or_b32 v221, s7, 5, v1
	s_cselect_b64 s[22:23], -1, 0
	v_cmp_gt_u32_e64 s[4:5], 16, v0
	s_lshl_b32 s62, s7, 10
	s_movk_i32 s7, 0xffc0
	v_mov_b32_e32 v0, s8
	v_bfi_b32 v222, s7, v0, v8
	v_lshrrev_b32_e32 v1, 1, v9
	v_mul_lo_u32 v0, v11, s9
	s_mov_b32 s8, 0xb000
	v_and_b32_e32 v218, 15, v8
	v_and_b32_e32 v2, 48, v8
	v_lshlrev_b32_e32 v3, 2, v8
	v_mad_u64_u32 v[0:1], s[24:25], v1, s8, v[0:1]
	v_lshl_or_b32 v2, v218, 6, v2
	v_and_b32_e32 v3, 32, v3
	v_or_b32_e32 v0, v0, v10
	v_bitop3_b32 v220, v2, s10, v3 bitop3:0xde
	s_mov_b64 s[10:11], 0xb0080
	v_add_lshl_u32 v0, v0, v12, 1
	v_mov_b32_e32 v1, v187
	v_lshl_add_u64 v[192:193], v[0:1], 0, s[10:11]
	v_lshrrev_b32_e32 v1, 1, v13
	v_mul_lo_u32 v0, v14, s9
	v_mad_u64_u32 v[0:1], s[8:9], v1, s8, v[0:1]
	s_waitcnt vmcnt(6)
	v_or_b32_e32 v0, v0, v15
	v_bitop3_b32 v4, v2, s6, v3 bitop3:0xde
	s_movk_i32 s6, 0x100
	v_add_lshl_u32 v0, v0, v16, 1
	v_mov_b32_e32 v1, v187
	s_add_i32 s63, 0, 0x10000
	s_add_i32 s64, 0, 0x14000
	v_or_b32_e32 v219, s59, v218
	v_cmp_gt_i32_e64 s[6:7], s6, v222
	v_lshl_add_u64 v[194:195], v[0:1], 0, s[10:11]
	v_mov_b64_e32 v[196:197], 0x400
	v_mov_b64_e32 v[198:199], 0x3ff
	v_add_u32_e32 v223, s63, v220
	v_add_u32_e32 v224, s64, v220
	v_add_u32_e32 v225, 0, v4
	s_mov_b64 s[24:25], 0x40000
	s_mov_b64 s[26:27], 0x48000
	s_mov_b64 s[28:29], 0x50000
	s_mov_b64 s[30:31], 0x58000
	v_mbcnt_hi_u32_b32 v217, -1, v248
	s_barrier
	s_mov_b32 s99, 0
	s_branch .LBB0_1140

.LBB0_1139:
	s_mov_b32 s99, 2
	s_andn2_b64 vcc, exec, s[8:9]
	s_mov_b32 s12, s66
	s_mov_b32 s13, s67
	s_mov_b64 s[38:39], s[34:35]
	s_mov_b64 s[36:37], s[10:11]
	s_mov_b32 s68, s65
	s_cbranch_vccz .LBB0_1175

.LBB0_1151:
	ds_read_b128 v[112:115], v223
	ds_read_b128 v[124:127], v223 offset:1024
	ds_read_b128 v[136:139], v223 offset:2048
	ds_read_b128 v[140:143], v223 offset:3072
	ds_read_b128 v[144:147], v224
	ds_read_b128 v[148:151], v224 offset:1024
	ds_read_b128 v[152:155], v224 offset:2048
	ds_read_b128 v[156:159], v224 offset:3072
	s_add_u32 s38, s36, 0x100
	s_addc_u32 s39, s37, 0
	s_cmp_eq_u32 s71, 40
	s_cselect_b32 s49, s11, s39
	s_cselect_b32 s48, s10, s38
	s_cselect_b32 s47, s35, s70
	s_cselect_b32 s46, s34, s69
	v_lshl_add_u64 v[208:209], s[36:37], 0, v[192:193]
	s_add_i32 m0, s55, 0xc000
	ds_read_b128 v[160:163], v225
	ds_read_b128 v[164:167], v225 offset:1024
	ds_read_b128 v[168:171], v225 offset:2048
	ds_read_b128 v[172:175], v225 offset:3072
	ds_read_b128 v[176:179], v225 offset:4096
	ds_read_b128 v[180:183], v225 offset:5120
	ds_read_b128 v[200:203], v225 offset:6144
	ds_read_b128 v[204:207], v225 offset:7168
	global_load_lds_dwordx4 v[208:209], off
	v_lshl_add_u64 v[208:209], s[36:37], 0, v[194:195]
	s_add_i32 m0, s55, 0xe000
	s_nop 0
	global_load_lds_dwordx4 v[208:209], off
	s_cmp_lg_u32 s71, -2
	s_cbranch_scc1 .Lzacc7a
	v_mov_b32_e32 v64, 0
	v_mov_b32_e32 v65, 0
	v_mov_b32_e32 v66, 0
	v_mov_b32_e32 v67, 0
	v_mov_b32_e32 v68, 0
	v_mov_b32_e32 v69, 0
	v_mov_b32_e32 v70, 0
	v_mov_b32_e32 v71, 0
	v_mov_b32_e32 v72, 0
	v_mov_b32_e32 v73, 0
	v_mov_b32_e32 v74, 0
	v_mov_b32_e32 v75, 0
	v_mov_b32_e32 v76, 0
	v_mov_b32_e32 v77, 0
	v_mov_b32_e32 v78, 0
	v_mov_b32_e32 v79, 0
	v_mov_b32_e32 v80, 0
	v_mov_b32_e32 v81, 0
	v_mov_b32_e32 v82, 0
	v_mov_b32_e32 v83, 0
	v_mov_b32_e32 v84, 0
	v_mov_b32_e32 v85, 0
	v_mov_b32_e32 v86, 0
	v_mov_b32_e32 v87, 0
	v_mov_b32_e32 v88, 0
	v_mov_b32_e32 v89, 0
	v_mov_b32_e32 v90, 0
	v_mov_b32_e32 v91, 0
	v_mov_b32_e32 v92, 0
	v_mov_b32_e32 v93, 0
	v_mov_b32_e32 v94, 0
	v_mov_b32_e32 v95, 0
	v_mov_b32_e32 v96, 0
	v_mov_b32_e32 v97, 0
	v_mov_b32_e32 v98, 0
	v_mov_b32_e32 v99, 0
	v_mov_b32_e32 v100, 0
	v_mov_b32_e32 v101, 0
	v_mov_b32_e32 v102, 0
	v_mov_b32_e32 v103, 0
	v_mov_b32_e32 v104, 0
	v_mov_b32_e32 v105, 0
	v_mov_b32_e32 v106, 0
	v_mov_b32_e32 v107, 0
	v_mov_b32_e32 v108, 0
	v_mov_b32_e32 v109, 0
	v_mov_b32_e32 v110, 0
	v_mov_b32_e32 v111, 0
	v_mov_b32_e32 v116, 0
	v_mov_b32_e32 v117, 0
	v_mov_b32_e32 v118, 0
	v_mov_b32_e32 v119, 0
	v_mov_b32_e32 v120, 0
	v_mov_b32_e32 v121, 0
	v_mov_b32_e32 v122, 0
	v_mov_b32_e32 v123, 0
	v_mov_b32_e32 v128, 0
	v_mov_b32_e32 v129, 0
	v_mov_b32_e32 v130, 0
	v_mov_b32_e32 v131, 0
	v_mov_b32_e32 v132, 0
	v_mov_b32_e32 v133, 0
	v_mov_b32_e32 v134, 0
	v_mov_b32_e32 v135, 0
	s_cmp_eq_u32 s99, 0
	s_cbranch_scc1 .Lzacc7a
	s_sub_u32 s99, s99, 1
	s_waitcnt vmcnt(24)
	s_branch .Lzacc7a_done

.Lzacc7a_done:
	s_waitcnt lgkmcnt(0)
	s_barrier
	s_setprio 1
	s_waitcnt lgkmcnt(0)
	v_mfma_f32_16x16x32_bf16 v[132:135], v[112:115], v[160:163], v[132:135]
	v_mfma_f32_16x16x32_bf16 v[128:131], v[136:139], v[160:163], v[128:131]
	v_mfma_f32_16x16x32_bf16 v[108:111], v[112:115], v[168:171], v[108:111]
	v_mfma_f32_16x16x32_bf16 v[104:107], v[136:139], v[168:171], v[104:107]
	v_mfma_f32_16x16x32_bf16 v[92:95], v[112:115], v[176:179], v[92:95]
	v_mfma_f32_16x16x32_bf16 v[88:91], v[136:139], v[176:179], v[88:91]
	v_mfma_f32_16x16x32_bf16 v[76:79], v[112:115], v[200:203], v[76:79]
	v_mfma_f32_16x16x32_bf16 v[72:75], v[136:139], v[200:203], v[72:75]
	v_mfma_f32_16x16x32_bf16 v[132:135], v[124:127], v[164:167], v[132:135]
	v_mfma_f32_16x16x32_bf16 v[128:131], v[140:143], v[164:167], v[128:131]
	v_mfma_f32_16x16x32_bf16 v[108:111], v[124:127], v[172:175], v[108:111]
	v_mfma_f32_16x16x32_bf16 v[104:107], v[140:143], v[172:175], v[104:107]
	v_mfma_f32_16x16x32_bf16 v[92:95], v[124:127], v[180:183], v[92:95]
	v_mfma_f32_16x16x32_bf16 v[88:91], v[140:143], v[180:183], v[88:91]
	v_mfma_f32_16x16x32_bf16 v[76:79], v[124:127], v[204:207], v[76:79]
	v_mfma_f32_16x16x32_bf16 v[72:75], v[140:143], v[204:207], v[72:75]
	s_setprio 0
	s_setprio 1
	v_mfma_f32_16x16x32_bf16 v[120:123], v[144:147], v[160:163], v[120:123]
	v_mfma_f32_16x16x32_bf16 v[116:119], v[152:155], v[160:163], v[116:119]
	v_mfma_f32_16x16x32_bf16 v[100:103], v[144:147], v[168:171], v[100:103]
	v_mfma_f32_16x16x32_bf16 v[96:99], v[152:155], v[168:171], v[96:99]
	v_mfma_f32_16x16x32_bf16 v[84:87], v[144:147], v[176:179], v[84:87]
	v_mfma_f32_16x16x32_bf16 v[80:83], v[152:155], v[176:179], v[80:83]
	v_mfma_f32_16x16x32_bf16 v[68:71], v[144:147], v[200:203], v[68:71]
	v_mfma_f32_16x16x32_bf16 v[64:67], v[152:155], v[200:203], v[64:67]
	v_mfma_f32_16x16x32_bf16 v[120:123], v[148:151], v[164:167], v[120:123]
	v_mfma_f32_16x16x32_bf16 v[116:119], v[156:159], v[164:167], v[116:119]
	v_mfma_f32_16x16x32_bf16 v[100:103], v[148:151], v[172:175], v[100:103]
	v_mfma_f32_16x16x32_bf16 v[96:99], v[156:159], v[172:175], v[96:99]
	v_mfma_f32_16x16x32_bf16 v[84:87], v[148:151], v[180:183], v[84:87]
	v_mfma_f32_16x16x32_bf16 v[80:83], v[156:159], v[180:183], v[80:83]
	v_mfma_f32_16x16x32_bf16 v[68:71], v[148:151], v[204:207], v[68:71]
	v_mfma_f32_16x16x32_bf16 v[64:67], v[156:159], v[204:207], v[64:67]
	s_setprio 0
	s_barrier
	s_add_i32 s36, s63, s54
	v_lshl_add_u64 v[208:209], s[46:47], 0, v[186:187]
	s_mov_b32 m0, s36
	ds_read_b128 v[160:163], v225 offset:16384
	ds_read_b128 v[164:167], v225 offset:17408
	ds_read_b128 v[168:171], v225 offset:18432
	ds_read_b128 v[172:175], v225 offset:19456
	ds_read_b128 v[176:179], v225 offset:20480
	ds_read_b128 v[180:183], v225 offset:21504
	ds_read_b128 v[200:203], v225 offset:22528
	ds_read_b128 v[204:207], v225 offset:23552
	global_load_lds_dwordx4 v[208:209], off
	s_add_i32 m0, s36, 0x2000
	s_add_u32 s36, s46, 0xb0000
	v_lshl_add_u64 v[210:211], s[46:47], 0, v[190:191]
	s_addc_u32 s37, s47, 0
	s_add_i32 s72, s64, s54
	global_load_lds_dwordx4 v[210:211], off
	v_lshl_add_u64 v[212:213], s[36:37], 0, v[186:187]
	s_mov_b32 m0, s72
	v_lshl_add_u64 v[214:215], s[48:49], 0, v[188:189]
	global_load_lds_dwordx4 v[212:213], off
	v_lshl_add_u64 v[212:213], s[36:37], 0, v[190:191]
	s_add_i32 m0, s72, 0x2000
	s_nop 0
	global_load_lds_dwordx4 v[212:213], off
	v_lshl_add_u64 v[212:213], s[48:49], 0, v[184:185]
	s_mov_b32 m0, s55
	s_nop 0
	global_load_lds_dwordx4 v[212:213], off
	s_mov_b32 m0, s56
	s_nop 0
	global_load_lds_dwordx4 v[214:215], off
	s_cmp_lg_u32 s71, -2
	s_cbranch_scc1 .Lzacc7b
	v_mov_b32_e32 v0, 0
	v_mov_b32_e32 v1, 0
	v_mov_b32_e32 v2, 0
	v_mov_b32_e32 v3, 0
	v_mov_b32_e32 v4, 0
	v_mov_b32_e32 v5, 0
	v_mov_b32_e32 v6, 0
	v_mov_b32_e32 v7, 0
	v_mov_b32_e32 v8, 0
	v_mov_b32_e32 v9, 0
	v_mov_b32_e32 v10, 0
	v_mov_b32_e32 v11, 0
	v_mov_b32_e32 v12, 0
	v_mov_b32_e32 v13, 0
	v_mov_b32_e32 v14, 0
	v_mov_b32_e32 v15, 0
	v_mov_b32_e32 v16, 0
	v_mov_b32_e32 v17, 0
	v_mov_b32_e32 v18, 0
	v_mov_b32_e32 v19, 0
	v_mov_b32_e32 v20, 0
	v_mov_b32_e32 v21, 0
	v_mov_b32_e32 v22, 0
	v_mov_b32_e32 v23, 0
	v_mov_b32_e32 v24, 0
	v_mov_b32_e32 v25, 0
	v_mov_b32_e32 v26, 0
	v_mov_b32_e32 v27, 0
	v_mov_b32_e32 v28, 0
	v_mov_b32_e32 v29, 0
	v_mov_b32_e32 v30, 0
	v_mov_b32_e32 v31, 0
	v_mov_b32_e32 v32, 0
	v_mov_b32_e32 v33, 0
	v_mov_b32_e32 v34, 0
	v_mov_b32_e32 v35, 0
	v_mov_b32_e32 v36, 0
	v_mov_b32_e32 v37, 0
	v_mov_b32_e32 v38, 0
	v_mov_b32_e32 v39, 0
	v_mov_b32_e32 v40, 0
	v_mov_b32_e32 v41, 0
	v_mov_b32_e32 v42, 0
	v_mov_b32_e32 v43, 0
	v_mov_b32_e32 v44, 0
	v_mov_b32_e32 v45, 0
	v_mov_b32_e32 v46, 0
	v_mov_b32_e32 v47, 0
	v_mov_b32_e32 v48, 0
	v_mov_b32_e32 v49, 0
	v_mov_b32_e32 v50, 0
	v_mov_b32_e32 v51, 0
	v_mov_b32_e32 v52, 0
	v_mov_b32_e32 v53, 0
	v_mov_b32_e32 v54, 0
	v_mov_b32_e32 v55, 0
	v_mov_b32_e32 v56, 0
	v_mov_b32_e32 v57, 0
	v_mov_b32_e32 v58, 0
	v_mov_b32_e32 v59, 0
	v_mov_b32_e32 v60, 0
	v_mov_b32_e32 v61, 0
	v_mov_b32_e32 v62, 0
	v_mov_b32_e32 v63, 0
	s_cmp_eq_u32 s99, 0
	s_cbranch_scc1 .Lzacc7b
	s_sub_u32 s99, s99, 1
	s_waitcnt vmcnt(24)
	s_branch .Lzacc7b_done

.Lzacc7b_done:
	s_waitcnt lgkmcnt(0)
	s_barrier
	s_setprio 1
	s_waitcnt lgkmcnt(0)
	v_mfma_f32_16x16x32_bf16 v[60:63], v[112:115], v[160:163], v[60:63]
	v_mfma_f32_16x16x32_bf16 v[56:59], v[136:139], v[160:163], v[56:59]
	v_mfma_f32_16x16x32_bf16 v[44:47], v[112:115], v[168:171], v[44:47]
	v_mfma_f32_16x16x32_bf16 v[40:43], v[136:139], v[168:171], v[40:43]
	v_mfma_f32_16x16x32_bf16 v[28:31], v[112:115], v[176:179], v[28:31]
	v_mfma_f32_16x16x32_bf16 v[24:27], v[136:139], v[176:179], v[24:27]
	v_mfma_f32_16x16x32_bf16 v[12:15], v[112:115], v[200:203], v[12:15]
	v_mfma_f32_16x16x32_bf16 v[8:11], v[136:139], v[200:203], v[8:11]
	v_mfma_f32_16x16x32_bf16 v[60:63], v[124:127], v[164:167], v[60:63]
	v_mfma_f32_16x16x32_bf16 v[56:59], v[140:143], v[164:167], v[56:59]
	v_mfma_f32_16x16x32_bf16 v[44:47], v[124:127], v[172:175], v[44:47]
	v_mfma_f32_16x16x32_bf16 v[40:43], v[140:143], v[172:175], v[40:43]
	v_mfma_f32_16x16x32_bf16 v[28:31], v[124:127], v[180:183], v[28:31]
	v_mfma_f32_16x16x32_bf16 v[24:27], v[140:143], v[180:183], v[24:27]
	v_mfma_f32_16x16x32_bf16 v[12:15], v[124:127], v[204:207], v[12:15]
	v_mfma_f32_16x16x32_bf16 v[8:11], v[140:143], v[204:207], v[8:11]
	s_setprio 0
	s_setprio 1
	v_mfma_f32_16x16x32_bf16 v[52:55], v[144:147], v[160:163], v[52:55]
	v_mfma_f32_16x16x32_bf16 v[48:51], v[152:155], v[160:163], v[48:51]
	v_mfma_f32_16x16x32_bf16 v[36:39], v[144:147], v[168:171], v[36:39]
	v_mfma_f32_16x16x32_bf16 v[32:35], v[152:155], v[168:171], v[32:35]
	v_mfma_f32_16x16x32_bf16 v[20:23], v[144:147], v[176:179], v[20:23]
	v_mfma_f32_16x16x32_bf16 v[16:19], v[152:155], v[176:179], v[16:19]
	v_mfma_f32_16x16x32_bf16 v[4:7], v[144:147], v[200:203], v[4:7]
	v_mfma_f32_16x16x32_bf16 v[0:3], v[152:155], v[200:203], v[0:3]
	v_mfma_f32_16x16x32_bf16 v[52:55], v[148:151], v[164:167], v[52:55]
	v_mfma_f32_16x16x32_bf16 v[48:51], v[156:159], v[164:167], v[48:51]
	v_mfma_f32_16x16x32_bf16 v[36:39], v[148:151], v[172:175], v[36:39]
	v_mfma_f32_16x16x32_bf16 v[32:35], v[156:159], v[172:175], v[32:35]
	v_mfma_f32_16x16x32_bf16 v[20:23], v[148:151], v[180:183], v[20:23]
	v_mfma_f32_16x16x32_bf16 v[16:19], v[156:159], v[180:183], v[16:19]
	v_mfma_f32_16x16x32_bf16 v[4:7], v[148:151], v[204:207], v[4:7]
	v_mfma_f32_16x16x32_bf16 v[0:3], v[156:159], v[204:207], v[0:3]
	s_setprio 0
	s_barrier
	s_add_i32 s72, 0, 0x18000
	s_add_i32 s73, 0, 0x1c000
	v_add_u32_e32 v140, s72, v220
	v_add_u32_e32 v156, s73, v220
	ds_read_b128 v[112:115], v140
	ds_read_b128 v[124:127], v140 offset:1024
	ds_read_b128 v[136:139], v140 offset:2048
	ds_read_b128 v[140:143], v140 offset:3072
	ds_read_b128 v[144:147], v156
	ds_read_b128 v[148:151], v156 offset:1024
	ds_read_b128 v[152:155], v156 offset:2048
	ds_read_b128 v[156:159], v156 offset:3072
	s_add_u32 s36, s48, 0xb0000
	s_addc_u32 s37, s49, 0
	s_mov_b32 m0, s57
	v_lshl_add_u64 v[226:227], s[36:37], 0, v[184:185]
	ds_read_b128 v[160:163], v225 offset:32768
	ds_read_b128 v[164:167], v225 offset:33792
	ds_read_b128 v[168:171], v225 offset:34816
	ds_read_b128 v[172:175], v225 offset:35840
	ds_read_b128 v[176:179], v225 offset:36864
	ds_read_b128 v[180:183], v225 offset:37888
	ds_read_b128 v[200:203], v225 offset:38912
	ds_read_b128 v[204:207], v225 offset:39936
	global_load_lds_dwordx4 v[226:227], off
	v_lshl_add_u64 v[226:227], s[36:37], 0, v[188:189]
	s_mov_b32 m0, s58
	s_nop 0
	global_load_lds_dwordx4 v[226:227], off
	s_waitcnt vmcnt(8)
	s_waitcnt lgkmcnt(0)
	s_barrier
	s_setprio 1
	s_waitcnt lgkmcnt(0)
	v_mfma_f32_16x16x32_bf16 v[132:135], v[112:115], v[160:163], v[132:135]
	v_mfma_f32_16x16x32_bf16 v[128:131], v[136:139], v[160:163], v[128:131]
	v_mfma_f32_16x16x32_bf16 v[108:111], v[112:115], v[168:171], v[108:111]
	v_mfma_f32_16x16x32_bf16 v[104:107], v[136:139], v[168:171], v[104:107]
	v_mfma_f32_16x16x32_bf16 v[92:95], v[112:115], v[176:179], v[92:95]
	v_mfma_f32_16x16x32_bf16 v[88:91], v[136:139], v[176:179], v[88:91]
	v_mfma_f32_16x16x32_bf16 v[76:79], v[112:115], v[200:203], v[76:79]
	v_mfma_f32_16x16x32_bf16 v[72:75], v[136:139], v[200:203], v[72:75]
	v_mfma_f32_16x16x32_bf16 v[132:135], v[124:127], v[164:167], v[132:135]
	v_mfma_f32_16x16x32_bf16 v[128:131], v[140:143], v[164:167], v[128:131]
	v_mfma_f32_16x16x32_bf16 v[108:111], v[124:127], v[172:175], v[108:111]
	v_mfma_f32_16x16x32_bf16 v[104:107], v[140:143], v[172:175], v[104:107]
	v_mfma_f32_16x16x32_bf16 v[92:95], v[124:127], v[180:183], v[92:95]
	v_mfma_f32_16x16x32_bf16 v[88:91], v[140:143], v[180:183], v[88:91]
	v_mfma_f32_16x16x32_bf16 v[76:79], v[124:127], v[204:207], v[76:79]
	v_mfma_f32_16x16x32_bf16 v[72:75], v[140:143], v[204:207], v[72:75]
	s_setprio 0
	s_setprio 1
	v_mfma_f32_16x16x32_bf16 v[120:123], v[144:147], v[160:163], v[120:123]
	v_mfma_f32_16x16x32_bf16 v[116:119], v[152:155], v[160:163], v[116:119]
	v_mfma_f32_16x16x32_bf16 v[100:103], v[144:147], v[168:171], v[100:103]
	v_mfma_f32_16x16x32_bf16 v[96:99], v[152:155], v[168:171], v[96:99]
	v_mfma_f32_16x16x32_bf16 v[84:87], v[144:147], v[176:179], v[84:87]
	v_mfma_f32_16x16x32_bf16 v[80:83], v[152:155], v[176:179], v[80:83]
	v_mfma_f32_16x16x32_bf16 v[68:71], v[144:147], v[200:203], v[68:71]
	v_mfma_f32_16x16x32_bf16 v[64:67], v[152:155], v[200:203], v[64:67]
	v_mfma_f32_16x16x32_bf16 v[120:123], v[148:151], v[164:167], v[120:123]
	v_mfma_f32_16x16x32_bf16 v[116:119], v[156:159], v[164:167], v[116:119]
	v_mfma_f32_16x16x32_bf16 v[100:103], v[148:151], v[172:175], v[100:103]
	v_mfma_f32_16x16x32_bf16 v[96:99], v[156:159], v[172:175], v[96:99]
	v_mfma_f32_16x16x32_bf16 v[84:87], v[148:151], v[180:183], v[84:87]
	v_mfma_f32_16x16x32_bf16 v[80:83], v[156:159], v[180:183], v[80:83]
	v_mfma_f32_16x16x32_bf16 v[68:71], v[148:151], v[204:207], v[68:71]
	v_mfma_f32_16x16x32_bf16 v[64:67], v[156:159], v[204:207], v[64:67]
	s_setprio 0
	s_barrier
	s_add_i32 s36, s72, s54
	v_lshl_add_u64 v[208:209], v[208:209], 0, s[20:21]
	s_mov_b32 m0, s36
	ds_read_b128 v[160:163], v225 offset:49152
	ds_read_b128 v[164:167], v225 offset:50176
	ds_read_b128 v[168:171], v225 offset:51200
	ds_read_b128 v[172:175], v225 offset:52224
	ds_read_b128 v[176:179], v225 offset:53248
	ds_read_b128 v[180:183], v225 offset:54272
	ds_read_b128 v[200:203], v225 offset:55296
	ds_read_b128 v[204:207], v225 offset:56320
	global_load_lds_dwordx4 v[208:209], off
	s_add_i32 m0, s36, 0x2000
	s_add_u32 s36, s46, 0xb0080
	v_lshl_add_u64 v[208:209], v[210:211], 0, s[20:21]
	s_addc_u32 s37, s47, 0
	s_add_i32 s46, s73, s54
	global_load_lds_dwordx4 v[208:209], off
	v_lshl_add_u64 v[208:209], s[36:37], 0, v[186:187]
	s_mov_b32 m0, s46
	s_nop 0
	global_load_lds_dwordx4 v[208:209], off
	v_lshl_add_u64 v[208:209], s[36:37], 0, v[190:191]
	s_add_i32 m0, s46, 0x2000
	s_nop 0
	global_load_lds_dwordx4 v[208:209], off
	v_lshl_add_u64 v[208:209], v[212:213], 0, s[20:21]
	s_mov_b32 m0, s60
	s_nop 0
	global_load_lds_dwordx4 v[208:209], off
	v_lshl_add_u64 v[208:209], v[214:215], 0, s[20:21]
	s_mov_b32 m0, s61
	s_nop 0
	global_load_lds_dwordx4 v[208:209], off
	s_waitcnt vmcnt(8)
	s_waitcnt lgkmcnt(0)
	s_barrier
	s_setprio 1
	s_waitcnt lgkmcnt(0)
	v_mfma_f32_16x16x32_bf16 v[60:63], v[112:115], v[160:163], v[60:63]
	v_mfma_f32_16x16x32_bf16 v[56:59], v[136:139], v[160:163], v[56:59]
	v_mfma_f32_16x16x32_bf16 v[44:47], v[112:115], v[168:171], v[44:47]
	v_mfma_f32_16x16x32_bf16 v[40:43], v[136:139], v[168:171], v[40:43]
	v_mfma_f32_16x16x32_bf16 v[28:31], v[112:115], v[176:179], v[28:31]
	v_mfma_f32_16x16x32_bf16 v[24:27], v[136:139], v[176:179], v[24:27]
	v_mfma_f32_16x16x32_bf16 v[12:15], v[112:115], v[200:203], v[12:15]
	v_mfma_f32_16x16x32_bf16 v[8:11], v[136:139], v[200:203], v[8:11]
	v_mfma_f32_16x16x32_bf16 v[60:63], v[124:127], v[164:167], v[60:63]
	v_mfma_f32_16x16x32_bf16 v[56:59], v[140:143], v[164:167], v[56:59]
	v_mfma_f32_16x16x32_bf16 v[44:47], v[124:127], v[172:175], v[44:47]
	v_mfma_f32_16x16x32_bf16 v[40:43], v[140:143], v[172:175], v[40:43]
	v_mfma_f32_16x16x32_bf16 v[28:31], v[124:127], v[180:183], v[28:31]
	v_mfma_f32_16x16x32_bf16 v[24:27], v[140:143], v[180:183], v[24:27]
	v_mfma_f32_16x16x32_bf16 v[12:15], v[124:127], v[204:207], v[12:15]
	v_mfma_f32_16x16x32_bf16 v[8:11], v[140:143], v[204:207], v[8:11]
	s_setprio 0
	s_setprio 1
	v_mfma_f32_16x16x32_bf16 v[52:55], v[144:147], v[160:163], v[52:55]
	v_mfma_f32_16x16x32_bf16 v[48:51], v[152:155], v[160:163], v[48:51]
	v_mfma_f32_16x16x32_bf16 v[36:39], v[144:147], v[168:171], v[36:39]
	v_mfma_f32_16x16x32_bf16 v[32:35], v[152:155], v[168:171], v[32:35]
	v_mfma_f32_16x16x32_bf16 v[20:23], v[144:147], v[176:179], v[20:23]
	v_mfma_f32_16x16x32_bf16 v[16:19], v[152:155], v[176:179], v[16:19]
	v_mfma_f32_16x16x32_bf16 v[4:7], v[144:147], v[200:203], v[4:7]
	v_mfma_f32_16x16x32_bf16 v[0:3], v[152:155], v[200:203], v[0:3]
	v_mfma_f32_16x16x32_bf16 v[52:55], v[148:151], v[164:167], v[52:55]
	v_mfma_f32_16x16x32_bf16 v[48:51], v[156:159], v[164:167], v[48:51]
	v_mfma_f32_16x16x32_bf16 v[36:39], v[148:151], v[172:175], v[36:39]
	v_mfma_f32_16x16x32_bf16 v[32:35], v[156:159], v[172:175], v[32:35]
	v_mfma_f32_16x16x32_bf16 v[20:23], v[148:151], v[180:183], v[20:23]
	v_mfma_f32_16x16x32_bf16 v[16:19], v[156:159], v[180:183], v[16:19]
	v_mfma_f32_16x16x32_bf16 v[4:7], v[148:151], v[204:207], v[4:7]
	v_mfma_f32_16x16x32_bf16 v[0:3], v[156:159], v[204:207], v[0:3]
	s_setprio 0
	s_barrier
	s_add_i32 s71, s71, 2
	s_add_u32 s69, s69, 0x100
	s_addc_u32 s70, s70, 0
	s_cmp_gt_u32 s71, 41
	s_mov_b64 s[36:37], s[38:39]
	s_cbranch_scc0 .LBB0_1151
	s_and_b64 vcc, exec, s[22:23]
	s_cbranch_vccz .LBB0_1154
	s_barrier

	.amdhsa_kernel _Z8yoco_fwd4Args
		.amdhsa_group_segment_fixed_size 0
		.amdhsa_private_segment_fixed_size 0
		.amdhsa_kernarg_size 408
		.amdhsa_user_sgpr_count 2
		.amdhsa_user_sgpr_dispatch_ptr 0
		.amdhsa_user_sgpr_queue_ptr 0
		.amdhsa_user_sgpr_kernarg_segment_ptr 1
		.amdhsa_user_sgpr_dispatch_id 0
		.amdhsa_user_sgpr_kernarg_preload_length 0
		.amdhsa_user_sgpr_kernarg_preload_offset 0
		.amdhsa_user_sgpr_private_segment_size 0
		.amdhsa_uses_dynamic_stack 0
		.amdhsa_enable_private_segment 0
		.amdhsa_system_sgpr_workgroup_id_x 1
		.amdhsa_system_sgpr_workgroup_id_y 0
		.amdhsa_system_sgpr_workgroup_id_z 0
		.amdhsa_system_sgpr_workgroup_info 0
		.amdhsa_system_vgpr_workitem_id 2
		.amdhsa_next_free_vgpr 256
		.amdhsa_next_free_sgpr 100
		.amdhsa_accum_offset 256
		.amdhsa_reserve_vcc 1
		.amdhsa_float_round_mode_32 0
		.amdhsa_float_round_mode_16_64 0
		.amdhsa_float_denorm_mode_32 3
		.amdhsa_float_denorm_mode_16_64 3
		.amdhsa_dx10_clamp 1
		.amdhsa_ieee_mode 1
		.amdhsa_fp16_overflow 0
		.amdhsa_tg_split 0
		.amdhsa_exception_fp_ieee_invalid_op 0
		.amdhsa_exception_fp_denorm_src 0
		.amdhsa_exception_fp_ieee_div_zero 0
		.amdhsa_exception_fp_ieee_overflow 0
		.amdhsa_exception_fp_ieee_underflow 0
		.amdhsa_exception_fp_ieee_inexact 0
		.amdhsa_exception_int_div_zero 0
	.end_amdhsa_kernel

amdhsa.kernels:
  - .agpr_count:     0
    .args:
      - .offset:         0
        .size:           152
        .value_kind:     by_value
      - .offset:         152
        .size:           4
        .value_kind:     hidden_block_count_x
      - .offset:         156
        .size:           4
        .value_kind:     hidden_block_count_y
      - .offset:         160
        .size:           4
        .value_kind:     hidden_block_count_z
      - .offset:         164
        .size:           2
        .value_kind:     hidden_group_size_x
      - .offset:         166
        .size:           2
        .value_kind:     hidden_group_size_y
      - .offset:         168
        .size:           2
        .value_kind:     hidden_group_size_z
      - .offset:         170
        .size:           2
        .value_kind:     hidden_remainder_x
      - .offset:         172
        .size:           2
        .value_kind:     hidden_remainder_y
      - .offset:         174
        .size:           2
        .value_kind:     hidden_remainder_z
      - .offset:         192
        .size:           8
        .value_kind:     hidden_global_offset_x
      - .offset:         200
        .size:           8
        .value_kind:     hidden_global_offset_y
      - .offset:         208
        .size:           8
        .value_kind:     hidden_global_offset_z
      - .offset:         216
        .size:           2
        .value_kind:     hidden_grid_dims
      - .offset:         240
        .size:           8
        .value_kind:     hidden_multigrid_sync_arg
      - .offset:         272
        .size:           4
        .value_kind:     hidden_dynamic_lds_size
    .group_segment_fixed_size: 0
    .kernarg_segment_align: 8
    .kernarg_segment_size: 408
    .language:       OpenCL C
    .language_version:
      - 2
      - 0
    .max_flat_workgroup_size: 512
    .name:           _Z8yoco_fwd4Args
    .private_segment_fixed_size: 0
    .sgpr_count:     106
    .sgpr_spill_count: 11
    .symbol:         _Z8yoco_fwd4Args.kd
    .uniform_work_group_size: 1
    .uses_dynamic_stack: false
    .vgpr_count:     256
    .vgpr_spill_count: 0
    .wavefront_size: 64
